# kpair MFMA order: k0,k1 of each accumulator back to back (SrcC forwarding), bf16 loops
# speedup vs baseline: 1.0142x; 1.0142x over previous
.LBB0_642:
	ds_read_b128 v[148:151], v139
	ds_read_b128 v[152:155], v139 offset:1024
	ds_read_b128 v[156:159], v139 offset:2048
	ds_read_b128 v[160:163], v139 offset:3072
	ds_read_b128 v[164:167], v140
	ds_read_b128 v[168:171], v140 offset:1024
	ds_read_b128 v[172:175], v140 offset:2048
	ds_read_b128 v[176:179], v140 offset:3072
	s_add_i32 s18, s71, 0xffe80080
	s_cmp_eq_u32 s58, s73
	s_cselect_b32 s74, s69, s18
	s_cselect_b32 s76, s70, s72
	s_or_b32 s75, s74, 0x80
	s_add_i32 s18, s71, 0xfff80000
	s_mov_b32 m0, s59
	ds_read_b128 v[180:183], v141
	ds_read_b128 v[184:187], v141 offset:1024
	ds_read_b128 v[188:191], v141 offset:2048
	ds_read_b128 v[192:195], v141 offset:3072
	ds_read_b128 v[196:199], v141 offset:4096
	ds_read_b128 v[200:203], v141 offset:5120
	ds_read_b128 v[204:207], v141 offset:6144
	ds_read_b128 v[208:211], v141 offset:7168
	buffer_load_dwordx4 v137, s[12:15], s18 offen lds
	s_mov_b32 m0, s60
	s_nop 0
	buffer_load_dwordx4 v137, s[12:15], s71 offen lds
	s_waitcnt vmcnt(8)
	s_waitcnt lgkmcnt(0)
	s_setprio 1
	s_waitcnt lgkmcnt(7)
	v_mfma_f32_16x16x32_bf16 v[118:121], v[148:151], v[180:183], v[118:121]
	s_barrier
	v_mfma_f32_16x16x32_bf16 v[118:121], v[152:155], v[184:187], v[118:121]
	s_waitcnt lgkmcnt(5)
	v_mfma_f32_16x16x32_bf16 v[114:117], v[156:159], v[180:183], v[114:117]
	v_mfma_f32_16x16x32_bf16 v[114:117], v[160:163], v[184:187], v[114:117]
	s_waitcnt lgkmcnt(3)
	v_mfma_f32_16x16x32_bf16 v[110:113], v[148:151], v[188:191], v[110:113]
	v_mfma_f32_16x16x32_bf16 v[110:113], v[152:155], v[192:195], v[110:113]
	s_waitcnt lgkmcnt(1)
	v_mfma_f32_16x16x32_bf16 v[102:105], v[156:159], v[188:191], v[102:105]
	v_mfma_f32_16x16x32_bf16 v[102:105], v[160:163], v[192:195], v[102:105]
	v_mfma_f32_16x16x32_bf16 v[94:97], v[148:151], v[196:199], v[94:97]
	v_mfma_f32_16x16x32_bf16 v[94:97], v[152:155], v[200:203], v[94:97]
	v_mfma_f32_16x16x32_bf16 v[86:89], v[156:159], v[196:199], v[86:89]
	v_mfma_f32_16x16x32_bf16 v[86:89], v[160:163], v[200:203], v[86:89]
	v_mfma_f32_16x16x32_bf16 v[78:81], v[148:151], v[204:207], v[78:81]
	v_mfma_f32_16x16x32_bf16 v[78:81], v[152:155], v[208:211], v[78:81]
	v_mfma_f32_16x16x32_bf16 v[66:69], v[156:159], v[204:207], v[66:69]
	v_mfma_f32_16x16x32_bf16 v[66:69], v[160:163], v[208:211], v[66:69]
	v_mfma_f32_16x16x32_bf16 v[126:129], v[164:167], v[180:183], v[126:129]
	v_mfma_f32_16x16x32_bf16 v[126:129], v[168:171], v[184:187], v[126:129]
	v_mfma_f32_16x16x32_bf16 v[122:125], v[172:175], v[180:183], v[122:125]
	v_mfma_f32_16x16x32_bf16 v[122:125], v[176:179], v[184:187], v[122:125]
	v_mfma_f32_16x16x32_bf16 v[106:109], v[164:167], v[188:191], v[106:109]
	v_mfma_f32_16x16x32_bf16 v[106:109], v[168:171], v[192:195], v[106:109]
	s_waitcnt lgkmcnt(0)
	v_mfma_f32_16x16x32_bf16 v[98:101], v[172:175], v[188:191], v[98:101]
	v_mfma_f32_16x16x32_bf16 v[98:101], v[176:179], v[192:195], v[98:101]
	v_mfma_f32_16x16x32_bf16 v[90:93], v[164:167], v[196:199], v[90:93]
	v_mfma_f32_16x16x32_bf16 v[90:93], v[168:171], v[200:203], v[90:93]
	v_mfma_f32_16x16x32_bf16 v[82:85], v[172:175], v[196:199], v[82:85]
	v_mfma_f32_16x16x32_bf16 v[82:85], v[176:179], v[200:203], v[82:85]
	v_mfma_f32_16x16x32_bf16 v[74:77], v[164:167], v[204:207], v[74:77]
	v_mfma_f32_16x16x32_bf16 v[74:77], v[168:171], v[208:211], v[74:77]
	v_mfma_f32_16x16x32_bf16 v[70:73], v[172:175], v[204:207], v[70:73]
	v_mfma_f32_16x16x32_bf16 v[70:73], v[176:179], v[208:211], v[70:73]
	s_setprio 0
	s_barrier
	s_mov_b32 m0, s30
	s_mov_b32 s18, s14
	s_mov_b32 s19, s15
	ds_read_b128 v[180:183], v141 offset:16384
	ds_read_b128 v[184:187], v141 offset:17408
	ds_read_b128 v[188:191], v141 offset:18432
	ds_read_b128 v[192:195], v141 offset:19456
	ds_read_b128 v[196:199], v141 offset:20480
	ds_read_b128 v[200:203], v141 offset:21504
	ds_read_b128 v[204:207], v141 offset:22528
	ds_read_b128 v[208:211], v141 offset:23552
	buffer_load_dwordx4 v138, s[16:19], s76 offen lds
	s_add_i32 s77, s76, 0x80000
	s_mov_b32 m0, s31
	s_nop 0
	buffer_load_dwordx4 v138, s[16:19], s77 offen lds
	s_add_i32 s77, s76, 0x100000
	s_mov_b32 m0, s44
	s_nop 0
	buffer_load_dwordx4 v138, s[16:19], s77 offen lds
	s_add_i32 s77, s76, 0x180000
	s_mov_b32 m0, s45
	s_nop 0
	buffer_load_dwordx4 v138, s[16:19], s77 offen lds
	s_mov_b32 m0, s27
	s_add_i32 s77, s74, 0x80000
	buffer_load_dwordx4 v137, s[12:15], s74 offen lds
	s_mov_b32 m0, s46
	s_nop 0
	buffer_load_dwordx4 v137, s[12:15], s77 offen lds
	s_waitcnt vmcnt(8)
	s_waitcnt lgkmcnt(0)
	s_setprio 1
	s_waitcnt lgkmcnt(7)
	v_mfma_f32_16x16x32_bf16 v[62:65], v[148:151], v[180:183], v[62:65]
	s_barrier
	v_mfma_f32_16x16x32_bf16 v[62:65], v[152:155], v[184:187], v[62:65]
	s_waitcnt lgkmcnt(5)
	v_mfma_f32_16x16x32_bf16 v[54:57], v[156:159], v[180:183], v[54:57]
	v_mfma_f32_16x16x32_bf16 v[54:57], v[160:163], v[184:187], v[54:57]
	s_waitcnt lgkmcnt(3)
	v_mfma_f32_16x16x32_bf16 v[46:49], v[148:151], v[188:191], v[46:49]
	v_mfma_f32_16x16x32_bf16 v[46:49], v[152:155], v[192:195], v[46:49]
	s_waitcnt lgkmcnt(1)
	v_mfma_f32_16x16x32_bf16 v[38:41], v[156:159], v[188:191], v[38:41]
	v_mfma_f32_16x16x32_bf16 v[38:41], v[160:163], v[192:195], v[38:41]
	v_mfma_f32_16x16x32_bf16 v[30:33], v[148:151], v[196:199], v[30:33]
	v_mfma_f32_16x16x32_bf16 v[30:33], v[152:155], v[200:203], v[30:33]
	v_mfma_f32_16x16x32_bf16 v[22:25], v[156:159], v[196:199], v[22:25]
	v_mfma_f32_16x16x32_bf16 v[22:25], v[160:163], v[200:203], v[22:25]
	v_mfma_f32_16x16x32_bf16 v[14:17], v[148:151], v[204:207], v[14:17]
	v_mfma_f32_16x16x32_bf16 v[14:17], v[152:155], v[208:211], v[14:17]
	v_mfma_f32_16x16x32_bf16 v[6:9], v[156:159], v[204:207], v[6:9]
	v_mfma_f32_16x16x32_bf16 v[6:9], v[160:163], v[208:211], v[6:9]
	v_mfma_f32_16x16x32_bf16 v[58:61], v[164:167], v[180:183], v[58:61]
	v_mfma_f32_16x16x32_bf16 v[58:61], v[168:171], v[184:187], v[58:61]
	v_mfma_f32_16x16x32_bf16 v[50:53], v[172:175], v[180:183], v[50:53]
	v_mfma_f32_16x16x32_bf16 v[50:53], v[176:179], v[184:187], v[50:53]
	v_mfma_f32_16x16x32_bf16 v[42:45], v[164:167], v[188:191], v[42:45]
	v_mfma_f32_16x16x32_bf16 v[42:45], v[168:171], v[192:195], v[42:45]
	s_waitcnt lgkmcnt(0)
	v_mfma_f32_16x16x32_bf16 v[34:37], v[172:175], v[188:191], v[34:37]
	v_mfma_f32_16x16x32_bf16 v[34:37], v[176:179], v[192:195], v[34:37]
	v_mfma_f32_16x16x32_bf16 v[26:29], v[164:167], v[196:199], v[26:29]
	v_mfma_f32_16x16x32_bf16 v[26:29], v[168:171], v[200:203], v[26:29]
	v_mfma_f32_16x16x32_bf16 v[18:21], v[172:175], v[196:199], v[18:21]
	v_mfma_f32_16x16x32_bf16 v[18:21], v[176:179], v[200:203], v[18:21]
	v_mfma_f32_16x16x32_bf16 v[10:13], v[164:167], v[204:207], v[10:13]
	v_mfma_f32_16x16x32_bf16 v[10:13], v[168:171], v[208:211], v[10:13]
	v_mfma_f32_16x16x32_bf16 v[2:5], v[172:175], v[204:207], v[2:5]
	v_mfma_f32_16x16x32_bf16 v[2:5], v[176:179], v[208:211], v[2:5]
	s_setprio 0
	s_barrier
	ds_read_b128 v[148:151], v142
	ds_read_b128 v[152:155], v142 offset:1024
	ds_read_b128 v[156:159], v142 offset:2048
	ds_read_b128 v[160:163], v142 offset:3072
	ds_read_b128 v[164:167], v143
	ds_read_b128 v[168:171], v143 offset:1024
	ds_read_b128 v[172:175], v143 offset:2048
	ds_read_b128 v[176:179], v143 offset:3072
	s_mov_b32 m0, s47
	s_add_i32 s77, s74, 0x100000
	ds_read_b128 v[180:183], v141 offset:32768
	ds_read_b128 v[184:187], v141 offset:33792
	ds_read_b128 v[188:191], v141 offset:34816
	ds_read_b128 v[192:195], v141 offset:35840
	ds_read_b128 v[196:199], v141 offset:36864
	ds_read_b128 v[200:203], v141 offset:37888
	ds_read_b128 v[204:207], v141 offset:38912
	ds_read_b128 v[208:211], v141 offset:39936
	buffer_load_dwordx4 v137, s[12:15], s77 offen lds
	s_add_i32 s77, s74, 0x180000
	s_mov_b32 m0, s48
	s_nop 0
	buffer_load_dwordx4 v137, s[12:15], s77 offen lds
	s_waitcnt vmcnt(8)
	s_waitcnt lgkmcnt(0)
	s_setprio 1
	s_waitcnt lgkmcnt(7)
	v_mfma_f32_16x16x32_bf16 v[118:121], v[148:151], v[180:183], v[118:121]
	s_barrier
	v_mfma_f32_16x16x32_bf16 v[118:121], v[152:155], v[184:187], v[118:121]
	s_waitcnt lgkmcnt(5)
	v_mfma_f32_16x16x32_bf16 v[114:117], v[156:159], v[180:183], v[114:117]
	v_mfma_f32_16x16x32_bf16 v[114:117], v[160:163], v[184:187], v[114:117]
	s_waitcnt lgkmcnt(3)
	v_mfma_f32_16x16x32_bf16 v[110:113], v[148:151], v[188:191], v[110:113]
	v_mfma_f32_16x16x32_bf16 v[110:113], v[152:155], v[192:195], v[110:113]
	s_waitcnt lgkmcnt(1)
	v_mfma_f32_16x16x32_bf16 v[102:105], v[156:159], v[188:191], v[102:105]
	v_mfma_f32_16x16x32_bf16 v[102:105], v[160:163], v[192:195], v[102:105]
	v_mfma_f32_16x16x32_bf16 v[94:97], v[148:151], v[196:199], v[94:97]
	v_mfma_f32_16x16x32_bf16 v[94:97], v[152:155], v[200:203], v[94:97]
	v_mfma_f32_16x16x32_bf16 v[86:89], v[156:159], v[196:199], v[86:89]
	v_mfma_f32_16x16x32_bf16 v[86:89], v[160:163], v[200:203], v[86:89]
	v_mfma_f32_16x16x32_bf16 v[78:81], v[148:151], v[204:207], v[78:81]
	v_mfma_f32_16x16x32_bf16 v[78:81], v[152:155], v[208:211], v[78:81]
	v_mfma_f32_16x16x32_bf16 v[66:69], v[156:159], v[204:207], v[66:69]
	v_mfma_f32_16x16x32_bf16 v[66:69], v[160:163], v[208:211], v[66:69]
	v_mfma_f32_16x16x32_bf16 v[126:129], v[164:167], v[180:183], v[126:129]
	v_mfma_f32_16x16x32_bf16 v[126:129], v[168:171], v[184:187], v[126:129]
	v_mfma_f32_16x16x32_bf16 v[122:125], v[172:175], v[180:183], v[122:125]
	v_mfma_f32_16x16x32_bf16 v[122:125], v[176:179], v[184:187], v[122:125]
	v_mfma_f32_16x16x32_bf16 v[106:109], v[164:167], v[188:191], v[106:109]
	v_mfma_f32_16x16x32_bf16 v[106:109], v[168:171], v[192:195], v[106:109]
	s_waitcnt lgkmcnt(0)
	v_mfma_f32_16x16x32_bf16 v[98:101], v[172:175], v[188:191], v[98:101]
	v_mfma_f32_16x16x32_bf16 v[98:101], v[176:179], v[192:195], v[98:101]
	v_mfma_f32_16x16x32_bf16 v[90:93], v[164:167], v[196:199], v[90:93]
	v_mfma_f32_16x16x32_bf16 v[90:93], v[168:171], v[200:203], v[90:93]
	v_mfma_f32_16x16x32_bf16 v[82:85], v[172:175], v[196:199], v[82:85]
	v_mfma_f32_16x16x32_bf16 v[82:85], v[176:179], v[200:203], v[82:85]
	v_mfma_f32_16x16x32_bf16 v[74:77], v[164:167], v[204:207], v[74:77]
	v_mfma_f32_16x16x32_bf16 v[74:77], v[168:171], v[208:211], v[74:77]
	v_mfma_f32_16x16x32_bf16 v[70:73], v[172:175], v[204:207], v[70:73]
	v_mfma_f32_16x16x32_bf16 v[70:73], v[176:179], v[208:211], v[70:73]
	s_setprio 0
	s_barrier
	s_mov_b32 m0, s50
	s_or_b32 s77, s76, 0x80
	ds_read_b128 v[180:183], v141 offset:49152
	ds_read_b128 v[184:187], v141 offset:50176
	ds_read_b128 v[188:191], v141 offset:51200
	ds_read_b128 v[192:195], v141 offset:52224
	ds_read_b128 v[196:199], v141 offset:53248
	ds_read_b128 v[200:203], v141 offset:54272
	ds_read_b128 v[204:207], v141 offset:55296
	ds_read_b128 v[208:211], v141 offset:56320
	buffer_load_dwordx4 v138, s[16:19], s77 offen lds
	s_add_i32 s77, s76, 0x80080
	s_mov_b32 m0, s51
	s_add_i32 s74, s74, 0x80080
	buffer_load_dwordx4 v138, s[16:19], s77 offen lds
	s_add_i32 s77, s76, 0x100080
	s_mov_b32 m0, s54
	s_add_i32 s76, s76, 0x180080
	buffer_load_dwordx4 v138, s[16:19], s77 offen lds
	s_mov_b32 m0, s55
	s_nop 0
	buffer_load_dwordx4 v138, s[16:19], s76 offen lds
	s_mov_b32 m0, s52
	s_nop 0
	buffer_load_dwordx4 v137, s[12:15], s75 offen lds
	s_mov_b32 m0, s53
	s_nop 0
	buffer_load_dwordx4 v137, s[12:15], s74 offen lds
	s_waitcnt vmcnt(8)
	s_waitcnt lgkmcnt(0)
	s_setprio 1
	s_waitcnt lgkmcnt(7)
	v_mfma_f32_16x16x32_bf16 v[62:65], v[148:151], v[180:183], v[62:65]
	s_barrier
	v_mfma_f32_16x16x32_bf16 v[62:65], v[152:155], v[184:187], v[62:65]
	s_waitcnt lgkmcnt(5)
	v_mfma_f32_16x16x32_bf16 v[54:57], v[156:159], v[180:183], v[54:57]
	v_mfma_f32_16x16x32_bf16 v[54:57], v[160:163], v[184:187], v[54:57]
	s_waitcnt lgkmcnt(3)
	v_mfma_f32_16x16x32_bf16 v[46:49], v[148:151], v[188:191], v[46:49]
	v_mfma_f32_16x16x32_bf16 v[46:49], v[152:155], v[192:195], v[46:49]
	s_waitcnt lgkmcnt(1)
	v_mfma_f32_16x16x32_bf16 v[38:41], v[156:159], v[188:191], v[38:41]
	v_mfma_f32_16x16x32_bf16 v[38:41], v[160:163], v[192:195], v[38:41]
	v_mfma_f32_16x16x32_bf16 v[30:33], v[148:151], v[196:199], v[30:33]
	v_mfma_f32_16x16x32_bf16 v[30:33], v[152:155], v[200:203], v[30:33]
	v_mfma_f32_16x16x32_bf16 v[22:25], v[156:159], v[196:199], v[22:25]
	v_mfma_f32_16x16x32_bf16 v[22:25], v[160:163], v[200:203], v[22:25]
	v_mfma_f32_16x16x32_bf16 v[14:17], v[148:151], v[204:207], v[14:17]
	v_mfma_f32_16x16x32_bf16 v[14:17], v[152:155], v[208:211], v[14:17]
	v_mfma_f32_16x16x32_bf16 v[6:9], v[156:159], v[204:207], v[6:9]
	v_mfma_f32_16x16x32_bf16 v[6:9], v[160:163], v[208:211], v[6:9]
	v_mfma_f32_16x16x32_bf16 v[58:61], v[164:167], v[180:183], v[58:61]
	v_mfma_f32_16x16x32_bf16 v[58:61], v[168:171], v[184:187], v[58:61]
	v_mfma_f32_16x16x32_bf16 v[50:53], v[172:175], v[180:183], v[50:53]
	v_mfma_f32_16x16x32_bf16 v[50:53], v[176:179], v[184:187], v[50:53]
	v_mfma_f32_16x16x32_bf16 v[42:45], v[164:167], v[188:191], v[42:45]
	v_mfma_f32_16x16x32_bf16 v[42:45], v[168:171], v[192:195], v[42:45]
	s_waitcnt lgkmcnt(0)
	v_mfma_f32_16x16x32_bf16 v[34:37], v[172:175], v[188:191], v[34:37]
	v_mfma_f32_16x16x32_bf16 v[34:37], v[176:179], v[192:195], v[34:37]
	v_mfma_f32_16x16x32_bf16 v[26:29], v[164:167], v[196:199], v[26:29]
	v_mfma_f32_16x16x32_bf16 v[26:29], v[168:171], v[200:203], v[26:29]
	v_mfma_f32_16x16x32_bf16 v[18:21], v[172:175], v[196:199], v[18:21]
	v_mfma_f32_16x16x32_bf16 v[18:21], v[176:179], v[200:203], v[18:21]
	v_mfma_f32_16x16x32_bf16 v[10:13], v[164:167], v[204:207], v[10:13]
	v_mfma_f32_16x16x32_bf16 v[10:13], v[168:171], v[208:211], v[10:13]
	v_mfma_f32_16x16x32_bf16 v[2:5], v[172:175], v[204:207], v[2:5]
	v_mfma_f32_16x16x32_bf16 v[2:5], v[176:179], v[208:211], v[2:5]
	s_setprio 0
	s_barrier
	s_add_i32 s73, s73, 2
	s_addk_i32 s71, 0x100
	s_addk_i32 s72, 0x100
	s_cmp_ge_i32 s73, s3
	s_cbranch_scc0 .LBB0_642
	s_and_b64 vcc, exec, s[42:43]
	s_cbranch_vccz .LBB0_645

.LBB0_799:
	ds_read_b128 v[134:137], v210
	ds_read_b128 v[138:141], v210 offset:1024
	ds_read_b128 v[142:145], v210 offset:2048
	ds_read_b128 v[148:151], v210 offset:3072
	ds_read_b128 v[152:155], v211
	ds_read_b128 v[156:159], v211 offset:1024
	ds_read_b128 v[160:163], v211 offset:2048
	ds_read_b128 v[164:167], v211 offset:3072
	s_add_i32 s18, s77, 0xffbf8080
	s_cmp_eq_u32 s62, s79
	s_cselect_b32 s80, s6, s18
	s_cselect_b32 s82, s7, s78
	s_or_b32 s81, s80, 0x80
	s_add_i32 s18, s77, 0xffea8000
	s_mov_b32 m0, s63
	ds_read_b128 v[168:171], v212
	ds_read_b128 v[172:175], v212 offset:1024
	ds_read_b128 v[176:179], v212 offset:2048
	ds_read_b128 v[180:183], v212 offset:3072
	ds_read_b128 v[184:187], v212 offset:4096
	ds_read_b128 v[188:191], v212 offset:5120
	ds_read_b128 v[192:195], v212 offset:6144
	ds_read_b128 v[196:199], v212 offset:7168
	buffer_load_dwordx4 v208, s[12:15], s18 offen lds
	s_mov_b32 m0, s66
	s_nop 0
	buffer_load_dwordx4 v208, s[12:15], s77 offen lds
	s_waitcnt vmcnt(8)
	s_waitcnt lgkmcnt(0)
	s_setprio 1
	s_waitcnt lgkmcnt(7)
	v_mfma_f32_16x16x32_bf16 v[126:129], v[134:137], v[168:171], v[126:129]
	s_barrier
	v_mfma_f32_16x16x32_bf16 v[126:129], v[138:141], v[172:175], v[126:129]
	s_waitcnt lgkmcnt(5)
	v_mfma_f32_16x16x32_bf16 v[122:125], v[142:145], v[168:171], v[122:125]
	v_mfma_f32_16x16x32_bf16 v[122:125], v[148:151], v[172:175], v[122:125]
	s_waitcnt lgkmcnt(3)
	v_mfma_f32_16x16x32_bf16 v[118:121], v[134:137], v[176:179], v[118:121]
	v_mfma_f32_16x16x32_bf16 v[118:121], v[138:141], v[180:183], v[118:121]
	s_waitcnt lgkmcnt(1)
	v_mfma_f32_16x16x32_bf16 v[114:117], v[142:145], v[176:179], v[114:117]
	v_mfma_f32_16x16x32_bf16 v[114:117], v[148:151], v[180:183], v[114:117]
	v_mfma_f32_16x16x32_bf16 v[106:109], v[134:137], v[184:187], v[106:109]
	v_mfma_f32_16x16x32_bf16 v[106:109], v[138:141], v[188:191], v[106:109]
	v_mfma_f32_16x16x32_bf16 v[98:101], v[142:145], v[184:187], v[98:101]
	v_mfma_f32_16x16x32_bf16 v[98:101], v[148:151], v[188:191], v[98:101]
	v_mfma_f32_16x16x32_bf16 v[90:93], v[134:137], v[192:195], v[90:93]
	v_mfma_f32_16x16x32_bf16 v[90:93], v[138:141], v[196:199], v[90:93]
	v_mfma_f32_16x16x32_bf16 v[82:85], v[142:145], v[192:195], v[82:85]
	v_mfma_f32_16x16x32_bf16 v[82:85], v[148:151], v[196:199], v[82:85]
	v_mfma_f32_16x16x32_bf16 v[110:113], v[152:155], v[168:171], v[110:113]
	v_mfma_f32_16x16x32_bf16 v[110:113], v[156:159], v[172:175], v[110:113]
	v_mfma_f32_16x16x32_bf16 v[102:105], v[160:163], v[168:171], v[102:105]
	v_mfma_f32_16x16x32_bf16 v[102:105], v[164:167], v[172:175], v[102:105]
	v_mfma_f32_16x16x32_bf16 v[94:97], v[152:155], v[176:179], v[94:97]
	v_mfma_f32_16x16x32_bf16 v[94:97], v[156:159], v[180:183], v[94:97]
	s_waitcnt lgkmcnt(0)
	v_mfma_f32_16x16x32_bf16 v[86:89], v[160:163], v[176:179], v[86:89]
	v_mfma_f32_16x16x32_bf16 v[86:89], v[164:167], v[180:183], v[86:89]
	v_mfma_f32_16x16x32_bf16 v[78:81], v[152:155], v[184:187], v[78:81]
	v_mfma_f32_16x16x32_bf16 v[78:81], v[156:159], v[188:191], v[78:81]
	v_mfma_f32_16x16x32_bf16 v[74:77], v[160:163], v[184:187], v[74:77]
	v_mfma_f32_16x16x32_bf16 v[74:77], v[164:167], v[188:191], v[74:77]
	v_mfma_f32_16x16x32_bf16 v[70:73], v[152:155], v[192:195], v[70:73]
	v_mfma_f32_16x16x32_bf16 v[70:73], v[156:159], v[196:199], v[70:73]
	v_mfma_f32_16x16x32_bf16 v[66:69], v[160:163], v[192:195], v[66:69]
	v_mfma_f32_16x16x32_bf16 v[66:69], v[164:167], v[196:199], v[66:69]
	s_setprio 0
	s_barrier
	s_mov_b32 m0, s25
	s_mov_b32 s18, s14
	s_mov_b32 s19, s15
	ds_read_b128 v[168:171], v212 offset:16384
	ds_read_b128 v[172:175], v212 offset:17408
	ds_read_b128 v[176:179], v212 offset:18432
	ds_read_b128 v[180:183], v212 offset:19456
	ds_read_b128 v[184:187], v212 offset:20480
	ds_read_b128 v[188:191], v212 offset:21504
	ds_read_b128 v[192:195], v212 offset:22528
	ds_read_b128 v[196:199], v212 offset:23552
	buffer_load_dwordx4 v209, s[16:19], s82 offen lds
	s_add_i32 s83, s82, 0x158000
	s_mov_b32 m0, s27
	s_nop 0
	buffer_load_dwordx4 v209, s[16:19], s83 offen lds
	s_add_i32 s83, s82, 0x2b0000
	s_mov_b32 m0, s30
	s_nop 0
	buffer_load_dwordx4 v209, s[16:19], s83 offen lds
	s_add_i32 s83, s82, 0x408000
	s_mov_b32 m0, s31
	s_nop 0
	buffer_load_dwordx4 v209, s[16:19], s83 offen lds
	s_mov_b32 m0, s21
	s_add_i32 s83, s80, 0x158000
	buffer_load_dwordx4 v208, s[12:15], s80 offen lds
	s_mov_b32 m0, s48
	s_nop 0
	buffer_load_dwordx4 v208, s[12:15], s83 offen lds
	s_waitcnt vmcnt(8)
	s_waitcnt lgkmcnt(0)
	s_setprio 1
	s_waitcnt lgkmcnt(7)
	v_mfma_f32_16x16x32_bf16 v[62:65], v[134:137], v[168:171], v[62:65]
	s_barrier
	v_mfma_f32_16x16x32_bf16 v[62:65], v[138:141], v[172:175], v[62:65]
	s_waitcnt lgkmcnt(5)
	v_mfma_f32_16x16x32_bf16 v[58:61], v[142:145], v[168:171], v[58:61]
	v_mfma_f32_16x16x32_bf16 v[58:61], v[148:151], v[172:175], v[58:61]
	s_waitcnt lgkmcnt(3)
	v_mfma_f32_16x16x32_bf16 v[54:57], v[134:137], v[176:179], v[54:57]
	v_mfma_f32_16x16x32_bf16 v[54:57], v[138:141], v[180:183], v[54:57]
	s_waitcnt lgkmcnt(1)
	v_mfma_f32_16x16x32_bf16 v[50:53], v[142:145], v[176:179], v[50:53]
	v_mfma_f32_16x16x32_bf16 v[50:53], v[148:151], v[180:183], v[50:53]
	v_mfma_f32_16x16x32_bf16 v[42:45], v[134:137], v[184:187], v[42:45]
	v_mfma_f32_16x16x32_bf16 v[42:45], v[138:141], v[188:191], v[42:45]
	v_mfma_f32_16x16x32_bf16 v[34:37], v[142:145], v[184:187], v[34:37]
	v_mfma_f32_16x16x32_bf16 v[34:37], v[148:151], v[188:191], v[34:37]
	v_mfma_f32_16x16x32_bf16 v[26:29], v[134:137], v[192:195], v[26:29]
	v_mfma_f32_16x16x32_bf16 v[26:29], v[138:141], v[196:199], v[26:29]
	v_mfma_f32_16x16x32_bf16 v[18:21], v[142:145], v[192:195], v[18:21]
	v_mfma_f32_16x16x32_bf16 v[18:21], v[148:151], v[196:199], v[18:21]
	v_mfma_f32_16x16x32_bf16 v[46:49], v[152:155], v[168:171], v[46:49]
	v_mfma_f32_16x16x32_bf16 v[46:49], v[156:159], v[172:175], v[46:49]
	v_mfma_f32_16x16x32_bf16 v[38:41], v[160:163], v[168:171], v[38:41]
	v_mfma_f32_16x16x32_bf16 v[38:41], v[164:167], v[172:175], v[38:41]
	v_mfma_f32_16x16x32_bf16 v[30:33], v[152:155], v[176:179], v[30:33]
	v_mfma_f32_16x16x32_bf16 v[30:33], v[156:159], v[180:183], v[30:33]
	s_waitcnt lgkmcnt(0)
	v_mfma_f32_16x16x32_bf16 v[22:25], v[160:163], v[176:179], v[22:25]
	v_mfma_f32_16x16x32_bf16 v[22:25], v[164:167], v[180:183], v[22:25]
	v_mfma_f32_16x16x32_bf16 v[14:17], v[152:155], v[184:187], v[14:17]
	v_mfma_f32_16x16x32_bf16 v[14:17], v[156:159], v[188:191], v[14:17]
	v_mfma_f32_16x16x32_bf16 v[10:13], v[160:163], v[184:187], v[10:13]
	v_mfma_f32_16x16x32_bf16 v[10:13], v[164:167], v[188:191], v[10:13]
	v_mfma_f32_16x16x32_bf16 v[6:9], v[152:155], v[192:195], v[6:9]
	v_mfma_f32_16x16x32_bf16 v[6:9], v[156:159], v[196:199], v[6:9]
	v_mfma_f32_16x16x32_bf16 v[2:5], v[160:163], v[192:195], v[2:5]
	v_mfma_f32_16x16x32_bf16 v[2:5], v[164:167], v[196:199], v[2:5]
	s_setprio 0
	s_barrier
	ds_read_b128 v[134:137], v213
	ds_read_b128 v[138:141], v213 offset:1024
	ds_read_b128 v[142:145], v213 offset:2048
	ds_read_b128 v[148:151], v213 offset:3072
	ds_read_b128 v[152:155], v214
	ds_read_b128 v[156:159], v214 offset:1024
	ds_read_b128 v[160:163], v214 offset:2048
	ds_read_b128 v[164:167], v214 offset:3072
	s_mov_b32 m0, s49
	s_add_i32 s83, s80, 0x2b0000
	ds_read_b128 v[168:171], v212 offset:32768
	ds_read_b128 v[172:175], v212 offset:33792
	ds_read_b128 v[176:179], v212 offset:34816
	ds_read_b128 v[180:183], v212 offset:35840
	ds_read_b128 v[184:187], v212 offset:36864
	ds_read_b128 v[188:191], v212 offset:37888
	ds_read_b128 v[192:195], v212 offset:38912
	ds_read_b128 v[196:199], v212 offset:39936
	buffer_load_dwordx4 v208, s[12:15], s83 offen lds
	s_add_i32 s83, s80, 0x408000
	s_mov_b32 m0, s50
	s_nop 0
	buffer_load_dwordx4 v208, s[12:15], s83 offen lds
	s_waitcnt vmcnt(8)
	s_waitcnt lgkmcnt(0)
	s_setprio 1
	s_waitcnt lgkmcnt(7)
	v_mfma_f32_16x16x32_bf16 v[126:129], v[134:137], v[168:171], v[126:129]
	s_barrier
	v_mfma_f32_16x16x32_bf16 v[126:129], v[138:141], v[172:175], v[126:129]
	s_waitcnt lgkmcnt(5)
	v_mfma_f32_16x16x32_bf16 v[122:125], v[142:145], v[168:171], v[122:125]
	v_mfma_f32_16x16x32_bf16 v[122:125], v[148:151], v[172:175], v[122:125]
	s_waitcnt lgkmcnt(3)
	v_mfma_f32_16x16x32_bf16 v[118:121], v[134:137], v[176:179], v[118:121]
	v_mfma_f32_16x16x32_bf16 v[118:121], v[138:141], v[180:183], v[118:121]
	s_waitcnt lgkmcnt(1)
	v_mfma_f32_16x16x32_bf16 v[114:117], v[142:145], v[176:179], v[114:117]
	v_mfma_f32_16x16x32_bf16 v[114:117], v[148:151], v[180:183], v[114:117]
	v_mfma_f32_16x16x32_bf16 v[106:109], v[134:137], v[184:187], v[106:109]
	v_mfma_f32_16x16x32_bf16 v[106:109], v[138:141], v[188:191], v[106:109]
	v_mfma_f32_16x16x32_bf16 v[98:101], v[142:145], v[184:187], v[98:101]
	v_mfma_f32_16x16x32_bf16 v[98:101], v[148:151], v[188:191], v[98:101]
	v_mfma_f32_16x16x32_bf16 v[90:93], v[134:137], v[192:195], v[90:93]
	v_mfma_f32_16x16x32_bf16 v[90:93], v[138:141], v[196:199], v[90:93]
	v_mfma_f32_16x16x32_bf16 v[82:85], v[142:145], v[192:195], v[82:85]
	v_mfma_f32_16x16x32_bf16 v[82:85], v[148:151], v[196:199], v[82:85]
	v_mfma_f32_16x16x32_bf16 v[110:113], v[152:155], v[168:171], v[110:113]
	v_mfma_f32_16x16x32_bf16 v[110:113], v[156:159], v[172:175], v[110:113]
	v_mfma_f32_16x16x32_bf16 v[102:105], v[160:163], v[168:171], v[102:105]
	v_mfma_f32_16x16x32_bf16 v[102:105], v[164:167], v[172:175], v[102:105]
	v_mfma_f32_16x16x32_bf16 v[94:97], v[152:155], v[176:179], v[94:97]
	v_mfma_f32_16x16x32_bf16 v[94:97], v[156:159], v[180:183], v[94:97]
	s_waitcnt lgkmcnt(0)
	v_mfma_f32_16x16x32_bf16 v[86:89], v[160:163], v[176:179], v[86:89]
	v_mfma_f32_16x16x32_bf16 v[86:89], v[164:167], v[180:183], v[86:89]
	v_mfma_f32_16x16x32_bf16 v[78:81], v[152:155], v[184:187], v[78:81]
	v_mfma_f32_16x16x32_bf16 v[78:81], v[156:159], v[188:191], v[78:81]
	v_mfma_f32_16x16x32_bf16 v[74:77], v[160:163], v[184:187], v[74:77]
	v_mfma_f32_16x16x32_bf16 v[74:77], v[164:167], v[188:191], v[74:77]
	v_mfma_f32_16x16x32_bf16 v[70:73], v[152:155], v[192:195], v[70:73]
	v_mfma_f32_16x16x32_bf16 v[70:73], v[156:159], v[196:199], v[70:73]
	v_mfma_f32_16x16x32_bf16 v[66:69], v[160:163], v[192:195], v[66:69]
	v_mfma_f32_16x16x32_bf16 v[66:69], v[164:167], v[196:199], v[66:69]
	s_setprio 0
	s_barrier
	s_mov_b32 m0, s54
	s_or_b32 s83, s82, 0x80
	ds_read_b128 v[168:171], v212 offset:49152
	ds_read_b128 v[172:175], v212 offset:50176
	ds_read_b128 v[176:179], v212 offset:51200
	ds_read_b128 v[180:183], v212 offset:52224
	ds_read_b128 v[184:187], v212 offset:53248
	ds_read_b128 v[188:191], v212 offset:54272
	ds_read_b128 v[192:195], v212 offset:55296
	ds_read_b128 v[196:199], v212 offset:56320
	buffer_load_dwordx4 v209, s[16:19], s83 offen lds
	s_add_i32 s83, s82, 0x158080
	s_mov_b32 m0, s55
	s_add_i32 s80, s80, 0x158080
	buffer_load_dwordx4 v209, s[16:19], s83 offen lds
	s_add_i32 s83, s82, 0x2b0080
	s_mov_b32 m0, s58
	s_add_i32 s82, s82, 0x408080
	buffer_load_dwordx4 v209, s[16:19], s83 offen lds
	s_mov_b32 m0, s59
	s_nop 0
	buffer_load_dwordx4 v209, s[16:19], s82 offen lds
	s_mov_b32 m0, s56
	s_nop 0
	buffer_load_dwordx4 v208, s[12:15], s81 offen lds
	s_mov_b32 m0, s57
	s_nop 0
	buffer_load_dwordx4 v208, s[12:15], s80 offen lds
	s_waitcnt vmcnt(8)
	s_waitcnt lgkmcnt(0)
	s_setprio 1
	s_waitcnt lgkmcnt(7)
	v_mfma_f32_16x16x32_bf16 v[62:65], v[134:137], v[168:171], v[62:65]
	s_barrier
	v_mfma_f32_16x16x32_bf16 v[62:65], v[138:141], v[172:175], v[62:65]
	s_waitcnt lgkmcnt(5)
	v_mfma_f32_16x16x32_bf16 v[58:61], v[142:145], v[168:171], v[58:61]
	v_mfma_f32_16x16x32_bf16 v[58:61], v[148:151], v[172:175], v[58:61]
	s_waitcnt lgkmcnt(3)
	v_mfma_f32_16x16x32_bf16 v[54:57], v[134:137], v[176:179], v[54:57]
	v_mfma_f32_16x16x32_bf16 v[54:57], v[138:141], v[180:183], v[54:57]
	s_waitcnt lgkmcnt(1)
	v_mfma_f32_16x16x32_bf16 v[50:53], v[142:145], v[176:179], v[50:53]
	v_mfma_f32_16x16x32_bf16 v[50:53], v[148:151], v[180:183], v[50:53]
	v_mfma_f32_16x16x32_bf16 v[42:45], v[134:137], v[184:187], v[42:45]
	v_mfma_f32_16x16x32_bf16 v[42:45], v[138:141], v[188:191], v[42:45]
	v_mfma_f32_16x16x32_bf16 v[34:37], v[142:145], v[184:187], v[34:37]
	v_mfma_f32_16x16x32_bf16 v[34:37], v[148:151], v[188:191], v[34:37]
	v_mfma_f32_16x16x32_bf16 v[26:29], v[134:137], v[192:195], v[26:29]
	v_mfma_f32_16x16x32_bf16 v[26:29], v[138:141], v[196:199], v[26:29]
	v_mfma_f32_16x16x32_bf16 v[18:21], v[142:145], v[192:195], v[18:21]
	v_mfma_f32_16x16x32_bf16 v[18:21], v[148:151], v[196:199], v[18:21]
	v_mfma_f32_16x16x32_bf16 v[46:49], v[152:155], v[168:171], v[46:49]
	v_mfma_f32_16x16x32_bf16 v[46:49], v[156:159], v[172:175], v[46:49]
	v_mfma_f32_16x16x32_bf16 v[38:41], v[160:163], v[168:171], v[38:41]
	v_mfma_f32_16x16x32_bf16 v[38:41], v[164:167], v[172:175], v[38:41]
	v_mfma_f32_16x16x32_bf16 v[30:33], v[152:155], v[176:179], v[30:33]
	v_mfma_f32_16x16x32_bf16 v[30:33], v[156:159], v[180:183], v[30:33]
	s_waitcnt lgkmcnt(0)
	v_mfma_f32_16x16x32_bf16 v[22:25], v[160:163], v[176:179], v[22:25]
	v_mfma_f32_16x16x32_bf16 v[22:25], v[164:167], v[180:183], v[22:25]
	v_mfma_f32_16x16x32_bf16 v[14:17], v[152:155], v[184:187], v[14:17]
	v_mfma_f32_16x16x32_bf16 v[14:17], v[156:159], v[188:191], v[14:17]
	v_mfma_f32_16x16x32_bf16 v[10:13], v[160:163], v[184:187], v[10:13]
	v_mfma_f32_16x16x32_bf16 v[10:13], v[164:167], v[188:191], v[10:13]
	v_mfma_f32_16x16x32_bf16 v[6:9], v[152:155], v[192:195], v[6:9]
	v_mfma_f32_16x16x32_bf16 v[6:9], v[156:159], v[196:199], v[6:9]
	v_mfma_f32_16x16x32_bf16 v[2:5], v[160:163], v[192:195], v[2:5]
	v_mfma_f32_16x16x32_bf16 v[2:5], v[164:167], v[196:199], v[2:5]
	s_setprio 0
	s_barrier
	s_add_i32 s79, s79, 2
	s_addk_i32 s77, 0x100
	s_addk_i32 s78, 0x100
	s_cmp_ge_i32 s79, s3
	s_cbranch_scc0 .LBB0_799
	v_pk_mul_f32 v[184:185], v[128:129], 0.5 op_sel_hi:[1,0]
	v_pk_mul_f32 v[186:187], v[126:127], 0.5 op_sel_hi:[1,0]
	v_pk_mul_f32 v[188:189], v[124:125], 0.5 op_sel_hi:[1,0]
	v_pk_mul_f32 v[190:191], v[122:123], 0.5 op_sel_hi:[1,0]
	v_pk_mul_f32 v[198:199], v[112:113], 0.5 op_sel_hi:[1,0]
	v_pk_mul_f32 v[196:197], v[110:111], 0.5 op_sel_hi:[1,0]
	v_pk_mul_f32 v[194:195], v[104:105], 0.5 op_sel_hi:[1,0]
	v_pk_mul_f32 v[192:193], v[102:103], 0.5 op_sel_hi:[1,0]
	v_pk_mul_f32 v[182:183], v[120:121], 0.5 op_sel_hi:[1,0]
	v_pk_mul_f32 v[180:181], v[118:119], 0.5 op_sel_hi:[1,0]
	v_pk_mul_f32 v[178:179], v[116:117], 0.5 op_sel_hi:[1,0]
	v_pk_mul_f32 v[176:177], v[114:115], 0.5 op_sel_hi:[1,0]
	v_pk_mul_f32 v[172:173], v[96:97], 0.5 op_sel_hi:[1,0]
	v_pk_mul_f32 v[170:171], v[94:95], 0.5 op_sel_hi:[1,0]
	v_pk_mul_f32 v[168:169], v[88:89], 0.5 op_sel_hi:[1,0]
	v_pk_mul_f32 v[166:167], v[86:87], 0.5 op_sel_hi:[1,0]
	v_pk_mul_f32 v[164:165], v[108:109], 0.5 op_sel_hi:[1,0]
	v_pk_mul_f32 v[162:163], v[106:107], 0.5 op_sel_hi:[1,0]
	v_pk_mul_f32 v[160:161], v[100:101], 0.5 op_sel_hi:[1,0]
	v_pk_mul_f32 v[158:159], v[98:99], 0.5 op_sel_hi:[1,0]
	v_pk_mul_f32 v[156:157], v[80:81], 0.5 op_sel_hi:[1,0]
	v_pk_mul_f32 v[154:155], v[78:79], 0.5 op_sel_hi:[1,0]
	v_pk_mul_f32 v[152:153], v[76:77], 0.5 op_sel_hi:[1,0]
	v_pk_mul_f32 v[150:151], v[74:75], 0.5 op_sel_hi:[1,0]
	v_pk_mul_f32 v[144:145], v[92:93], 0.5 op_sel_hi:[1,0]
	v_pk_mul_f32 v[142:143], v[90:91], 0.5 op_sel_hi:[1,0]
	v_pk_mul_f32 v[140:141], v[84:85], 0.5 op_sel_hi:[1,0]
	v_pk_mul_f32 v[138:139], v[82:83], 0.5 op_sel_hi:[1,0]
	v_pk_mul_f32 v[136:137], v[72:73], 0.5 op_sel_hi:[1,0]
	v_pk_mul_f32 v[134:135], v[70:71], 0.5 op_sel_hi:[1,0]
	v_pk_mul_f32 v[128:129], v[68:69], 0.5 op_sel_hi:[1,0]
	v_pk_mul_f32 v[126:127], v[66:67], 0.5 op_sel_hi:[1,0]
	v_pk_mul_f32 v[122:123], v[64:65], 0.5 op_sel_hi:[1,0]
	v_pk_mul_f32 v[120:121], v[62:63], 0.5 op_sel_hi:[1,0]
	v_pk_mul_f32 v[118:119], v[60:61], 0.5 op_sel_hi:[1,0]
	v_pk_mul_f32 v[116:117], v[58:59], 0.5 op_sel_hi:[1,0]
	v_pk_mul_f32 v[112:113], v[48:49], 0.5 op_sel_hi:[1,0]
	v_pk_mul_f32 v[110:111], v[46:47], 0.5 op_sel_hi:[1,0]
	v_pk_mul_f32 v[108:109], v[40:41], 0.5 op_sel_hi:[1,0]
	v_pk_mul_f32 v[106:107], v[38:39], 0.5 op_sel_hi:[1,0]
	v_pk_mul_f32 v[104:105], v[56:57], 0.5 op_sel_hi:[1,0]
	v_pk_mul_f32 v[102:103], v[54:55], 0.5 op_sel_hi:[1,0]
	v_pk_mul_f32 v[100:101], v[52:53], 0.5 op_sel_hi:[1,0]
	v_pk_mul_f32 v[98:99], v[50:51], 0.5 op_sel_hi:[1,0]
	v_pk_mul_f32 v[96:97], v[32:33], 0.5 op_sel_hi:[1,0]
	v_pk_mul_f32 v[94:95], v[30:31], 0.5 op_sel_hi:[1,0]
	v_pk_mul_f32 v[92:93], v[24:25], 0.5 op_sel_hi:[1,0]
	v_pk_mul_f32 v[90:91], v[22:23], 0.5 op_sel_hi:[1,0]
	v_pk_mul_f32 v[88:89], v[44:45], 0.5 op_sel_hi:[1,0]
	v_pk_mul_f32 v[86:87], v[42:43], 0.5 op_sel_hi:[1,0]
	v_pk_mul_f32 v[84:85], v[36:37], 0.5 op_sel_hi:[1,0]
	v_pk_mul_f32 v[82:83], v[34:35], 0.5 op_sel_hi:[1,0]
	v_pk_mul_f32 v[80:81], v[16:17], 0.5 op_sel_hi:[1,0]
	v_pk_mul_f32 v[78:79], v[14:15], 0.5 op_sel_hi:[1,0]
	v_pk_mul_f32 v[76:77], v[12:13], 0.5 op_sel_hi:[1,0]
	v_pk_mul_f32 v[74:75], v[10:11], 0.5 op_sel_hi:[1,0]
	v_pk_mul_f32 v[72:73], v[28:29], 0.5 op_sel_hi:[1,0]
	v_pk_mul_f32 v[70:71], v[26:27], 0.5 op_sel_hi:[1,0]
	v_pk_mul_f32 v[68:69], v[20:21], 0.5 op_sel_hi:[1,0]
	v_pk_mul_f32 v[66:67], v[18:19], 0.5 op_sel_hi:[1,0]
	v_pk_mul_f32 v[64:65], v[8:9], 0.5 op_sel_hi:[1,0]
	v_pk_mul_f32 v[62:63], v[6:7], 0.5 op_sel_hi:[1,0]
	v_pk_mul_f32 v[60:61], v[4:5], 0.5 op_sel_hi:[1,0]
	v_pk_mul_f32 v[58:59], v[2:3], 0.5 op_sel_hi:[1,0]
	s_and_b64 vcc, exec, s[38:39]
	s_cbranch_vccz .LBB0_802

.LBB0_892:
	ds_read_b128 v[130:133], v172
	ds_read_b128 v[134:137], v172 offset:1024
	ds_read_b128 v[148:151], v172 offset:2048
	ds_read_b128 v[152:155], v172 offset:3072
	ds_read_b128 v[156:159], v173
	ds_read_b128 v[160:163], v173 offset:1024
	ds_read_b128 v[164:167], v173 offset:2048
	ds_read_b128 v[180:183], v173 offset:3072
	s_add_i32 s18, s8, 0xffe80080
	s_cmp_eq_u32 s77, s52
	s_cselect_b32 s53, s6, s18
	s_cselect_b32 s58, s7, s9
	s_or_b32 s57, s53, 0x80
	s_add_i32 s18, s8, 0xfff80000
	s_mov_b32 m0, s78
	ds_read_b128 v[184:187], v174
	ds_read_b128 v[188:191], v174 offset:1024
	ds_read_b128 v[192:195], v174 offset:2048
	ds_read_b128 v[196:199], v174 offset:3072
	ds_read_b128 v[200:203], v174 offset:4096
	ds_read_b128 v[204:207], v174 offset:5120
	ds_read_b128 v[208:211], v174 offset:6144
	ds_read_b128 v[212:215], v174 offset:7168
	buffer_load_dwordx4 v170, s[12:15], s18 offen lds
	s_mov_b32 m0, s79
	s_nop 0
	buffer_load_dwordx4 v170, s[12:15], s8 offen lds
	s_waitcnt vmcnt(8)
	s_waitcnt lgkmcnt(0)
	s_setprio 1
	s_waitcnt lgkmcnt(7)
	v_mfma_f32_16x16x32_bf16 v[126:129], v[130:133], v[184:187], v[126:129]
	s_barrier
	v_mfma_f32_16x16x32_bf16 v[126:129], v[134:137], v[188:191], v[126:129]
	s_waitcnt lgkmcnt(5)
	v_mfma_f32_16x16x32_bf16 v[118:121], v[148:151], v[184:187], v[118:121]
	v_mfma_f32_16x16x32_bf16 v[118:121], v[152:155], v[188:191], v[118:121]
	s_waitcnt lgkmcnt(3)
	v_mfma_f32_16x16x32_bf16 v[110:113], v[130:133], v[192:195], v[110:113]
	v_mfma_f32_16x16x32_bf16 v[110:113], v[134:137], v[196:199], v[110:113]
	s_waitcnt lgkmcnt(1)
	v_mfma_f32_16x16x32_bf16 v[102:105], v[148:151], v[192:195], v[102:105]
	v_mfma_f32_16x16x32_bf16 v[102:105], v[152:155], v[196:199], v[102:105]
	v_mfma_f32_16x16x32_bf16 v[94:97], v[130:133], v[200:203], v[94:97]
	v_mfma_f32_16x16x32_bf16 v[94:97], v[134:137], v[204:207], v[94:97]
	v_mfma_f32_16x16x32_bf16 v[90:93], v[148:151], v[200:203], v[90:93]
	v_mfma_f32_16x16x32_bf16 v[90:93], v[152:155], v[204:207], v[90:93]
	v_mfma_f32_16x16x32_bf16 v[78:81], v[130:133], v[208:211], v[78:81]
	v_mfma_f32_16x16x32_bf16 v[78:81], v[134:137], v[212:215], v[78:81]
	v_mfma_f32_16x16x32_bf16 v[70:73], v[148:151], v[208:211], v[70:73]
	v_mfma_f32_16x16x32_bf16 v[70:73], v[152:155], v[212:215], v[70:73]
	v_mfma_f32_16x16x32_bf16 v[122:125], v[156:159], v[184:187], v[122:125]
	v_mfma_f32_16x16x32_bf16 v[122:125], v[160:163], v[188:191], v[122:125]
	v_mfma_f32_16x16x32_bf16 v[114:117], v[164:167], v[184:187], v[114:117]
	v_mfma_f32_16x16x32_bf16 v[114:117], v[180:183], v[188:191], v[114:117]
	v_mfma_f32_16x16x32_bf16 v[106:109], v[156:159], v[192:195], v[106:109]
	v_mfma_f32_16x16x32_bf16 v[106:109], v[160:163], v[196:199], v[106:109]
	s_waitcnt lgkmcnt(0)
	v_mfma_f32_16x16x32_bf16 v[98:101], v[164:167], v[192:195], v[98:101]
	v_mfma_f32_16x16x32_bf16 v[98:101], v[180:183], v[196:199], v[98:101]
	v_mfma_f32_16x16x32_bf16 v[86:89], v[156:159], v[200:203], v[86:89]
	v_mfma_f32_16x16x32_bf16 v[86:89], v[160:163], v[204:207], v[86:89]
	v_mfma_f32_16x16x32_bf16 v[82:85], v[164:167], v[200:203], v[82:85]
	v_mfma_f32_16x16x32_bf16 v[82:85], v[180:183], v[204:207], v[82:85]
	v_mfma_f32_16x16x32_bf16 v[74:77], v[156:159], v[208:211], v[74:77]
	v_mfma_f32_16x16x32_bf16 v[74:77], v[160:163], v[212:215], v[74:77]
	v_mfma_f32_16x16x32_bf16 v[66:69], v[164:167], v[208:211], v[66:69]
	v_mfma_f32_16x16x32_bf16 v[66:69], v[180:183], v[212:215], v[66:69]
	s_setprio 0
	s_barrier
	s_mov_b32 m0, s27
	s_mov_b32 s18, s14
	s_mov_b32 s19, s15
	ds_read_b128 v[184:187], v174 offset:16384
	ds_read_b128 v[188:191], v174 offset:17408
	ds_read_b128 v[192:195], v174 offset:18432
	ds_read_b128 v[196:199], v174 offset:19456
	ds_read_b128 v[200:203], v174 offset:20480
	ds_read_b128 v[204:207], v174 offset:21504
	ds_read_b128 v[208:211], v174 offset:22528
	ds_read_b128 v[212:215], v174 offset:23552
	buffer_load_dwordx4 v171, s[16:19], s58 offen lds
	s_add_i32 s59, s58, 0x80000
	s_mov_b32 m0, s60
	s_nop 0
	buffer_load_dwordx4 v171, s[16:19], s59 offen lds
	s_add_i32 s59, s58, 0x100000
	s_mov_b32 m0, s61
	s_nop 0
	buffer_load_dwordx4 v171, s[16:19], s59 offen lds
	s_add_i32 s59, s58, 0x180000
	s_mov_b32 m0, s62
	s_nop 0
	buffer_load_dwordx4 v171, s[16:19], s59 offen lds
	s_mov_b32 m0, s25
	s_add_i32 s59, s53, 0x80000
	buffer_load_dwordx4 v170, s[12:15], s53 offen lds
	s_mov_b32 m0, s63
	s_nop 0
	buffer_load_dwordx4 v170, s[12:15], s59 offen lds
	s_waitcnt vmcnt(8)
	s_waitcnt lgkmcnt(0)
	s_setprio 1
	s_waitcnt lgkmcnt(7)
	v_mfma_f32_16x16x32_bf16 v[62:65], v[130:133], v[184:187], v[62:65]
	s_barrier
	v_mfma_f32_16x16x32_bf16 v[62:65], v[134:137], v[188:191], v[62:65]
	s_waitcnt lgkmcnt(5)
	v_mfma_f32_16x16x32_bf16 v[54:57], v[148:151], v[184:187], v[54:57]
	v_mfma_f32_16x16x32_bf16 v[54:57], v[152:155], v[188:191], v[54:57]
	s_waitcnt lgkmcnt(3)
	v_mfma_f32_16x16x32_bf16 v[46:49], v[130:133], v[192:195], v[46:49]
	v_mfma_f32_16x16x32_bf16 v[46:49], v[134:137], v[196:199], v[46:49]
	s_waitcnt lgkmcnt(1)
	v_mfma_f32_16x16x32_bf16 v[38:41], v[148:151], v[192:195], v[38:41]
	v_mfma_f32_16x16x32_bf16 v[38:41], v[152:155], v[196:199], v[38:41]
	v_mfma_f32_16x16x32_bf16 v[30:33], v[130:133], v[200:203], v[30:33]
	v_mfma_f32_16x16x32_bf16 v[30:33], v[134:137], v[204:207], v[30:33]
	v_mfma_f32_16x16x32_bf16 v[22:25], v[148:151], v[200:203], v[22:25]
	v_mfma_f32_16x16x32_bf16 v[22:25], v[152:155], v[204:207], v[22:25]
	v_mfma_f32_16x16x32_bf16 v[14:17], v[130:133], v[208:211], v[14:17]
	v_mfma_f32_16x16x32_bf16 v[14:17], v[134:137], v[212:215], v[14:17]
	v_mfma_f32_16x16x32_bf16 v[6:9], v[148:151], v[208:211], v[6:9]
	v_mfma_f32_16x16x32_bf16 v[6:9], v[152:155], v[212:215], v[6:9]
	v_mfma_f32_16x16x32_bf16 v[58:61], v[156:159], v[184:187], v[58:61]
	v_mfma_f32_16x16x32_bf16 v[58:61], v[160:163], v[188:191], v[58:61]
	v_mfma_f32_16x16x32_bf16 v[50:53], v[164:167], v[184:187], v[50:53]
	v_mfma_f32_16x16x32_bf16 v[50:53], v[180:183], v[188:191], v[50:53]
	v_mfma_f32_16x16x32_bf16 v[42:45], v[156:159], v[192:195], v[42:45]
	v_mfma_f32_16x16x32_bf16 v[42:45], v[160:163], v[196:199], v[42:45]
	s_waitcnt lgkmcnt(0)
	v_mfma_f32_16x16x32_bf16 v[34:37], v[164:167], v[192:195], v[34:37]
	v_mfma_f32_16x16x32_bf16 v[34:37], v[180:183], v[196:199], v[34:37]
	v_mfma_f32_16x16x32_bf16 v[26:29], v[156:159], v[200:203], v[26:29]
	v_mfma_f32_16x16x32_bf16 v[26:29], v[160:163], v[204:207], v[26:29]
	v_mfma_f32_16x16x32_bf16 v[18:21], v[164:167], v[200:203], v[18:21]
	v_mfma_f32_16x16x32_bf16 v[18:21], v[180:183], v[204:207], v[18:21]
	v_mfma_f32_16x16x32_bf16 v[10:13], v[156:159], v[208:211], v[10:13]
	v_mfma_f32_16x16x32_bf16 v[10:13], v[160:163], v[212:215], v[10:13]
	v_mfma_f32_16x16x32_bf16 v[2:5], v[164:167], v[208:211], v[2:5]
	v_mfma_f32_16x16x32_bf16 v[2:5], v[180:183], v[212:215], v[2:5]
	s_setprio 0
	s_barrier
	ds_read_b128 v[130:133], v175
	ds_read_b128 v[134:137], v175 offset:1024
	ds_read_b128 v[148:151], v175 offset:2048
	ds_read_b128 v[152:155], v175 offset:3072
	ds_read_b128 v[156:159], v176
	ds_read_b128 v[160:163], v176 offset:1024
	ds_read_b128 v[164:167], v176 offset:2048
	ds_read_b128 v[180:183], v176 offset:3072
	s_mov_b32 m0, s64
	s_add_i32 s59, s53, 0x100000
	ds_read_b128 v[184:187], v174 offset:32768
	ds_read_b128 v[188:191], v174 offset:33792
	ds_read_b128 v[192:195], v174 offset:34816
	ds_read_b128 v[196:199], v174 offset:35840
	ds_read_b128 v[200:203], v174 offset:36864
	ds_read_b128 v[204:207], v174 offset:37888
	ds_read_b128 v[208:211], v174 offset:38912
	ds_read_b128 v[212:215], v174 offset:39936
	buffer_load_dwordx4 v170, s[12:15], s59 offen lds
	s_add_i32 s59, s53, 0x180000
	s_mov_b32 m0, s65
	s_nop 0
	buffer_load_dwordx4 v170, s[12:15], s59 offen lds
	s_waitcnt vmcnt(8)
	s_waitcnt lgkmcnt(0)
	s_setprio 1
	s_waitcnt lgkmcnt(7)
	v_mfma_f32_16x16x32_bf16 v[126:129], v[130:133], v[184:187], v[126:129]
	s_barrier
	v_mfma_f32_16x16x32_bf16 v[126:129], v[134:137], v[188:191], v[126:129]
	s_waitcnt lgkmcnt(5)
	v_mfma_f32_16x16x32_bf16 v[118:121], v[148:151], v[184:187], v[118:121]
	v_mfma_f32_16x16x32_bf16 v[118:121], v[152:155], v[188:191], v[118:121]
	s_waitcnt lgkmcnt(3)
	v_mfma_f32_16x16x32_bf16 v[110:113], v[130:133], v[192:195], v[110:113]
	v_mfma_f32_16x16x32_bf16 v[110:113], v[134:137], v[196:199], v[110:113]
	s_waitcnt lgkmcnt(1)
	v_mfma_f32_16x16x32_bf16 v[102:105], v[148:151], v[192:195], v[102:105]
	v_mfma_f32_16x16x32_bf16 v[102:105], v[152:155], v[196:199], v[102:105]
	v_mfma_f32_16x16x32_bf16 v[94:97], v[130:133], v[200:203], v[94:97]
	v_mfma_f32_16x16x32_bf16 v[94:97], v[134:137], v[204:207], v[94:97]
	v_mfma_f32_16x16x32_bf16 v[90:93], v[148:151], v[200:203], v[90:93]
	v_mfma_f32_16x16x32_bf16 v[90:93], v[152:155], v[204:207], v[90:93]
	v_mfma_f32_16x16x32_bf16 v[78:81], v[130:133], v[208:211], v[78:81]
	v_mfma_f32_16x16x32_bf16 v[78:81], v[134:137], v[212:215], v[78:81]
	v_mfma_f32_16x16x32_bf16 v[70:73], v[148:151], v[208:211], v[70:73]
	v_mfma_f32_16x16x32_bf16 v[70:73], v[152:155], v[212:215], v[70:73]
	v_mfma_f32_16x16x32_bf16 v[122:125], v[156:159], v[184:187], v[122:125]
	v_mfma_f32_16x16x32_bf16 v[122:125], v[160:163], v[188:191], v[122:125]
	v_mfma_f32_16x16x32_bf16 v[114:117], v[164:167], v[184:187], v[114:117]
	v_mfma_f32_16x16x32_bf16 v[114:117], v[180:183], v[188:191], v[114:117]
	v_mfma_f32_16x16x32_bf16 v[106:109], v[156:159], v[192:195], v[106:109]
	v_mfma_f32_16x16x32_bf16 v[106:109], v[160:163], v[196:199], v[106:109]
	s_waitcnt lgkmcnt(0)
	v_mfma_f32_16x16x32_bf16 v[98:101], v[164:167], v[192:195], v[98:101]
	v_mfma_f32_16x16x32_bf16 v[98:101], v[180:183], v[196:199], v[98:101]
	v_mfma_f32_16x16x32_bf16 v[86:89], v[156:159], v[200:203], v[86:89]
	v_mfma_f32_16x16x32_bf16 v[86:89], v[160:163], v[204:207], v[86:89]
	v_mfma_f32_16x16x32_bf16 v[82:85], v[164:167], v[200:203], v[82:85]
	v_mfma_f32_16x16x32_bf16 v[82:85], v[180:183], v[204:207], v[82:85]
	v_mfma_f32_16x16x32_bf16 v[74:77], v[156:159], v[208:211], v[74:77]
	v_mfma_f32_16x16x32_bf16 v[74:77], v[160:163], v[212:215], v[74:77]
	v_mfma_f32_16x16x32_bf16 v[66:69], v[164:167], v[208:211], v[66:69]
	v_mfma_f32_16x16x32_bf16 v[66:69], v[180:183], v[212:215], v[66:69]
	s_setprio 0
	s_barrier
	s_mov_b32 m0, s70
	s_or_b32 s59, s58, 0x80
	ds_read_b128 v[184:187], v174 offset:49152
	ds_read_b128 v[188:191], v174 offset:50176
	ds_read_b128 v[192:195], v174 offset:51200
	ds_read_b128 v[196:199], v174 offset:52224
	ds_read_b128 v[200:203], v174 offset:53248
	ds_read_b128 v[204:207], v174 offset:54272
	ds_read_b128 v[208:211], v174 offset:55296
	ds_read_b128 v[212:215], v174 offset:56320
	buffer_load_dwordx4 v171, s[16:19], s59 offen lds
	s_add_i32 s59, s58, 0x80080
	s_mov_b32 m0, s71
	s_add_i32 s53, s53, 0x80080
	buffer_load_dwordx4 v171, s[16:19], s59 offen lds
	s_add_i32 s59, s58, 0x100080
	s_mov_b32 m0, s74
	s_add_i32 s58, s58, 0x180080
	buffer_load_dwordx4 v171, s[16:19], s59 offen lds
	s_mov_b32 m0, s75
	s_nop 0
	buffer_load_dwordx4 v171, s[16:19], s58 offen lds
	s_mov_b32 m0, s72
	s_nop 0
	buffer_load_dwordx4 v170, s[12:15], s57 offen lds
	s_mov_b32 m0, s73
	s_nop 0
	buffer_load_dwordx4 v170, s[12:15], s53 offen lds
	s_waitcnt vmcnt(8)
	s_waitcnt lgkmcnt(0)
	s_setprio 1
	s_waitcnt lgkmcnt(7)
	v_mfma_f32_16x16x32_bf16 v[62:65], v[130:133], v[184:187], v[62:65]
	s_barrier
	v_mfma_f32_16x16x32_bf16 v[62:65], v[134:137], v[188:191], v[62:65]
	s_waitcnt lgkmcnt(5)
	v_mfma_f32_16x16x32_bf16 v[54:57], v[148:151], v[184:187], v[54:57]
	v_mfma_f32_16x16x32_bf16 v[54:57], v[152:155], v[188:191], v[54:57]
	s_waitcnt lgkmcnt(3)
	v_mfma_f32_16x16x32_bf16 v[46:49], v[130:133], v[192:195], v[46:49]
	v_mfma_f32_16x16x32_bf16 v[46:49], v[134:137], v[196:199], v[46:49]
	s_waitcnt lgkmcnt(1)
	v_mfma_f32_16x16x32_bf16 v[38:41], v[148:151], v[192:195], v[38:41]
	v_mfma_f32_16x16x32_bf16 v[38:41], v[152:155], v[196:199], v[38:41]
	v_mfma_f32_16x16x32_bf16 v[30:33], v[130:133], v[200:203], v[30:33]
	v_mfma_f32_16x16x32_bf16 v[30:33], v[134:137], v[204:207], v[30:33]
	v_mfma_f32_16x16x32_bf16 v[22:25], v[148:151], v[200:203], v[22:25]
	v_mfma_f32_16x16x32_bf16 v[22:25], v[152:155], v[204:207], v[22:25]
	v_mfma_f32_16x16x32_bf16 v[14:17], v[130:133], v[208:211], v[14:17]
	v_mfma_f32_16x16x32_bf16 v[14:17], v[134:137], v[212:215], v[14:17]
	v_mfma_f32_16x16x32_bf16 v[6:9], v[148:151], v[208:211], v[6:9]
	v_mfma_f32_16x16x32_bf16 v[6:9], v[152:155], v[212:215], v[6:9]
	v_mfma_f32_16x16x32_bf16 v[58:61], v[156:159], v[184:187], v[58:61]
	v_mfma_f32_16x16x32_bf16 v[58:61], v[160:163], v[188:191], v[58:61]
	v_mfma_f32_16x16x32_bf16 v[50:53], v[164:167], v[184:187], v[50:53]
	v_mfma_f32_16x16x32_bf16 v[50:53], v[180:183], v[188:191], v[50:53]
	v_mfma_f32_16x16x32_bf16 v[42:45], v[156:159], v[192:195], v[42:45]
	v_mfma_f32_16x16x32_bf16 v[42:45], v[160:163], v[196:199], v[42:45]
	s_waitcnt lgkmcnt(0)
	v_mfma_f32_16x16x32_bf16 v[34:37], v[164:167], v[192:195], v[34:37]
	v_mfma_f32_16x16x32_bf16 v[34:37], v[180:183], v[196:199], v[34:37]
	v_mfma_f32_16x16x32_bf16 v[26:29], v[156:159], v[200:203], v[26:29]
	v_mfma_f32_16x16x32_bf16 v[26:29], v[160:163], v[204:207], v[26:29]
	v_mfma_f32_16x16x32_bf16 v[18:21], v[164:167], v[200:203], v[18:21]
	v_mfma_f32_16x16x32_bf16 v[18:21], v[180:183], v[204:207], v[18:21]
	v_mfma_f32_16x16x32_bf16 v[10:13], v[156:159], v[208:211], v[10:13]
	v_mfma_f32_16x16x32_bf16 v[10:13], v[160:163], v[212:215], v[10:13]
	v_mfma_f32_16x16x32_bf16 v[2:5], v[164:167], v[208:211], v[2:5]
	v_mfma_f32_16x16x32_bf16 v[2:5], v[180:183], v[212:215], v[2:5]
	s_setprio 0
	s_barrier
	s_add_i32 s52, s52, 2
	s_addk_i32 s8, 0x100
	s_addk_i32 s9, 0x100
	s_cmp_ge_i32 s52, s21
	s_cbranch_scc0 .LBB0_892
	s_and_b64 vcc, exec, s[48:49]
	s_cbranch_vccz .LBB0_895

.LBB0_1020:
	v_add_u32_e32 v142, 0x10000, v162
	v_add_u32_e32 v150, 0x14000, v162
	ds_read_b128 v[130:133], v142
	ds_read_b128 v[134:137], v142 offset:1024
	ds_read_b128 v[138:141], v142 offset:2048
	ds_read_b128 v[142:145], v142 offset:3072
	ds_read_b128 v[154:157], v150
	ds_read_b128 v[164:167], v150 offset:1024
	ds_read_b128 v[168:171], v150 offset:2048
	ds_read_b128 v[172:175], v150 offset:3072
	s_add_i32 s90, s6, 0x100
	s_add_i32 s7, s88, s6
	s_cmp_eq_u32 s81, s89
	s_cselect_b32 s91, 0, s90
	s_cselect_b32 s93, s87, s7
	s_add_i32 s91, s91, s70
	s_or_b32 s92, s91, 0x80
	s_add_i32 s6, s3, s6
	s_mov_b32 m0, s82
	s_add_i32 s7, s6, 0x20080
	ds_read_b128 v[176:179], v163
	ds_read_b128 v[180:183], v163 offset:1024
	ds_read_b128 v[184:187], v163 offset:2048
	ds_read_b128 v[188:191], v163 offset:3072
	ds_read_b128 v[192:195], v163 offset:4096
	ds_read_b128 v[196:199], v163 offset:5120
	ds_read_b128 v[200:203], v163 offset:6144
	ds_read_b128 v[204:207], v163 offset:7168
	buffer_load_dwordx4 v161, s[12:15], s7 offen lds
	s_add_i32 s6, s6, 0x30080
	s_mov_b32 m0, s83
	s_nop 0
	buffer_load_dwordx4 v161, s[12:15], s6 offen lds
	s_waitcnt vmcnt(8)
	s_waitcnt lgkmcnt(0)
	s_setprio 1
	s_waitcnt lgkmcnt(0)
	v_mfma_f32_16x16x32_bf16 v[126:129], v[130:133], v[176:179], v[126:129]
	s_barrier
	v_mfma_f32_16x16x32_bf16 v[126:129], v[134:137], v[180:183], v[126:129]
	v_mfma_f32_16x16x32_bf16 v[122:125], v[138:141], v[176:179], v[122:125]
	v_mfma_f32_16x16x32_bf16 v[122:125], v[142:145], v[180:183], v[122:125]
	v_mfma_f32_16x16x32_bf16 v[110:113], v[130:133], v[184:187], v[110:113]
	v_mfma_f32_16x16x32_bf16 v[110:113], v[134:137], v[188:191], v[110:113]
	v_mfma_f32_16x16x32_bf16 v[106:109], v[138:141], v[184:187], v[106:109]
	v_mfma_f32_16x16x32_bf16 v[106:109], v[142:145], v[188:191], v[106:109]
	v_mfma_f32_16x16x32_bf16 v[94:97], v[130:133], v[192:195], v[94:97]
	v_mfma_f32_16x16x32_bf16 v[94:97], v[134:137], v[196:199], v[94:97]
	v_mfma_f32_16x16x32_bf16 v[90:93], v[138:141], v[192:195], v[90:93]
	v_mfma_f32_16x16x32_bf16 v[90:93], v[142:145], v[196:199], v[90:93]
	v_mfma_f32_16x16x32_bf16 v[78:81], v[130:133], v[200:203], v[78:81]
	v_mfma_f32_16x16x32_bf16 v[78:81], v[134:137], v[204:207], v[78:81]
	v_mfma_f32_16x16x32_bf16 v[74:77], v[138:141], v[200:203], v[74:77]
	v_mfma_f32_16x16x32_bf16 v[74:77], v[142:145], v[204:207], v[74:77]
	v_mfma_f32_16x16x32_bf16 v[118:121], v[154:157], v[176:179], v[118:121]
	v_mfma_f32_16x16x32_bf16 v[118:121], v[164:167], v[180:183], v[118:121]
	v_mfma_f32_16x16x32_bf16 v[114:117], v[168:171], v[176:179], v[114:117]
	v_mfma_f32_16x16x32_bf16 v[114:117], v[172:175], v[180:183], v[114:117]
	v_mfma_f32_16x16x32_bf16 v[102:105], v[154:157], v[184:187], v[102:105]
	v_mfma_f32_16x16x32_bf16 v[102:105], v[164:167], v[188:191], v[102:105]
	v_mfma_f32_16x16x32_bf16 v[98:101], v[168:171], v[184:187], v[98:101]
	v_mfma_f32_16x16x32_bf16 v[98:101], v[172:175], v[188:191], v[98:101]
	v_mfma_f32_16x16x32_bf16 v[86:89], v[154:157], v[192:195], v[86:89]
	v_mfma_f32_16x16x32_bf16 v[86:89], v[164:167], v[196:199], v[86:89]
	v_mfma_f32_16x16x32_bf16 v[82:85], v[168:171], v[192:195], v[82:85]
	v_mfma_f32_16x16x32_bf16 v[82:85], v[172:175], v[196:199], v[82:85]
	v_mfma_f32_16x16x32_bf16 v[70:73], v[154:157], v[200:203], v[70:73]
	v_mfma_f32_16x16x32_bf16 v[70:73], v[164:167], v[204:207], v[70:73]
	v_mfma_f32_16x16x32_bf16 v[66:69], v[168:171], v[200:203], v[66:69]
	v_mfma_f32_16x16x32_bf16 v[66:69], v[172:175], v[204:207], v[66:69]
	s_setprio 0
	s_barrier
	s_mov_b32 m0, s66
	s_mov_b32 s6, s14
	s_mov_b32 s7, s15
	ds_read_b128 v[176:179], v163 offset:16384
	ds_read_b128 v[180:183], v163 offset:17408
	ds_read_b128 v[184:187], v163 offset:18432
	ds_read_b128 v[188:191], v163 offset:19456
	ds_read_b128 v[192:195], v163 offset:20480
	ds_read_b128 v[196:199], v163 offset:21504
	ds_read_b128 v[200:203], v163 offset:22528
	ds_read_b128 v[204:207], v163 offset:23552
	buffer_load_dwordx4 v160, s[4:7], s93 offen lds
	s_add_i32 s94, s93, 0x10000
	s_mov_b32 m0, s67
	s_nop 0
	buffer_load_dwordx4 v160, s[4:7], s94 offen lds
	s_add_i32 s94, s93, 0x20000
	s_mov_b32 m0, s68
	s_nop 0
	buffer_load_dwordx4 v160, s[4:7], s94 offen lds
	s_add_i32 s94, s93, 0x30000
	s_mov_b32 m0, s69
	s_nop 0
	buffer_load_dwordx4 v160, s[4:7], s94 offen lds
	s_mov_b32 m0, s65
	s_add_i32 s94, s91, 0x10000
	buffer_load_dwordx4 v161, s[12:15], s91 offen lds
	s_mov_b32 m0, s71
	s_nop 0
	buffer_load_dwordx4 v161, s[12:15], s94 offen lds
	s_waitcnt vmcnt(8)
	s_waitcnt lgkmcnt(0)
	s_setprio 1
	s_waitcnt lgkmcnt(7)
	v_mfma_f32_16x16x32_bf16 v[62:65], v[130:133], v[176:179], v[62:65]
	s_barrier
	v_mfma_f32_16x16x32_bf16 v[62:65], v[134:137], v[180:183], v[62:65]
	s_waitcnt lgkmcnt(5)
	v_mfma_f32_16x16x32_bf16 v[58:61], v[138:141], v[176:179], v[58:61]
	v_mfma_f32_16x16x32_bf16 v[58:61], v[142:145], v[180:183], v[58:61]
	s_waitcnt lgkmcnt(3)
	v_mfma_f32_16x16x32_bf16 v[46:49], v[130:133], v[184:187], v[46:49]
	v_mfma_f32_16x16x32_bf16 v[46:49], v[134:137], v[188:191], v[46:49]
	s_waitcnt lgkmcnt(1)
	v_mfma_f32_16x16x32_bf16 v[42:45], v[138:141], v[184:187], v[42:45]
	v_mfma_f32_16x16x32_bf16 v[42:45], v[142:145], v[188:191], v[42:45]
	v_mfma_f32_16x16x32_bf16 v[30:33], v[130:133], v[192:195], v[30:33]
	v_mfma_f32_16x16x32_bf16 v[30:33], v[134:137], v[196:199], v[30:33]
	v_mfma_f32_16x16x32_bf16 v[26:29], v[138:141], v[192:195], v[26:29]
	v_mfma_f32_16x16x32_bf16 v[26:29], v[142:145], v[196:199], v[26:29]
	v_mfma_f32_16x16x32_bf16 v[14:17], v[130:133], v[200:203], v[14:17]
	v_mfma_f32_16x16x32_bf16 v[14:17], v[134:137], v[204:207], v[14:17]
	v_mfma_f32_16x16x32_bf16 v[10:13], v[138:141], v[200:203], v[10:13]
	v_mfma_f32_16x16x32_bf16 v[10:13], v[142:145], v[204:207], v[10:13]
	v_mfma_f32_16x16x32_bf16 v[54:57], v[154:157], v[176:179], v[54:57]
	v_mfma_f32_16x16x32_bf16 v[54:57], v[164:167], v[180:183], v[54:57]
	v_mfma_f32_16x16x32_bf16 v[50:53], v[168:171], v[176:179], v[50:53]
	v_mfma_f32_16x16x32_bf16 v[50:53], v[172:175], v[180:183], v[50:53]
	v_mfma_f32_16x16x32_bf16 v[38:41], v[154:157], v[184:187], v[38:41]
	v_mfma_f32_16x16x32_bf16 v[38:41], v[164:167], v[188:191], v[38:41]
	s_waitcnt lgkmcnt(0)
	v_mfma_f32_16x16x32_bf16 v[34:37], v[168:171], v[184:187], v[34:37]
	v_mfma_f32_16x16x32_bf16 v[34:37], v[172:175], v[188:191], v[34:37]
	v_mfma_f32_16x16x32_bf16 v[22:25], v[154:157], v[192:195], v[22:25]
	v_mfma_f32_16x16x32_bf16 v[22:25], v[164:167], v[196:199], v[22:25]
	v_mfma_f32_16x16x32_bf16 v[18:21], v[168:171], v[192:195], v[18:21]
	v_mfma_f32_16x16x32_bf16 v[18:21], v[172:175], v[196:199], v[18:21]
	v_mfma_f32_16x16x32_bf16 v[6:9], v[154:157], v[200:203], v[6:9]
	v_mfma_f32_16x16x32_bf16 v[6:9], v[164:167], v[204:207], v[6:9]
	v_mfma_f32_16x16x32_bf16 v[2:5], v[168:171], v[200:203], v[2:5]
	v_mfma_f32_16x16x32_bf16 v[2:5], v[172:175], v[204:207], v[2:5]
	s_setprio 0
	s_barrier
	v_add_u32_e32 v142, 0x18000, v162
	v_add_u32_e32 v150, 0x1c000, v162
	ds_read_b128 v[130:133], v142
	ds_read_b128 v[134:137], v142 offset:1024
	ds_read_b128 v[138:141], v142 offset:2048
	ds_read_b128 v[142:145], v142 offset:3072
	ds_read_b128 v[154:157], v150
	ds_read_b128 v[164:167], v150 offset:1024
	ds_read_b128 v[168:171], v150 offset:2048
	ds_read_b128 v[172:175], v150 offset:3072
	s_mov_b32 m0, s72
	s_add_i32 s94, s91, 0x20000
	ds_read_b128 v[176:179], v163 offset:32768
	ds_read_b128 v[180:183], v163 offset:33792
	ds_read_b128 v[184:187], v163 offset:34816
	ds_read_b128 v[188:191], v163 offset:35840
	ds_read_b128 v[192:195], v163 offset:36864
	ds_read_b128 v[196:199], v163 offset:37888
	ds_read_b128 v[200:203], v163 offset:38912
	ds_read_b128 v[204:207], v163 offset:39936
	buffer_load_dwordx4 v161, s[12:15], s94 offen lds
	s_add_i32 s94, s91, 0x30000
	s_mov_b32 m0, s73
	s_nop 0
	buffer_load_dwordx4 v161, s[12:15], s94 offen lds
	s_waitcnt vmcnt(8)
	s_waitcnt lgkmcnt(0)
	s_setprio 1
	s_waitcnt lgkmcnt(7)
	v_mfma_f32_16x16x32_bf16 v[126:129], v[130:133], v[176:179], v[126:129]
	s_barrier
	v_mfma_f32_16x16x32_bf16 v[126:129], v[134:137], v[180:183], v[126:129]
	s_waitcnt lgkmcnt(5)
	v_mfma_f32_16x16x32_bf16 v[122:125], v[138:141], v[176:179], v[122:125]
	v_mfma_f32_16x16x32_bf16 v[122:125], v[142:145], v[180:183], v[122:125]
	s_waitcnt lgkmcnt(3)
	v_mfma_f32_16x16x32_bf16 v[110:113], v[130:133], v[184:187], v[110:113]
	v_mfma_f32_16x16x32_bf16 v[110:113], v[134:137], v[188:191], v[110:113]
	s_waitcnt lgkmcnt(1)
	v_mfma_f32_16x16x32_bf16 v[106:109], v[138:141], v[184:187], v[106:109]
	v_mfma_f32_16x16x32_bf16 v[106:109], v[142:145], v[188:191], v[106:109]
	v_mfma_f32_16x16x32_bf16 v[94:97], v[130:133], v[192:195], v[94:97]
	v_mfma_f32_16x16x32_bf16 v[94:97], v[134:137], v[196:199], v[94:97]
	v_mfma_f32_16x16x32_bf16 v[90:93], v[138:141], v[192:195], v[90:93]
	v_mfma_f32_16x16x32_bf16 v[90:93], v[142:145], v[196:199], v[90:93]
	v_mfma_f32_16x16x32_bf16 v[78:81], v[130:133], v[200:203], v[78:81]
	v_mfma_f32_16x16x32_bf16 v[78:81], v[134:137], v[204:207], v[78:81]
	v_mfma_f32_16x16x32_bf16 v[74:77], v[138:141], v[200:203], v[74:77]
	v_mfma_f32_16x16x32_bf16 v[74:77], v[142:145], v[204:207], v[74:77]
	v_mfma_f32_16x16x32_bf16 v[118:121], v[154:157], v[176:179], v[118:121]
	v_mfma_f32_16x16x32_bf16 v[118:121], v[164:167], v[180:183], v[118:121]
	v_mfma_f32_16x16x32_bf16 v[114:117], v[168:171], v[176:179], v[114:117]
	v_mfma_f32_16x16x32_bf16 v[114:117], v[172:175], v[180:183], v[114:117]
	v_mfma_f32_16x16x32_bf16 v[102:105], v[154:157], v[184:187], v[102:105]
	v_mfma_f32_16x16x32_bf16 v[102:105], v[164:167], v[188:191], v[102:105]
	s_waitcnt lgkmcnt(0)
	v_mfma_f32_16x16x32_bf16 v[98:101], v[168:171], v[184:187], v[98:101]
	v_mfma_f32_16x16x32_bf16 v[98:101], v[172:175], v[188:191], v[98:101]
	v_mfma_f32_16x16x32_bf16 v[86:89], v[154:157], v[192:195], v[86:89]
	v_mfma_f32_16x16x32_bf16 v[86:89], v[164:167], v[196:199], v[86:89]
	v_mfma_f32_16x16x32_bf16 v[82:85], v[168:171], v[192:195], v[82:85]
	v_mfma_f32_16x16x32_bf16 v[82:85], v[172:175], v[196:199], v[82:85]
	v_mfma_f32_16x16x32_bf16 v[70:73], v[154:157], v[200:203], v[70:73]
	v_mfma_f32_16x16x32_bf16 v[70:73], v[164:167], v[204:207], v[70:73]
	v_mfma_f32_16x16x32_bf16 v[66:69], v[168:171], v[200:203], v[66:69]
	v_mfma_f32_16x16x32_bf16 v[66:69], v[172:175], v[204:207], v[66:69]
	s_setprio 0
	s_barrier
	s_mov_b32 m0, s74
	s_or_b32 s94, s93, 0x80
	ds_read_b128 v[176:179], v163 offset:49152
	ds_read_b128 v[180:183], v163 offset:50176
	ds_read_b128 v[184:187], v163 offset:51200
	ds_read_b128 v[188:191], v163 offset:52224
	ds_read_b128 v[192:195], v163 offset:53248
	ds_read_b128 v[196:199], v163 offset:54272
	ds_read_b128 v[200:203], v163 offset:55296
	ds_read_b128 v[204:207], v163 offset:56320
	buffer_load_dwordx4 v160, s[4:7], s94 offen lds
	s_add_i32 s94, s93, 0x10080
	s_mov_b32 m0, s75
	s_add_i32 s91, s91, 0x10080
	buffer_load_dwordx4 v160, s[4:7], s94 offen lds
	s_add_i32 s94, s93, 0x20080
	s_mov_b32 m0, s78
	s_add_i32 s93, s93, 0x30080
	buffer_load_dwordx4 v160, s[4:7], s94 offen lds
	s_mov_b32 m0, s79
	s_nop 0
	buffer_load_dwordx4 v160, s[4:7], s93 offen lds
	s_mov_b32 m0, s76
	s_nop 0
	buffer_load_dwordx4 v161, s[12:15], s92 offen lds
	s_mov_b32 m0, s77
	s_nop 0
	buffer_load_dwordx4 v161, s[12:15], s91 offen lds
	s_waitcnt vmcnt(8)
	s_waitcnt lgkmcnt(0)
	s_setprio 1
	s_waitcnt lgkmcnt(7)
	v_mfma_f32_16x16x32_bf16 v[62:65], v[130:133], v[176:179], v[62:65]
	s_barrier
	v_mfma_f32_16x16x32_bf16 v[62:65], v[134:137], v[180:183], v[62:65]
	s_waitcnt lgkmcnt(5)
	v_mfma_f32_16x16x32_bf16 v[58:61], v[138:141], v[176:179], v[58:61]
	v_mfma_f32_16x16x32_bf16 v[58:61], v[142:145], v[180:183], v[58:61]
	s_waitcnt lgkmcnt(3)
	v_mfma_f32_16x16x32_bf16 v[46:49], v[130:133], v[184:187], v[46:49]
	v_mfma_f32_16x16x32_bf16 v[46:49], v[134:137], v[188:191], v[46:49]
	s_waitcnt lgkmcnt(1)
	v_mfma_f32_16x16x32_bf16 v[42:45], v[138:141], v[184:187], v[42:45]
	v_mfma_f32_16x16x32_bf16 v[42:45], v[142:145], v[188:191], v[42:45]
	v_mfma_f32_16x16x32_bf16 v[30:33], v[130:133], v[192:195], v[30:33]
	v_mfma_f32_16x16x32_bf16 v[30:33], v[134:137], v[196:199], v[30:33]
	v_mfma_f32_16x16x32_bf16 v[26:29], v[138:141], v[192:195], v[26:29]
	v_mfma_f32_16x16x32_bf16 v[26:29], v[142:145], v[196:199], v[26:29]
	v_mfma_f32_16x16x32_bf16 v[14:17], v[130:133], v[200:203], v[14:17]
	v_mfma_f32_16x16x32_bf16 v[14:17], v[134:137], v[204:207], v[14:17]
	v_mfma_f32_16x16x32_bf16 v[10:13], v[138:141], v[200:203], v[10:13]
	v_mfma_f32_16x16x32_bf16 v[10:13], v[142:145], v[204:207], v[10:13]
	v_mfma_f32_16x16x32_bf16 v[54:57], v[154:157], v[176:179], v[54:57]
	v_mfma_f32_16x16x32_bf16 v[54:57], v[164:167], v[180:183], v[54:57]
	v_mfma_f32_16x16x32_bf16 v[50:53], v[168:171], v[176:179], v[50:53]
	v_mfma_f32_16x16x32_bf16 v[50:53], v[172:175], v[180:183], v[50:53]
	v_mfma_f32_16x16x32_bf16 v[38:41], v[154:157], v[184:187], v[38:41]
	v_mfma_f32_16x16x32_bf16 v[38:41], v[164:167], v[188:191], v[38:41]
	s_waitcnt lgkmcnt(0)
	v_mfma_f32_16x16x32_bf16 v[34:37], v[168:171], v[184:187], v[34:37]
	v_mfma_f32_16x16x32_bf16 v[34:37], v[172:175], v[188:191], v[34:37]
	v_mfma_f32_16x16x32_bf16 v[22:25], v[154:157], v[192:195], v[22:25]
	v_mfma_f32_16x16x32_bf16 v[22:25], v[164:167], v[196:199], v[22:25]
	v_mfma_f32_16x16x32_bf16 v[18:21], v[168:171], v[192:195], v[18:21]
	v_mfma_f32_16x16x32_bf16 v[18:21], v[172:175], v[196:199], v[18:21]
	v_mfma_f32_16x16x32_bf16 v[6:9], v[154:157], v[200:203], v[6:9]
	v_mfma_f32_16x16x32_bf16 v[6:9], v[164:167], v[204:207], v[6:9]
	v_mfma_f32_16x16x32_bf16 v[2:5], v[168:171], v[200:203], v[2:5]
	v_mfma_f32_16x16x32_bf16 v[2:5], v[172:175], v[204:207], v[2:5]
	s_setprio 0
	s_barrier
	s_add_i32 s89, s89, 2
	s_cmp_ge_i32 s89, s63
	s_mov_b32 s6, s90
	s_cbranch_scc0 .LBB0_1020
	s_and_b64 vcc, exec, s[54:55]
	s_cbranch_vccz .LBB0_1023

.LBB0_1035:
	ds_read_b128 v[140:143], v134
	ds_read_b128 v[148:151], v134 offset:1024
	ds_read_b128 v[152:155], v134 offset:2048
	ds_read_b128 v[156:159], v134 offset:3072
	ds_read_b128 v[160:163], v135
	ds_read_b128 v[164:167], v135 offset:1024
	ds_read_b128 v[168:171], v135 offset:2048
	ds_read_b128 v[172:175], v135 offset:3072
	s_add_i32 s73, s70, 0xfffb8080
	s_cmp_eq_u32 s53, s72
	s_cselect_b32 s73, s68, s73
	s_cselect_b32 s75, s69, s71
	s_add_i32 s74, s73, 0x80
	s_add_i32 s76, s70, 0xfffe8000
	s_mov_b32 m0, s54
	ds_read_b128 v[176:179], v136
	ds_read_b128 v[180:183], v136 offset:1024
	ds_read_b128 v[184:187], v136 offset:2048
	ds_read_b128 v[188:191], v136 offset:3072
	ds_read_b128 v[192:195], v136 offset:4096
	ds_read_b128 v[196:199], v136 offset:5120
	ds_read_b128 v[200:203], v136 offset:6144
	ds_read_b128 v[204:207], v136 offset:7168
	buffer_load_dwordx4 v132, s[12:15], s76 offen lds
	s_mov_b32 m0, s55
	s_nop 0
	buffer_load_dwordx4 v132, s[12:15], s70 offen lds
	s_waitcnt vmcnt(8)
	s_waitcnt lgkmcnt(0)
	s_setprio 1
	s_waitcnt lgkmcnt(7)
	v_mfma_f32_16x16x32_bf16 v[126:129], v[140:143], v[176:179], v[126:129]
	s_barrier
	v_mfma_f32_16x16x32_bf16 v[126:129], v[148:151], v[180:183], v[126:129]
	s_waitcnt lgkmcnt(5)
	v_mfma_f32_16x16x32_bf16 v[122:125], v[152:155], v[176:179], v[122:125]
	v_mfma_f32_16x16x32_bf16 v[122:125], v[156:159], v[180:183], v[122:125]
	s_waitcnt lgkmcnt(3)
	v_mfma_f32_16x16x32_bf16 v[110:113], v[140:143], v[184:187], v[110:113]
	v_mfma_f32_16x16x32_bf16 v[110:113], v[148:151], v[188:191], v[110:113]
	s_waitcnt lgkmcnt(1)
	v_mfma_f32_16x16x32_bf16 v[106:109], v[152:155], v[184:187], v[106:109]
	v_mfma_f32_16x16x32_bf16 v[106:109], v[156:159], v[188:191], v[106:109]
	v_mfma_f32_16x16x32_bf16 v[94:97], v[140:143], v[192:195], v[94:97]
	v_mfma_f32_16x16x32_bf16 v[94:97], v[148:151], v[196:199], v[94:97]
	v_mfma_f32_16x16x32_bf16 v[90:93], v[152:155], v[192:195], v[90:93]
	v_mfma_f32_16x16x32_bf16 v[90:93], v[156:159], v[196:199], v[90:93]
	v_mfma_f32_16x16x32_bf16 v[78:81], v[140:143], v[200:203], v[78:81]
	v_mfma_f32_16x16x32_bf16 v[78:81], v[148:151], v[204:207], v[78:81]
	v_mfma_f32_16x16x32_bf16 v[74:77], v[152:155], v[200:203], v[74:77]
	v_mfma_f32_16x16x32_bf16 v[74:77], v[156:159], v[204:207], v[74:77]
	v_mfma_f32_16x16x32_bf16 v[118:121], v[160:163], v[176:179], v[118:121]
	v_mfma_f32_16x16x32_bf16 v[118:121], v[164:167], v[180:183], v[118:121]
	v_mfma_f32_16x16x32_bf16 v[114:117], v[168:171], v[176:179], v[114:117]
	v_mfma_f32_16x16x32_bf16 v[114:117], v[172:175], v[180:183], v[114:117]
	v_mfma_f32_16x16x32_bf16 v[102:105], v[160:163], v[184:187], v[102:105]
	v_mfma_f32_16x16x32_bf16 v[102:105], v[164:167], v[188:191], v[102:105]
	s_waitcnt lgkmcnt(0)
	v_mfma_f32_16x16x32_bf16 v[98:101], v[168:171], v[184:187], v[98:101]
	v_mfma_f32_16x16x32_bf16 v[98:101], v[172:175], v[188:191], v[98:101]
	v_mfma_f32_16x16x32_bf16 v[86:89], v[160:163], v[192:195], v[86:89]
	v_mfma_f32_16x16x32_bf16 v[86:89], v[164:167], v[196:199], v[86:89]
	v_mfma_f32_16x16x32_bf16 v[82:85], v[168:171], v[192:195], v[82:85]
	v_mfma_f32_16x16x32_bf16 v[82:85], v[172:175], v[196:199], v[82:85]
	v_mfma_f32_16x16x32_bf16 v[70:73], v[160:163], v[200:203], v[70:73]
	v_mfma_f32_16x16x32_bf16 v[70:73], v[164:167], v[204:207], v[70:73]
	v_mfma_f32_16x16x32_bf16 v[66:69], v[168:171], v[200:203], v[66:69]
	v_mfma_f32_16x16x32_bf16 v[66:69], v[172:175], v[204:207], v[66:69]
	s_setprio 0
	s_barrier
	s_mov_b32 m0, s30
	ds_read_b128 v[176:179], v136 offset:16384
	ds_read_b128 v[180:183], v136 offset:17408
	ds_read_b128 v[184:187], v136 offset:18432
	ds_read_b128 v[188:191], v136 offset:19456
	ds_read_b128 v[192:195], v136 offset:20480
	ds_read_b128 v[196:199], v136 offset:21504
	ds_read_b128 v[200:203], v136 offset:22528
	ds_read_b128 v[204:207], v136 offset:23552
	buffer_load_dwordx4 v133, s[16:19], s75 offen lds
	s_add_i32 s76, s75, 0x200000
	s_mov_b32 m0, s31
	s_nop 0
	buffer_load_dwordx4 v133, s[16:19], s76 offen lds
	s_add_i32 s76, s75, 0x400000
	s_mov_b32 m0, s35
	s_nop 0
	buffer_load_dwordx4 v133, s[16:19], s76 offen lds
	s_add_i32 s76, s75, 0x600000
	s_mov_b32 m0, s42
	s_nop 0
	buffer_load_dwordx4 v133, s[16:19], s76 offen lds
	s_mov_b32 m0, s27
	s_add_i32 s76, s73, 0x18000
	buffer_load_dwordx4 v132, s[12:15], s73 offen lds
	s_mov_b32 m0, s43
	s_nop 0
	buffer_load_dwordx4 v132, s[12:15], s76 offen lds
	s_waitcnt vmcnt(8)
	s_waitcnt lgkmcnt(0)
	s_setprio 1
	s_waitcnt lgkmcnt(7)
	v_mfma_f32_16x16x32_bf16 v[62:65], v[140:143], v[176:179], v[62:65]
	s_barrier
	v_mfma_f32_16x16x32_bf16 v[62:65], v[148:151], v[180:183], v[62:65]
	s_waitcnt lgkmcnt(5)
	v_mfma_f32_16x16x32_bf16 v[58:61], v[152:155], v[176:179], v[58:61]
	v_mfma_f32_16x16x32_bf16 v[58:61], v[156:159], v[180:183], v[58:61]
	s_waitcnt lgkmcnt(3)
	v_mfma_f32_16x16x32_bf16 v[46:49], v[140:143], v[184:187], v[46:49]
	v_mfma_f32_16x16x32_bf16 v[46:49], v[148:151], v[188:191], v[46:49]
	s_waitcnt lgkmcnt(1)
	v_mfma_f32_16x16x32_bf16 v[42:45], v[152:155], v[184:187], v[42:45]
	v_mfma_f32_16x16x32_bf16 v[42:45], v[156:159], v[188:191], v[42:45]
	v_mfma_f32_16x16x32_bf16 v[30:33], v[140:143], v[192:195], v[30:33]
	v_mfma_f32_16x16x32_bf16 v[30:33], v[148:151], v[196:199], v[30:33]
	v_mfma_f32_16x16x32_bf16 v[26:29], v[152:155], v[192:195], v[26:29]
	v_mfma_f32_16x16x32_bf16 v[26:29], v[156:159], v[196:199], v[26:29]
	v_mfma_f32_16x16x32_bf16 v[14:17], v[140:143], v[200:203], v[14:17]
	v_mfma_f32_16x16x32_bf16 v[14:17], v[148:151], v[204:207], v[14:17]
	v_mfma_f32_16x16x32_bf16 v[10:13], v[152:155], v[200:203], v[10:13]
	v_mfma_f32_16x16x32_bf16 v[10:13], v[156:159], v[204:207], v[10:13]
	v_mfma_f32_16x16x32_bf16 v[54:57], v[160:163], v[176:179], v[54:57]
	v_mfma_f32_16x16x32_bf16 v[54:57], v[164:167], v[180:183], v[54:57]
	v_mfma_f32_16x16x32_bf16 v[50:53], v[168:171], v[176:179], v[50:53]
	v_mfma_f32_16x16x32_bf16 v[50:53], v[172:175], v[180:183], v[50:53]
	v_mfma_f32_16x16x32_bf16 v[38:41], v[160:163], v[184:187], v[38:41]
	v_mfma_f32_16x16x32_bf16 v[38:41], v[164:167], v[188:191], v[38:41]
	s_waitcnt lgkmcnt(0)
	v_mfma_f32_16x16x32_bf16 v[34:37], v[168:171], v[184:187], v[34:37]
	v_mfma_f32_16x16x32_bf16 v[34:37], v[172:175], v[188:191], v[34:37]
	v_mfma_f32_16x16x32_bf16 v[22:25], v[160:163], v[192:195], v[22:25]
	v_mfma_f32_16x16x32_bf16 v[22:25], v[164:167], v[196:199], v[22:25]
	v_mfma_f32_16x16x32_bf16 v[18:21], v[168:171], v[192:195], v[18:21]
	v_mfma_f32_16x16x32_bf16 v[18:21], v[172:175], v[196:199], v[18:21]
	v_mfma_f32_16x16x32_bf16 v[6:9], v[160:163], v[200:203], v[6:9]
	v_mfma_f32_16x16x32_bf16 v[6:9], v[164:167], v[204:207], v[6:9]
	v_mfma_f32_16x16x32_bf16 v[2:5], v[168:171], v[200:203], v[2:5]
	v_mfma_f32_16x16x32_bf16 v[2:5], v[172:175], v[204:207], v[2:5]
	s_setprio 0
	s_barrier
	ds_read_b128 v[140:143], v137
	ds_read_b128 v[148:151], v137 offset:1024
	ds_read_b128 v[152:155], v137 offset:2048
	ds_read_b128 v[156:159], v137 offset:3072
	ds_read_b128 v[160:163], v138
	ds_read_b128 v[164:167], v138 offset:1024
	ds_read_b128 v[168:171], v138 offset:2048
	ds_read_b128 v[172:175], v138 offset:3072
	s_mov_b32 m0, s44
	s_add_i32 s76, s73, 0x30000
	ds_read_b128 v[176:179], v136 offset:32768
	ds_read_b128 v[180:183], v136 offset:33792
	ds_read_b128 v[184:187], v136 offset:34816
	ds_read_b128 v[188:191], v136 offset:35840
	ds_read_b128 v[192:195], v136 offset:36864
	ds_read_b128 v[196:199], v136 offset:37888
	ds_read_b128 v[200:203], v136 offset:38912
	ds_read_b128 v[204:207], v136 offset:39936
	buffer_load_dwordx4 v132, s[12:15], s76 offen lds
	s_add_i32 s76, s73, 0x48000
	s_mov_b32 m0, s45
	s_nop 0
	buffer_load_dwordx4 v132, s[12:15], s76 offen lds
	s_waitcnt vmcnt(8)
	s_waitcnt lgkmcnt(0)
	s_setprio 1
	s_waitcnt lgkmcnt(7)
	v_mfma_f32_16x16x32_bf16 v[126:129], v[140:143], v[176:179], v[126:129]
	s_barrier
	v_mfma_f32_16x16x32_bf16 v[126:129], v[148:151], v[180:183], v[126:129]
	s_waitcnt lgkmcnt(5)
	v_mfma_f32_16x16x32_bf16 v[122:125], v[152:155], v[176:179], v[122:125]
	v_mfma_f32_16x16x32_bf16 v[122:125], v[156:159], v[180:183], v[122:125]
	s_waitcnt lgkmcnt(3)
	v_mfma_f32_16x16x32_bf16 v[110:113], v[140:143], v[184:187], v[110:113]
	v_mfma_f32_16x16x32_bf16 v[110:113], v[148:151], v[188:191], v[110:113]
	s_waitcnt lgkmcnt(1)
	v_mfma_f32_16x16x32_bf16 v[106:109], v[152:155], v[184:187], v[106:109]
	v_mfma_f32_16x16x32_bf16 v[106:109], v[156:159], v[188:191], v[106:109]
	v_mfma_f32_16x16x32_bf16 v[94:97], v[140:143], v[192:195], v[94:97]
	v_mfma_f32_16x16x32_bf16 v[94:97], v[148:151], v[196:199], v[94:97]
	v_mfma_f32_16x16x32_bf16 v[90:93], v[152:155], v[192:195], v[90:93]
	v_mfma_f32_16x16x32_bf16 v[90:93], v[156:159], v[196:199], v[90:93]
	v_mfma_f32_16x16x32_bf16 v[78:81], v[140:143], v[200:203], v[78:81]
	v_mfma_f32_16x16x32_bf16 v[78:81], v[148:151], v[204:207], v[78:81]
	v_mfma_f32_16x16x32_bf16 v[74:77], v[152:155], v[200:203], v[74:77]
	v_mfma_f32_16x16x32_bf16 v[74:77], v[156:159], v[204:207], v[74:77]
	v_mfma_f32_16x16x32_bf16 v[118:121], v[160:163], v[176:179], v[118:121]
	v_mfma_f32_16x16x32_bf16 v[118:121], v[164:167], v[180:183], v[118:121]
	v_mfma_f32_16x16x32_bf16 v[114:117], v[168:171], v[176:179], v[114:117]
	v_mfma_f32_16x16x32_bf16 v[114:117], v[172:175], v[180:183], v[114:117]
	v_mfma_f32_16x16x32_bf16 v[102:105], v[160:163], v[184:187], v[102:105]
	v_mfma_f32_16x16x32_bf16 v[102:105], v[164:167], v[188:191], v[102:105]
	s_waitcnt lgkmcnt(0)
	v_mfma_f32_16x16x32_bf16 v[98:101], v[168:171], v[184:187], v[98:101]
	v_mfma_f32_16x16x32_bf16 v[98:101], v[172:175], v[188:191], v[98:101]
	v_mfma_f32_16x16x32_bf16 v[86:89], v[160:163], v[192:195], v[86:89]
	v_mfma_f32_16x16x32_bf16 v[86:89], v[164:167], v[196:199], v[86:89]
	v_mfma_f32_16x16x32_bf16 v[82:85], v[168:171], v[192:195], v[82:85]
	v_mfma_f32_16x16x32_bf16 v[82:85], v[172:175], v[196:199], v[82:85]
	v_mfma_f32_16x16x32_bf16 v[70:73], v[160:163], v[200:203], v[70:73]
	v_mfma_f32_16x16x32_bf16 v[70:73], v[164:167], v[204:207], v[70:73]
	v_mfma_f32_16x16x32_bf16 v[66:69], v[168:171], v[200:203], v[66:69]
	v_mfma_f32_16x16x32_bf16 v[66:69], v[172:175], v[204:207], v[66:69]
	s_setprio 0
	s_barrier
	s_mov_b32 m0, s46
	s_add_i32 s76, s75, 0x80
	ds_read_b128 v[176:179], v136 offset:49152
	ds_read_b128 v[180:183], v136 offset:50176
	ds_read_b128 v[184:187], v136 offset:51200
	ds_read_b128 v[188:191], v136 offset:52224
	ds_read_b128 v[192:195], v136 offset:53248
	ds_read_b128 v[196:199], v136 offset:54272
	ds_read_b128 v[200:203], v136 offset:55296
	ds_read_b128 v[204:207], v136 offset:56320
	buffer_load_dwordx4 v133, s[16:19], s76 offen lds
	s_add_i32 s76, s75, 0x200080
	s_mov_b32 m0, s47
	s_add_i32 s73, s73, 0x18080
	buffer_load_dwordx4 v133, s[16:19], s76 offen lds
	s_add_i32 s76, s75, 0x400080
	s_mov_b32 m0, s50
	s_add_i32 s75, s75, 0x600080
	buffer_load_dwordx4 v133, s[16:19], s76 offen lds
	s_mov_b32 m0, s51
	s_nop 0
	buffer_load_dwordx4 v133, s[16:19], s75 offen lds
	s_mov_b32 m0, s48
	s_nop 0
	buffer_load_dwordx4 v132, s[12:15], s74 offen lds
	s_mov_b32 m0, s49
	s_nop 0
	buffer_load_dwordx4 v132, s[12:15], s73 offen lds
	s_waitcnt vmcnt(8)
	s_waitcnt lgkmcnt(0)
	s_setprio 1
	s_waitcnt lgkmcnt(7)
	v_mfma_f32_16x16x32_bf16 v[62:65], v[140:143], v[176:179], v[62:65]
	s_barrier
	v_mfma_f32_16x16x32_bf16 v[62:65], v[148:151], v[180:183], v[62:65]
	s_waitcnt lgkmcnt(5)
	v_mfma_f32_16x16x32_bf16 v[58:61], v[152:155], v[176:179], v[58:61]
	v_mfma_f32_16x16x32_bf16 v[58:61], v[156:159], v[180:183], v[58:61]
	s_waitcnt lgkmcnt(3)
	v_mfma_f32_16x16x32_bf16 v[46:49], v[140:143], v[184:187], v[46:49]
	v_mfma_f32_16x16x32_bf16 v[46:49], v[148:151], v[188:191], v[46:49]
	s_waitcnt lgkmcnt(1)
	v_mfma_f32_16x16x32_bf16 v[42:45], v[152:155], v[184:187], v[42:45]
	v_mfma_f32_16x16x32_bf16 v[42:45], v[156:159], v[188:191], v[42:45]
	v_mfma_f32_16x16x32_bf16 v[30:33], v[140:143], v[192:195], v[30:33]
	v_mfma_f32_16x16x32_bf16 v[30:33], v[148:151], v[196:199], v[30:33]
	v_mfma_f32_16x16x32_bf16 v[26:29], v[152:155], v[192:195], v[26:29]
	v_mfma_f32_16x16x32_bf16 v[26:29], v[156:159], v[196:199], v[26:29]
	v_mfma_f32_16x16x32_bf16 v[14:17], v[140:143], v[200:203], v[14:17]
	v_mfma_f32_16x16x32_bf16 v[14:17], v[148:151], v[204:207], v[14:17]
	v_mfma_f32_16x16x32_bf16 v[10:13], v[152:155], v[200:203], v[10:13]
	v_mfma_f32_16x16x32_bf16 v[10:13], v[156:159], v[204:207], v[10:13]
	v_mfma_f32_16x16x32_bf16 v[54:57], v[160:163], v[176:179], v[54:57]
	v_mfma_f32_16x16x32_bf16 v[54:57], v[164:167], v[180:183], v[54:57]
	v_mfma_f32_16x16x32_bf16 v[50:53], v[168:171], v[176:179], v[50:53]
	v_mfma_f32_16x16x32_bf16 v[50:53], v[172:175], v[180:183], v[50:53]
	v_mfma_f32_16x16x32_bf16 v[38:41], v[160:163], v[184:187], v[38:41]
	v_mfma_f32_16x16x32_bf16 v[38:41], v[164:167], v[188:191], v[38:41]
	s_waitcnt lgkmcnt(0)
	v_mfma_f32_16x16x32_bf16 v[34:37], v[168:171], v[184:187], v[34:37]
	v_mfma_f32_16x16x32_bf16 v[34:37], v[172:175], v[188:191], v[34:37]
	v_mfma_f32_16x16x32_bf16 v[22:25], v[160:163], v[192:195], v[22:25]
	v_mfma_f32_16x16x32_bf16 v[22:25], v[164:167], v[196:199], v[22:25]
	v_mfma_f32_16x16x32_bf16 v[18:21], v[168:171], v[192:195], v[18:21]
	v_mfma_f32_16x16x32_bf16 v[18:21], v[172:175], v[196:199], v[18:21]
	v_mfma_f32_16x16x32_bf16 v[6:9], v[160:163], v[200:203], v[6:9]
	v_mfma_f32_16x16x32_bf16 v[6:9], v[164:167], v[204:207], v[6:9]
	v_mfma_f32_16x16x32_bf16 v[2:5], v[168:171], v[200:203], v[2:5]
	v_mfma_f32_16x16x32_bf16 v[2:5], v[172:175], v[204:207], v[2:5]
	s_setprio 0
	s_barrier
	s_add_i32 s72, s72, 2
	s_addk_i32 s70, 0x100
	s_addk_i32 s71, 0x100
	s_cmp_ge_i32 s72, s21
	s_cbranch_scc0 .LBB0_1035

.LBB0_1050:
	ds_read_b128 v[132:135], v142
	ds_read_b128 v[136:139], v142 offset:1024
	ds_read_b128 v[148:151], v142 offset:2048
	ds_read_b128 v[152:155], v142 offset:3072
	ds_read_b128 v[156:159], v143
	ds_read_b128 v[160:163], v143 offset:1024
	ds_read_b128 v[164:167], v143 offset:2048
	ds_read_b128 v[168:171], v143 offset:3072
	s_add_i32 s18, s61, 0xfff40080
	s_cmp_eq_u32 s54, s62
	s_cselect_b32 s64, s35, s18
	s_add_i32 s63, s64, 0x80
	s_add_i32 s18, s61, 0xfffc0000
	s_mov_b32 m0, s55
	ds_read_b128 v[172:175], v144
	ds_read_b128 v[176:179], v144 offset:1024
	ds_read_b128 v[180:183], v144 offset:2048
	ds_read_b128 v[184:187], v144 offset:3072
	ds_read_b128 v[188:191], v144 offset:4096
	ds_read_b128 v[192:195], v144 offset:5120
	ds_read_b128 v[196:199], v144 offset:6144
	ds_read_b128 v[200:203], v144 offset:7168
	buffer_load_dwordx4 v140, s[12:15], s18 offen lds
	s_mov_b32 m0, s56
	s_nop 0
	buffer_load_dwordx4 v140, s[12:15], s61 offen lds
	s_waitcnt vmcnt(8)
	s_waitcnt lgkmcnt(0)
	s_setprio 1
	s_waitcnt lgkmcnt(7)
	v_mfma_f32_16x16x32_bf16 v[126:129], v[132:135], v[172:175], v[126:129]
	s_barrier
	v_mfma_f32_16x16x32_bf16 v[126:129], v[136:139], v[176:179], v[126:129]
	s_waitcnt lgkmcnt(5)
	v_mfma_f32_16x16x32_bf16 v[122:125], v[148:151], v[172:175], v[122:125]
	v_mfma_f32_16x16x32_bf16 v[122:125], v[152:155], v[176:179], v[122:125]
	s_waitcnt lgkmcnt(3)
	v_mfma_f32_16x16x32_bf16 v[110:113], v[132:135], v[180:183], v[110:113]
	v_mfma_f32_16x16x32_bf16 v[110:113], v[136:139], v[184:187], v[110:113]
	s_waitcnt lgkmcnt(1)
	v_mfma_f32_16x16x32_bf16 v[106:109], v[148:151], v[180:183], v[106:109]
	v_mfma_f32_16x16x32_bf16 v[106:109], v[152:155], v[184:187], v[106:109]
	v_mfma_f32_16x16x32_bf16 v[94:97], v[132:135], v[188:191], v[94:97]
	v_mfma_f32_16x16x32_bf16 v[94:97], v[136:139], v[192:195], v[94:97]
	v_mfma_f32_16x16x32_bf16 v[90:93], v[148:151], v[188:191], v[90:93]
	v_mfma_f32_16x16x32_bf16 v[90:93], v[152:155], v[192:195], v[90:93]
	v_mfma_f32_16x16x32_bf16 v[78:81], v[132:135], v[196:199], v[78:81]
	v_mfma_f32_16x16x32_bf16 v[78:81], v[136:139], v[200:203], v[78:81]
	v_mfma_f32_16x16x32_bf16 v[74:77], v[148:151], v[196:199], v[74:77]
	v_mfma_f32_16x16x32_bf16 v[74:77], v[152:155], v[200:203], v[74:77]
	v_mfma_f32_16x16x32_bf16 v[118:121], v[156:159], v[172:175], v[118:121]
	v_mfma_f32_16x16x32_bf16 v[118:121], v[160:163], v[176:179], v[118:121]
	v_mfma_f32_16x16x32_bf16 v[114:117], v[164:167], v[172:175], v[114:117]
	v_mfma_f32_16x16x32_bf16 v[114:117], v[168:171], v[176:179], v[114:117]
	v_mfma_f32_16x16x32_bf16 v[102:105], v[156:159], v[180:183], v[102:105]
	v_mfma_f32_16x16x32_bf16 v[102:105], v[160:163], v[184:187], v[102:105]
	s_waitcnt lgkmcnt(0)
	v_mfma_f32_16x16x32_bf16 v[98:101], v[164:167], v[180:183], v[98:101]
	v_mfma_f32_16x16x32_bf16 v[98:101], v[168:171], v[184:187], v[98:101]
	v_mfma_f32_16x16x32_bf16 v[86:89], v[156:159], v[188:191], v[86:89]
	v_mfma_f32_16x16x32_bf16 v[86:89], v[160:163], v[192:195], v[86:89]
	v_mfma_f32_16x16x32_bf16 v[82:85], v[164:167], v[188:191], v[82:85]
	v_mfma_f32_16x16x32_bf16 v[82:85], v[168:171], v[192:195], v[82:85]
	v_mfma_f32_16x16x32_bf16 v[70:73], v[156:159], v[196:199], v[70:73]
	v_mfma_f32_16x16x32_bf16 v[70:73], v[160:163], v[200:203], v[70:73]
	v_mfma_f32_16x16x32_bf16 v[66:69], v[164:167], v[196:199], v[66:69]
	v_mfma_f32_16x16x32_bf16 v[66:69], v[168:171], v[200:203], v[66:69]
	s_setprio 0
	s_barrier
	s_mov_b32 m0, s25
	s_mov_b32 s18, s14
	s_mov_b32 s19, s15
	ds_read_b128 v[172:175], v144 offset:16384
	ds_read_b128 v[176:179], v144 offset:17408
	ds_read_b128 v[180:183], v144 offset:18432
	ds_read_b128 v[184:187], v144 offset:19456
	ds_read_b128 v[188:191], v144 offset:20480
	ds_read_b128 v[192:195], v144 offset:21504
	ds_read_b128 v[196:199], v144 offset:22528
	ds_read_b128 v[200:203], v144 offset:23552
	buffer_load_dwordx4 v141, s[16:19], s64 offen lds
	s_add_i32 s65, s64, 0x40000
	s_mov_b32 m0, s27
	s_add_i32 s66, s64, 0x80000
	buffer_load_dwordx4 v141, s[16:19], s65 offen lds
	s_mov_b32 m0, s30
	s_add_i32 s67, s64, 0xc0000
	buffer_load_dwordx4 v141, s[16:19], s66 offen lds
	s_mov_b32 m0, s31
	s_nop 0
	buffer_load_dwordx4 v141, s[16:19], s67 offen lds
	s_mov_b32 m0, s21
	s_nop 0
	buffer_load_dwordx4 v140, s[12:15], s64 offen lds
	s_mov_b32 m0, s38
	s_nop 0
	buffer_load_dwordx4 v140, s[12:15], s65 offen lds
	s_waitcnt vmcnt(8)
	s_waitcnt lgkmcnt(0)
	s_setprio 1
	s_waitcnt lgkmcnt(7)
	v_mfma_f32_16x16x32_bf16 v[62:65], v[132:135], v[172:175], v[62:65]
	s_barrier
	v_mfma_f32_16x16x32_bf16 v[62:65], v[136:139], v[176:179], v[62:65]
	s_waitcnt lgkmcnt(5)
	v_mfma_f32_16x16x32_bf16 v[58:61], v[148:151], v[172:175], v[58:61]
	v_mfma_f32_16x16x32_bf16 v[58:61], v[152:155], v[176:179], v[58:61]
	s_waitcnt lgkmcnt(3)
	v_mfma_f32_16x16x32_bf16 v[46:49], v[132:135], v[180:183], v[46:49]
	v_mfma_f32_16x16x32_bf16 v[46:49], v[136:139], v[184:187], v[46:49]
	s_waitcnt lgkmcnt(1)
	v_mfma_f32_16x16x32_bf16 v[42:45], v[148:151], v[180:183], v[42:45]
	v_mfma_f32_16x16x32_bf16 v[42:45], v[152:155], v[184:187], v[42:45]
	v_mfma_f32_16x16x32_bf16 v[30:33], v[132:135], v[188:191], v[30:33]
	v_mfma_f32_16x16x32_bf16 v[30:33], v[136:139], v[192:195], v[30:33]
	v_mfma_f32_16x16x32_bf16 v[26:29], v[148:151], v[188:191], v[26:29]
	v_mfma_f32_16x16x32_bf16 v[26:29], v[152:155], v[192:195], v[26:29]
	v_mfma_f32_16x16x32_bf16 v[14:17], v[132:135], v[196:199], v[14:17]
	v_mfma_f32_16x16x32_bf16 v[14:17], v[136:139], v[200:203], v[14:17]
	v_mfma_f32_16x16x32_bf16 v[10:13], v[148:151], v[196:199], v[10:13]
	v_mfma_f32_16x16x32_bf16 v[10:13], v[152:155], v[200:203], v[10:13]
	v_mfma_f32_16x16x32_bf16 v[54:57], v[156:159], v[172:175], v[54:57]
	v_mfma_f32_16x16x32_bf16 v[54:57], v[160:163], v[176:179], v[54:57]
	v_mfma_f32_16x16x32_bf16 v[50:53], v[164:167], v[172:175], v[50:53]
	v_mfma_f32_16x16x32_bf16 v[50:53], v[168:171], v[176:179], v[50:53]
	v_mfma_f32_16x16x32_bf16 v[38:41], v[156:159], v[180:183], v[38:41]
	v_mfma_f32_16x16x32_bf16 v[38:41], v[160:163], v[184:187], v[38:41]
	s_waitcnt lgkmcnt(0)
	v_mfma_f32_16x16x32_bf16 v[34:37], v[164:167], v[180:183], v[34:37]
	v_mfma_f32_16x16x32_bf16 v[34:37], v[168:171], v[184:187], v[34:37]
	v_mfma_f32_16x16x32_bf16 v[22:25], v[156:159], v[188:191], v[22:25]
	v_mfma_f32_16x16x32_bf16 v[22:25], v[160:163], v[192:195], v[22:25]
	v_mfma_f32_16x16x32_bf16 v[18:21], v[164:167], v[188:191], v[18:21]
	v_mfma_f32_16x16x32_bf16 v[18:21], v[168:171], v[192:195], v[18:21]
	v_mfma_f32_16x16x32_bf16 v[6:9], v[156:159], v[196:199], v[6:9]
	v_mfma_f32_16x16x32_bf16 v[6:9], v[160:163], v[200:203], v[6:9]
	v_mfma_f32_16x16x32_bf16 v[2:5], v[164:167], v[196:199], v[2:5]
	v_mfma_f32_16x16x32_bf16 v[2:5], v[168:171], v[200:203], v[2:5]
	s_setprio 0
	s_barrier
	ds_read_b128 v[132:135], v145
	ds_read_b128 v[136:139], v145 offset:1024
	ds_read_b128 v[148:151], v145 offset:2048
	ds_read_b128 v[152:155], v145 offset:3072
	ds_read_b128 v[156:159], v147
	ds_read_b128 v[160:163], v147 offset:1024
	ds_read_b128 v[164:167], v147 offset:2048
	ds_read_b128 v[168:171], v147 offset:3072
	s_mov_b32 m0, s39
	ds_read_b128 v[172:175], v144 offset:32768
	ds_read_b128 v[176:179], v144 offset:33792
	ds_read_b128 v[180:183], v144 offset:34816
	ds_read_b128 v[184:187], v144 offset:35840
	ds_read_b128 v[188:191], v144 offset:36864
	ds_read_b128 v[192:195], v144 offset:37888
	ds_read_b128 v[196:199], v144 offset:38912
	ds_read_b128 v[200:203], v144 offset:39936
	buffer_load_dwordx4 v140, s[12:15], s66 offen lds
	s_mov_b32 m0, s40
	s_nop 0
	buffer_load_dwordx4 v140, s[12:15], s67 offen lds
	s_waitcnt vmcnt(8)
	s_waitcnt lgkmcnt(0)
	s_setprio 1
	s_waitcnt lgkmcnt(7)
	v_mfma_f32_16x16x32_bf16 v[126:129], v[132:135], v[172:175], v[126:129]
	s_barrier
	v_mfma_f32_16x16x32_bf16 v[126:129], v[136:139], v[176:179], v[126:129]
	s_waitcnt lgkmcnt(5)
	v_mfma_f32_16x16x32_bf16 v[122:125], v[148:151], v[172:175], v[122:125]
	v_mfma_f32_16x16x32_bf16 v[122:125], v[152:155], v[176:179], v[122:125]
	s_waitcnt lgkmcnt(3)
	v_mfma_f32_16x16x32_bf16 v[110:113], v[132:135], v[180:183], v[110:113]
	v_mfma_f32_16x16x32_bf16 v[110:113], v[136:139], v[184:187], v[110:113]
	s_waitcnt lgkmcnt(1)
	v_mfma_f32_16x16x32_bf16 v[106:109], v[148:151], v[180:183], v[106:109]
	v_mfma_f32_16x16x32_bf16 v[106:109], v[152:155], v[184:187], v[106:109]
	v_mfma_f32_16x16x32_bf16 v[94:97], v[132:135], v[188:191], v[94:97]
	v_mfma_f32_16x16x32_bf16 v[94:97], v[136:139], v[192:195], v[94:97]
	v_mfma_f32_16x16x32_bf16 v[90:93], v[148:151], v[188:191], v[90:93]
	v_mfma_f32_16x16x32_bf16 v[90:93], v[152:155], v[192:195], v[90:93]
	v_mfma_f32_16x16x32_bf16 v[78:81], v[132:135], v[196:199], v[78:81]
	v_mfma_f32_16x16x32_bf16 v[78:81], v[136:139], v[200:203], v[78:81]
	v_mfma_f32_16x16x32_bf16 v[74:77], v[148:151], v[196:199], v[74:77]
	v_mfma_f32_16x16x32_bf16 v[74:77], v[152:155], v[200:203], v[74:77]
	v_mfma_f32_16x16x32_bf16 v[118:121], v[156:159], v[172:175], v[118:121]
	v_mfma_f32_16x16x32_bf16 v[118:121], v[160:163], v[176:179], v[118:121]
	v_mfma_f32_16x16x32_bf16 v[114:117], v[164:167], v[172:175], v[114:117]
	v_mfma_f32_16x16x32_bf16 v[114:117], v[168:171], v[176:179], v[114:117]
	v_mfma_f32_16x16x32_bf16 v[102:105], v[156:159], v[180:183], v[102:105]
	v_mfma_f32_16x16x32_bf16 v[102:105], v[160:163], v[184:187], v[102:105]
	s_waitcnt lgkmcnt(0)
	v_mfma_f32_16x16x32_bf16 v[98:101], v[164:167], v[180:183], v[98:101]
	v_mfma_f32_16x16x32_bf16 v[98:101], v[168:171], v[184:187], v[98:101]
	v_mfma_f32_16x16x32_bf16 v[86:89], v[156:159], v[188:191], v[86:89]
	v_mfma_f32_16x16x32_bf16 v[86:89], v[160:163], v[192:195], v[86:89]
	v_mfma_f32_16x16x32_bf16 v[82:85], v[164:167], v[188:191], v[82:85]
	v_mfma_f32_16x16x32_bf16 v[82:85], v[168:171], v[192:195], v[82:85]
	v_mfma_f32_16x16x32_bf16 v[70:73], v[156:159], v[196:199], v[70:73]
	v_mfma_f32_16x16x32_bf16 v[70:73], v[160:163], v[200:203], v[70:73]
	v_mfma_f32_16x16x32_bf16 v[66:69], v[164:167], v[196:199], v[66:69]
	v_mfma_f32_16x16x32_bf16 v[66:69], v[168:171], v[200:203], v[66:69]
	s_setprio 0
	s_barrier
	s_mov_b32 m0, s48
	ds_read_b128 v[172:175], v144 offset:49152
	ds_read_b128 v[176:179], v144 offset:50176
	ds_read_b128 v[180:183], v144 offset:51200
	ds_read_b128 v[184:187], v144 offset:52224
	ds_read_b128 v[188:191], v144 offset:53248
	ds_read_b128 v[192:195], v144 offset:54272
	ds_read_b128 v[196:199], v144 offset:55296
	ds_read_b128 v[200:203], v144 offset:56320
	buffer_load_dwordx4 v141, s[16:19], s63 offen lds
	s_add_i32 s65, s64, 0x40080
	s_mov_b32 m0, s49
	s_add_i32 s66, s64, 0x80080
	buffer_load_dwordx4 v141, s[16:19], s65 offen lds
	s_mov_b32 m0, s52
	s_add_i32 s64, s64, 0xc0080
	buffer_load_dwordx4 v141, s[16:19], s66 offen lds
	s_mov_b32 m0, s53
	s_nop 0
	buffer_load_dwordx4 v141, s[16:19], s64 offen lds
	s_mov_b32 m0, s50
	s_nop 0
	buffer_load_dwordx4 v140, s[12:15], s63 offen lds
	s_mov_b32 m0, s51
	s_nop 0
	buffer_load_dwordx4 v140, s[12:15], s65 offen lds
	s_waitcnt vmcnt(8)
	s_waitcnt lgkmcnt(0)
	s_setprio 1
	s_waitcnt lgkmcnt(7)
	v_mfma_f32_16x16x32_bf16 v[62:65], v[132:135], v[172:175], v[62:65]
	s_barrier
	v_mfma_f32_16x16x32_bf16 v[62:65], v[136:139], v[176:179], v[62:65]
	s_waitcnt lgkmcnt(5)
	v_mfma_f32_16x16x32_bf16 v[58:61], v[148:151], v[172:175], v[58:61]
	v_mfma_f32_16x16x32_bf16 v[58:61], v[152:155], v[176:179], v[58:61]
	s_waitcnt lgkmcnt(3)
	v_mfma_f32_16x16x32_bf16 v[46:49], v[132:135], v[180:183], v[46:49]
	v_mfma_f32_16x16x32_bf16 v[46:49], v[136:139], v[184:187], v[46:49]
	s_waitcnt lgkmcnt(1)
	v_mfma_f32_16x16x32_bf16 v[42:45], v[148:151], v[180:183], v[42:45]
	v_mfma_f32_16x16x32_bf16 v[42:45], v[152:155], v[184:187], v[42:45]
	v_mfma_f32_16x16x32_bf16 v[30:33], v[132:135], v[188:191], v[30:33]
	v_mfma_f32_16x16x32_bf16 v[30:33], v[136:139], v[192:195], v[30:33]
	v_mfma_f32_16x16x32_bf16 v[26:29], v[148:151], v[188:191], v[26:29]
	v_mfma_f32_16x16x32_bf16 v[26:29], v[152:155], v[192:195], v[26:29]
	v_mfma_f32_16x16x32_bf16 v[14:17], v[132:135], v[196:199], v[14:17]
	v_mfma_f32_16x16x32_bf16 v[14:17], v[136:139], v[200:203], v[14:17]
	v_mfma_f32_16x16x32_bf16 v[10:13], v[148:151], v[196:199], v[10:13]
	v_mfma_f32_16x16x32_bf16 v[10:13], v[152:155], v[200:203], v[10:13]
	v_mfma_f32_16x16x32_bf16 v[54:57], v[156:159], v[172:175], v[54:57]
	v_mfma_f32_16x16x32_bf16 v[54:57], v[160:163], v[176:179], v[54:57]
	v_mfma_f32_16x16x32_bf16 v[50:53], v[164:167], v[172:175], v[50:53]
	v_mfma_f32_16x16x32_bf16 v[50:53], v[168:171], v[176:179], v[50:53]
	v_mfma_f32_16x16x32_bf16 v[38:41], v[156:159], v[180:183], v[38:41]
	v_mfma_f32_16x16x32_bf16 v[38:41], v[160:163], v[184:187], v[38:41]
	s_waitcnt lgkmcnt(0)
	v_mfma_f32_16x16x32_bf16 v[34:37], v[164:167], v[180:183], v[34:37]
	v_mfma_f32_16x16x32_bf16 v[34:37], v[168:171], v[184:187], v[34:37]
	v_mfma_f32_16x16x32_bf16 v[22:25], v[156:159], v[188:191], v[22:25]
	v_mfma_f32_16x16x32_bf16 v[22:25], v[160:163], v[192:195], v[22:25]
	v_mfma_f32_16x16x32_bf16 v[18:21], v[164:167], v[188:191], v[18:21]
	v_mfma_f32_16x16x32_bf16 v[18:21], v[168:171], v[192:195], v[18:21]
	v_mfma_f32_16x16x32_bf16 v[6:9], v[156:159], v[196:199], v[6:9]
	v_mfma_f32_16x16x32_bf16 v[6:9], v[160:163], v[200:203], v[6:9]
	v_mfma_f32_16x16x32_bf16 v[2:5], v[164:167], v[196:199], v[2:5]
	v_mfma_f32_16x16x32_bf16 v[2:5], v[168:171], v[200:203], v[2:5]
	s_setprio 0
	s_barrier
	s_add_i32 s62, s62, 2
	s_addk_i32 s61, 0x100
	s_cmp_ge_i32 s62, s3
	s_cbranch_scc0 .LBB0_1050

.LBB0_1181:
	v_add_u32_e32 v2, 0x10000, v232
	ds_read_b128 v[134:137], v2
	ds_read_b128 v[138:141], v2 offset:1024
	ds_read_b128 v[142:145], v2 offset:2048
	ds_read_b128 v[146:149], v2 offset:3072
	v_add_u32_e32 v2, 0x14000, v232
	ds_read_b128 v[150:153], v2
	ds_read_b128 v[154:157], v2 offset:1024
	ds_read_b128 v[158:161], v2 offset:2048
	ds_read_b128 v[162:165], v2 offset:3072
	s_add_i32 s50, s47, s90
	s_and_b64 s[18:19], exec, s[18:19]
	s_cselect_b32 s51, s88, s50
	s_add_i32 s50, s92, 0x80
	s_or_b32 s52, s51, 0x80
	s_add_i32 s18, s89, s93
	s_add_i32 s94, s94, 0x1bfffc80
	s_cmp_lt_u32 s91, 8
	s_cselect_b32 s18, s18, s94
	s_mov_b32 m0, s74
	s_add_i32 s19, s18, 0x80000
	ds_read_b128 v[166:169], v233
	ds_read_b128 v[170:173], v233 offset:1024
	ds_read_b128 v[174:177], v233 offset:2048
	ds_read_b128 v[178:181], v233 offset:3072
	ds_read_b128 v[182:185], v233 offset:4096
	ds_read_b128 v[186:189], v233 offset:5120
	ds_read_b128 v[190:193], v233 offset:6144
	ds_read_b128 v[194:197], v233 offset:7168
	buffer_load_dwordx4 v230, s[12:15], s19 offen lds
	s_add_i32 s18, s18, 0xc0000
	s_mov_b32 m0, s75
	s_nop 0
	buffer_load_dwordx4 v230, s[12:15], s18 offen lds
	s_waitcnt vmcnt(8)
	s_waitcnt lgkmcnt(0)
	s_setprio 1
	s_waitcnt lgkmcnt(7)
	v_mfma_f32_16x16x32_bf16 v[130:133], v[134:137], v[166:169], v[130:133]
	s_barrier
	v_mfma_f32_16x16x32_bf16 v[130:133], v[138:141], v[170:173], v[130:133]
	s_waitcnt lgkmcnt(5)
	v_mfma_f32_16x16x32_bf16 v[126:129], v[142:145], v[166:169], v[126:129]
	v_mfma_f32_16x16x32_bf16 v[126:129], v[146:149], v[170:173], v[126:129]
	s_waitcnt lgkmcnt(3)
	v_mfma_f32_16x16x32_bf16 v[114:117], v[134:137], v[174:177], v[114:117]
	v_mfma_f32_16x16x32_bf16 v[114:117], v[138:141], v[178:181], v[114:117]
	s_waitcnt lgkmcnt(1)
	v_mfma_f32_16x16x32_bf16 v[110:113], v[142:145], v[174:177], v[110:113]
	v_mfma_f32_16x16x32_bf16 v[110:113], v[146:149], v[178:181], v[110:113]
	v_mfma_f32_16x16x32_bf16 v[98:101], v[134:137], v[182:185], v[98:101]
	v_mfma_f32_16x16x32_bf16 v[98:101], v[138:141], v[186:189], v[98:101]
	v_mfma_f32_16x16x32_bf16 v[94:97], v[142:145], v[182:185], v[94:97]
	v_mfma_f32_16x16x32_bf16 v[94:97], v[146:149], v[186:189], v[94:97]
	v_mfma_f32_16x16x32_bf16 v[82:85], v[134:137], v[190:193], v[82:85]
	v_mfma_f32_16x16x32_bf16 v[82:85], v[138:141], v[194:197], v[82:85]
	v_mfma_f32_16x16x32_bf16 v[78:81], v[142:145], v[190:193], v[78:81]
	v_mfma_f32_16x16x32_bf16 v[78:81], v[146:149], v[194:197], v[78:81]
	v_mfma_f32_16x16x32_bf16 v[122:125], v[150:153], v[166:169], v[122:125]
	v_mfma_f32_16x16x32_bf16 v[122:125], v[154:157], v[170:173], v[122:125]
	v_mfma_f32_16x16x32_bf16 v[118:121], v[158:161], v[166:169], v[118:121]
	v_mfma_f32_16x16x32_bf16 v[118:121], v[162:165], v[170:173], v[118:121]
	v_mfma_f32_16x16x32_bf16 v[106:109], v[150:153], v[174:177], v[106:109]
	v_mfma_f32_16x16x32_bf16 v[106:109], v[154:157], v[178:181], v[106:109]
	s_waitcnt lgkmcnt(0)
	v_mfma_f32_16x16x32_bf16 v[102:105], v[158:161], v[174:177], v[102:105]
	v_mfma_f32_16x16x32_bf16 v[102:105], v[162:165], v[178:181], v[102:105]
	v_mfma_f32_16x16x32_bf16 v[90:93], v[150:153], v[182:185], v[90:93]
	v_mfma_f32_16x16x32_bf16 v[90:93], v[154:157], v[186:189], v[90:93]
	v_mfma_f32_16x16x32_bf16 v[86:89], v[158:161], v[182:185], v[86:89]
	v_mfma_f32_16x16x32_bf16 v[86:89], v[162:165], v[186:189], v[86:89]
	v_mfma_f32_16x16x32_bf16 v[74:77], v[150:153], v[190:193], v[74:77]
	v_mfma_f32_16x16x32_bf16 v[74:77], v[154:157], v[194:197], v[74:77]
	v_mfma_f32_16x16x32_bf16 v[70:73], v[158:161], v[190:193], v[70:73]
	v_mfma_f32_16x16x32_bf16 v[70:73], v[162:165], v[194:197], v[70:73]
	s_setprio 0
	s_barrier
	s_mov_b32 m0, s27
	s_mov_b32 s18, s14
	s_mov_b32 s19, s15
	ds_read_b128 v[166:169], v233 offset:16384
	ds_read_b128 v[170:173], v233 offset:17408
	ds_read_b128 v[174:177], v233 offset:18432
	ds_read_b128 v[178:181], v233 offset:19456
	ds_read_b128 v[182:185], v233 offset:20480
	ds_read_b128 v[186:189], v233 offset:21504
	ds_read_b128 v[190:193], v233 offset:22528
	ds_read_b128 v[194:197], v233 offset:23552
	buffer_load_dwordx4 v231, s[16:19], s51 offen lds
	s_add_i32 s53, s51, 0x18000
	s_mov_b32 m0, s30
	s_nop 0
	buffer_load_dwordx4 v231, s[16:19], s53 offen lds
	s_add_i32 s53, s51, 0x30000
	s_mov_b32 m0, s31
	s_nop 0
	buffer_load_dwordx4 v231, s[16:19], s53 offen lds
	s_add_i32 s53, s51, 0x48000
	s_mov_b32 m0, s54
	s_nop 0
	buffer_load_dwordx4 v231, s[16:19], s53 offen lds
	s_mov_b32 m0, s25
	s_add_i32 s53, s92, 0x40000
	buffer_load_dwordx4 v230, s[12:15], s92 offen lds
	s_mov_b32 m0, s55
	s_nop 0
	buffer_load_dwordx4 v230, s[12:15], s53 offen lds
	s_waitcnt vmcnt(8)
	s_waitcnt lgkmcnt(0)
	s_setprio 1
	s_waitcnt lgkmcnt(7)
	v_mfma_f32_16x16x32_bf16 v[66:69], v[134:137], v[166:169], v[66:69]
	s_barrier
	v_mfma_f32_16x16x32_bf16 v[62:65], v[142:145], v[166:169], v[62:65]
	s_waitcnt lgkmcnt(5)
	v_mfma_f32_16x16x32_bf16 v[50:53], v[134:137], v[174:177], v[50:53]
	v_mfma_f32_16x16x32_bf16 v[46:49], v[142:145], v[174:177], v[46:49]
	s_waitcnt lgkmcnt(3)
	v_mfma_f32_16x16x32_bf16 v[34:37], v[134:137], v[182:185], v[34:37]
	v_mfma_f32_16x16x32_bf16 v[30:33], v[142:145], v[182:185], v[30:33]
	s_waitcnt lgkmcnt(1)
	v_mfma_f32_16x16x32_bf16 v[18:21], v[134:137], v[190:193], v[18:21]
	v_mfma_f32_16x16x32_bf16 v[14:17], v[142:145], v[190:193], v[14:17]
	v_mfma_f32_16x16x32_bf16 v[58:61], v[150:153], v[166:169], v[58:61]
	v_mfma_f32_16x16x32_bf16 v[54:57], v[158:161], v[166:169], v[54:57]
	v_mfma_f32_16x16x32_bf16 v[42:45], v[150:153], v[174:177], v[42:45]
	v_mfma_f32_16x16x32_bf16 v[38:41], v[158:161], v[174:177], v[38:41]
	v_mfma_f32_16x16x32_bf16 v[26:29], v[150:153], v[182:185], v[26:29]
	v_mfma_f32_16x16x32_bf16 v[22:25], v[158:161], v[182:185], v[22:25]
	v_mfma_f32_16x16x32_bf16 v[10:13], v[150:153], v[190:193], v[10:13]
	v_mfma_f32_16x16x32_bf16 v[4:7], v[158:161], v[190:193], v[6:9]
	v_mfma_f32_16x16x32_bf16 v[66:69], v[138:141], v[170:173], v[66:69]
	v_mfma_f32_16x16x32_bf16 v[62:65], v[146:149], v[170:173], v[62:65]
	v_mfma_f32_16x16x32_bf16 v[50:53], v[138:141], v[178:181], v[50:53]
	v_mfma_f32_16x16x32_bf16 v[46:49], v[146:149], v[178:181], v[46:49]
	v_mfma_f32_16x16x32_bf16 v[34:37], v[138:141], v[186:189], v[34:37]
	v_mfma_f32_16x16x32_bf16 v[30:33], v[146:149], v[186:189], v[30:33]
	s_waitcnt lgkmcnt(0)
	v_mfma_f32_16x16x32_bf16 v[18:21], v[138:141], v[194:197], v[18:21]
	v_mfma_f32_16x16x32_bf16 v[14:17], v[146:149], v[194:197], v[14:17]
	v_mfma_f32_16x16x32_bf16 v[58:61], v[154:157], v[170:173], v[58:61]
	v_mfma_f32_16x16x32_bf16 v[54:57], v[162:165], v[170:173], v[54:57]
	v_mfma_f32_16x16x32_bf16 v[42:45], v[154:157], v[178:181], v[42:45]
	v_mfma_f32_16x16x32_bf16 v[38:41], v[162:165], v[178:181], v[38:41]
	v_mfma_f32_16x16x32_bf16 v[26:29], v[154:157], v[186:189], v[26:29]
	v_mfma_f32_16x16x32_bf16 v[22:25], v[162:165], v[186:189], v[22:25]
	v_mfma_f32_16x16x32_bf16 v[10:13], v[154:157], v[194:197], v[10:13]
	v_mfma_f32_16x16x32_bf16 v[4:7], v[162:165], v[194:197], v[4:7]
	s_setprio 0
	s_barrier
	v_add_u32_e32 v2, 0x18000, v232
	ds_read_b128 v[134:137], v2
	ds_read_b128 v[138:141], v2 offset:1024
	ds_read_b128 v[142:145], v2 offset:2048
	ds_read_b128 v[146:149], v2 offset:3072
	v_add_u32_e32 v2, 0x1c000, v232
	ds_read_b128 v[150:153], v2
	ds_read_b128 v[154:157], v2 offset:1024
	ds_read_b128 v[158:161], v2 offset:2048
	ds_read_b128 v[162:165], v2 offset:3072
	s_mov_b32 m0, s56
	s_add_i32 s53, s92, 0x80000
	ds_read_b128 v[166:169], v233 offset:32768
	ds_read_b128 v[170:173], v233 offset:33792
	ds_read_b128 v[174:177], v233 offset:34816
	ds_read_b128 v[178:181], v233 offset:35840
	ds_read_b128 v[182:185], v233 offset:36864
	ds_read_b128 v[186:189], v233 offset:37888
	ds_read_b128 v[190:193], v233 offset:38912
	ds_read_b128 v[194:197], v233 offset:39936
	buffer_load_dwordx4 v230, s[12:15], s53 offen lds
	s_add_i32 s53, s92, 0xc0000
	s_mov_b32 m0, s57
	s_nop 0
	buffer_load_dwordx4 v230, s[12:15], s53 offen lds
	s_waitcnt vmcnt(8)
	s_waitcnt lgkmcnt(0)
	s_setprio 1
	s_waitcnt lgkmcnt(7)
	v_mfma_f32_16x16x32_bf16 v[130:133], v[134:137], v[166:169], v[130:133]
	s_barrier
	v_mfma_f32_16x16x32_bf16 v[130:133], v[138:141], v[170:173], v[130:133]
	s_waitcnt lgkmcnt(5)
	v_mfma_f32_16x16x32_bf16 v[126:129], v[142:145], v[166:169], v[126:129]
	v_mfma_f32_16x16x32_bf16 v[126:129], v[146:149], v[170:173], v[126:129]
	s_waitcnt lgkmcnt(3)
	v_mfma_f32_16x16x32_bf16 v[114:117], v[134:137], v[174:177], v[114:117]
	v_mfma_f32_16x16x32_bf16 v[114:117], v[138:141], v[178:181], v[114:117]
	s_waitcnt lgkmcnt(1)
	v_mfma_f32_16x16x32_bf16 v[110:113], v[142:145], v[174:177], v[110:113]
	v_mfma_f32_16x16x32_bf16 v[110:113], v[146:149], v[178:181], v[110:113]
	v_mfma_f32_16x16x32_bf16 v[98:101], v[134:137], v[182:185], v[98:101]
	v_mfma_f32_16x16x32_bf16 v[98:101], v[138:141], v[186:189], v[98:101]
	v_mfma_f32_16x16x32_bf16 v[94:97], v[142:145], v[182:185], v[94:97]
	v_mfma_f32_16x16x32_bf16 v[94:97], v[146:149], v[186:189], v[94:97]
	v_mfma_f32_16x16x32_bf16 v[82:85], v[134:137], v[190:193], v[82:85]
	v_mfma_f32_16x16x32_bf16 v[82:85], v[138:141], v[194:197], v[82:85]
	v_mfma_f32_16x16x32_bf16 v[78:81], v[142:145], v[190:193], v[78:81]
	v_mfma_f32_16x16x32_bf16 v[78:81], v[146:149], v[194:197], v[78:81]
	v_mfma_f32_16x16x32_bf16 v[122:125], v[150:153], v[166:169], v[122:125]
	v_mfma_f32_16x16x32_bf16 v[122:125], v[154:157], v[170:173], v[122:125]
	v_mfma_f32_16x16x32_bf16 v[118:121], v[158:161], v[166:169], v[118:121]
	v_mfma_f32_16x16x32_bf16 v[118:121], v[162:165], v[170:173], v[118:121]
	v_mfma_f32_16x16x32_bf16 v[106:109], v[150:153], v[174:177], v[106:109]
	v_mfma_f32_16x16x32_bf16 v[106:109], v[154:157], v[178:181], v[106:109]
	s_waitcnt lgkmcnt(0)
	v_mfma_f32_16x16x32_bf16 v[102:105], v[158:161], v[174:177], v[102:105]
	v_mfma_f32_16x16x32_bf16 v[102:105], v[162:165], v[178:181], v[102:105]
	v_mfma_f32_16x16x32_bf16 v[90:93], v[150:153], v[182:185], v[90:93]
	v_mfma_f32_16x16x32_bf16 v[90:93], v[154:157], v[186:189], v[90:93]
	v_mfma_f32_16x16x32_bf16 v[86:89], v[158:161], v[182:185], v[86:89]
	v_mfma_f32_16x16x32_bf16 v[86:89], v[162:165], v[186:189], v[86:89]
	v_mfma_f32_16x16x32_bf16 v[74:77], v[150:153], v[190:193], v[74:77]
	v_mfma_f32_16x16x32_bf16 v[74:77], v[154:157], v[194:197], v[74:77]
	v_mfma_f32_16x16x32_bf16 v[70:73], v[158:161], v[190:193], v[70:73]
	v_mfma_f32_16x16x32_bf16 v[70:73], v[162:165], v[194:197], v[70:73]
	s_setprio 0
	s_barrier
	s_mov_b32 m0, s64
	ds_read_b128 v[166:169], v233 offset:49152
	ds_read_b128 v[170:173], v233 offset:50176
	ds_read_b128 v[174:177], v233 offset:51200
	ds_read_b128 v[178:181], v233 offset:52224
	ds_read_b128 v[182:185], v233 offset:53248
	ds_read_b128 v[186:189], v233 offset:54272
	ds_read_b128 v[190:193], v233 offset:55296
	ds_read_b128 v[194:197], v233 offset:56320
	buffer_load_dwordx4 v231, s[16:19], s52 offen lds
	s_add_i32 s52, s51, 0x18080
	s_mov_b32 m0, s65
	s_nop 0
	buffer_load_dwordx4 v231, s[16:19], s52 offen lds
	s_add_i32 s52, s51, 0x30080
	s_mov_b32 m0, s68
	s_add_i32 s51, s51, 0x48080
	buffer_load_dwordx4 v231, s[16:19], s52 offen lds
	s_mov_b32 m0, s69
	s_nop 0
	buffer_load_dwordx4 v231, s[16:19], s51 offen lds
	s_mov_b32 m0, s66
	s_add_i32 s18, s92, 0x40080
	buffer_load_dwordx4 v230, s[12:15], s50 offen lds
	s_mov_b32 m0, s67
	s_nop 0
	buffer_load_dwordx4 v230, s[12:15], s18 offen lds
	s_waitcnt vmcnt(8)
	s_waitcnt lgkmcnt(0)
	s_setprio 1
	s_waitcnt lgkmcnt(7)
	v_mfma_f32_16x16x32_bf16 v[66:69], v[134:137], v[166:169], v[66:69]
	s_barrier
	v_mfma_f32_16x16x32_bf16 v[62:65], v[142:145], v[166:169], v[62:65]
	s_waitcnt lgkmcnt(5)
	v_mfma_f32_16x16x32_bf16 v[50:53], v[134:137], v[174:177], v[50:53]
	v_mfma_f32_16x16x32_bf16 v[46:49], v[142:145], v[174:177], v[46:49]
	s_waitcnt lgkmcnt(3)
	v_mfma_f32_16x16x32_bf16 v[34:37], v[134:137], v[182:185], v[34:37]
	v_mfma_f32_16x16x32_bf16 v[30:33], v[142:145], v[182:185], v[30:33]
	s_waitcnt lgkmcnt(1)
	v_mfma_f32_16x16x32_bf16 v[18:21], v[134:137], v[190:193], v[18:21]
	v_mfma_f32_16x16x32_bf16 v[14:17], v[142:145], v[190:193], v[14:17]
	v_mfma_f32_16x16x32_bf16 v[58:61], v[150:153], v[166:169], v[58:61]
	v_mfma_f32_16x16x32_bf16 v[54:57], v[158:161], v[166:169], v[54:57]
	v_mfma_f32_16x16x32_bf16 v[42:45], v[150:153], v[174:177], v[42:45]
	v_mfma_f32_16x16x32_bf16 v[38:41], v[158:161], v[174:177], v[38:41]
	v_mfma_f32_16x16x32_bf16 v[26:29], v[150:153], v[182:185], v[26:29]
	v_mfma_f32_16x16x32_bf16 v[22:25], v[158:161], v[182:185], v[22:25]
	v_mfma_f32_16x16x32_bf16 v[8:11], v[150:153], v[190:193], v[10:13]
	v_mfma_f32_16x16x32_bf16 v[4:7], v[158:161], v[190:193], v[4:7]
	v_mfma_f32_16x16x32_bf16 v[66:69], v[138:141], v[170:173], v[66:69]
	v_mfma_f32_16x16x32_bf16 v[62:65], v[146:149], v[170:173], v[62:65]
	v_mfma_f32_16x16x32_bf16 v[50:53], v[138:141], v[178:181], v[50:53]
	v_mfma_f32_16x16x32_bf16 v[46:49], v[146:149], v[178:181], v[46:49]
	v_mfma_f32_16x16x32_bf16 v[34:37], v[138:141], v[186:189], v[34:37]
	v_mfma_f32_16x16x32_bf16 v[30:33], v[146:149], v[186:189], v[30:33]
	s_waitcnt lgkmcnt(0)
	v_mfma_f32_16x16x32_bf16 v[18:21], v[138:141], v[194:197], v[18:21]
	v_mfma_f32_16x16x32_bf16 v[14:17], v[146:149], v[194:197], v[14:17]
	v_mfma_f32_16x16x32_bf16 v[58:61], v[154:157], v[170:173], v[58:61]
	v_mfma_f32_16x16x32_bf16 v[54:57], v[162:165], v[170:173], v[54:57]
	v_mfma_f32_16x16x32_bf16 v[42:45], v[154:157], v[178:181], v[42:45]
	v_mfma_f32_16x16x32_bf16 v[38:41], v[162:165], v[178:181], v[38:41]
	v_mfma_f32_16x16x32_bf16 v[26:29], v[154:157], v[186:189], v[26:29]
	v_mfma_f32_16x16x32_bf16 v[22:25], v[162:165], v[186:189], v[22:25]
	v_mfma_f32_16x16x32_bf16 v[10:13], v[154:157], v[194:197], v[8:11]
	v_mfma_f32_16x16x32_bf16 v[6:9], v[162:165], v[194:197], v[4:7]
	s_setprio 0
	s_barrier
	s_add_i32 s91, s91, 2
	s_addk_i32 s90, 0x100
	s_cmp_ge_i32 s91, s3
	s_cbranch_scc1 .LBB0_1193

.LBB0_1290:
	ds_read_b128 v[106:109], v224
	ds_read_b128 v[118:121], v224 offset:1024
	ds_read_b128 v[130:133], v224 offset:2048
	ds_read_b128 v[138:141], v224 offset:3072
	ds_read_b128 v[146:149], v225
	ds_read_b128 v[150:153], v225 offset:1024
	ds_read_b128 v[154:157], v225 offset:2048
	ds_read_b128 v[158:161], v225 offset:3072
	s_add_i32 s18, s72, 0xffe80080
	s_cmp_eq_u32 s56, s74
	s_cselect_b32 s75, s6, s18
	s_cselect_b32 s77, s7, s73
	s_or_b32 s76, s75, 0x80
	s_add_i32 s18, s72, 0xfff80000
	s_mov_b32 m0, s57
	ds_read_b128 v[162:165], v226
	ds_read_b128 v[166:169], v226 offset:1024
	ds_read_b128 v[170:173], v226 offset:2048
	ds_read_b128 v[174:177], v226 offset:3072
	ds_read_b128 v[178:181], v226 offset:4096
	ds_read_b128 v[182:185], v226 offset:5120
	ds_read_b128 v[190:193], v226 offset:6144
	ds_read_b128 v[194:197], v226 offset:7168
	buffer_load_dwordx4 v222, s[12:15], s18 offen lds
	s_mov_b32 m0, s60
	s_nop 0
	buffer_load_dwordx4 v222, s[12:15], s72 offen lds
	s_waitcnt vmcnt(8)
	s_waitcnt lgkmcnt(0)
	s_setprio 1
	s_waitcnt lgkmcnt(7)
	v_mfma_f32_16x16x32_bf16 v[142:145], v[106:109], v[162:165], v[142:145]
	s_barrier
	v_mfma_f32_16x16x32_bf16 v[142:145], v[118:121], v[166:169], v[142:145]
	s_waitcnt lgkmcnt(5)
	v_mfma_f32_16x16x32_bf16 v[134:137], v[130:133], v[162:165], v[134:137]
	v_mfma_f32_16x16x32_bf16 v[134:137], v[138:141], v[166:169], v[134:137]
	s_waitcnt lgkmcnt(3)
	v_mfma_f32_16x16x32_bf16 v[114:117], v[106:109], v[170:173], v[114:117]
	v_mfma_f32_16x16x32_bf16 v[114:117], v[118:121], v[174:177], v[114:117]
	s_waitcnt lgkmcnt(1)
	v_mfma_f32_16x16x32_bf16 v[110:113], v[130:133], v[170:173], v[110:113]
	v_mfma_f32_16x16x32_bf16 v[110:113], v[138:141], v[174:177], v[110:113]
	v_mfma_f32_16x16x32_bf16 v[94:97], v[106:109], v[178:181], v[94:97]
	v_mfma_f32_16x16x32_bf16 v[94:97], v[118:121], v[182:185], v[94:97]
	v_mfma_f32_16x16x32_bf16 v[90:93], v[130:133], v[178:181], v[90:93]
	v_mfma_f32_16x16x32_bf16 v[90:93], v[138:141], v[182:185], v[90:93]
	v_mfma_f32_16x16x32_bf16 v[78:81], v[106:109], v[190:193], v[78:81]
	v_mfma_f32_16x16x32_bf16 v[78:81], v[118:121], v[194:197], v[78:81]
	v_mfma_f32_16x16x32_bf16 v[74:77], v[130:133], v[190:193], v[74:77]
	v_mfma_f32_16x16x32_bf16 v[74:77], v[138:141], v[194:197], v[74:77]
	v_mfma_f32_16x16x32_bf16 v[126:129], v[146:149], v[162:165], v[126:129]
	v_mfma_f32_16x16x32_bf16 v[126:129], v[150:153], v[166:169], v[126:129]
	v_mfma_f32_16x16x32_bf16 v[122:125], v[154:157], v[162:165], v[122:125]
	v_mfma_f32_16x16x32_bf16 v[122:125], v[158:161], v[166:169], v[122:125]
	v_mfma_f32_16x16x32_bf16 v[102:105], v[146:149], v[170:173], v[102:105]
	v_mfma_f32_16x16x32_bf16 v[102:105], v[150:153], v[174:177], v[102:105]
	s_waitcnt lgkmcnt(0)
	v_mfma_f32_16x16x32_bf16 v[98:101], v[154:157], v[170:173], v[98:101]
	v_mfma_f32_16x16x32_bf16 v[98:101], v[158:161], v[174:177], v[98:101]
	v_mfma_f32_16x16x32_bf16 v[86:89], v[146:149], v[178:181], v[86:89]
	v_mfma_f32_16x16x32_bf16 v[86:89], v[150:153], v[182:185], v[86:89]
	v_mfma_f32_16x16x32_bf16 v[82:85], v[154:157], v[178:181], v[82:85]
	v_mfma_f32_16x16x32_bf16 v[82:85], v[158:161], v[182:185], v[82:85]
	v_mfma_f32_16x16x32_bf16 v[70:73], v[146:149], v[190:193], v[70:73]
	v_mfma_f32_16x16x32_bf16 v[70:73], v[150:153], v[194:197], v[70:73]
	v_mfma_f32_16x16x32_bf16 v[66:69], v[154:157], v[190:193], v[66:69]
	v_mfma_f32_16x16x32_bf16 v[66:69], v[158:161], v[194:197], v[66:69]
	s_setprio 0
	s_barrier
	s_mov_b32 m0, s27
	s_mov_b32 s18, s14
	s_mov_b32 s19, s15
	ds_read_b128 v[162:165], v226 offset:16384
	ds_read_b128 v[166:169], v226 offset:17408
	ds_read_b128 v[170:173], v226 offset:18432
	ds_read_b128 v[174:177], v226 offset:19456
	ds_read_b128 v[178:181], v226 offset:20480
	ds_read_b128 v[182:185], v226 offset:21504
	ds_read_b128 v[190:193], v226 offset:22528
	ds_read_b128 v[194:197], v226 offset:23552
	buffer_load_dwordx4 v223, s[16:19], s77 offen lds
	s_add_i32 s78, s77, 0x80000
	s_mov_b32 m0, s30
	s_nop 0
	buffer_load_dwordx4 v223, s[16:19], s78 offen lds
	s_add_i32 s78, s77, 0x100000
	s_mov_b32 m0, s31
	s_nop 0
	buffer_load_dwordx4 v223, s[16:19], s78 offen lds
	s_add_i32 s78, s77, 0x180000
	s_mov_b32 m0, s41
	s_nop 0
	buffer_load_dwordx4 v223, s[16:19], s78 offen lds
	s_mov_b32 m0, s25
	s_add_i32 s78, s75, 0x80000
	buffer_load_dwordx4 v222, s[12:15], s75 offen lds
	s_mov_b32 m0, s42
	s_nop 0
	buffer_load_dwordx4 v222, s[12:15], s78 offen lds
	s_waitcnt vmcnt(8)
	s_waitcnt lgkmcnt(0)
	s_setprio 1
	s_waitcnt lgkmcnt(7)
	v_mfma_f32_16x16x32_bf16 v[62:65], v[106:109], v[162:165], v[62:65]
	s_barrier
	v_mfma_f32_16x16x32_bf16 v[62:65], v[118:121], v[166:169], v[62:65]
	s_waitcnt lgkmcnt(5)
	v_mfma_f32_16x16x32_bf16 v[58:61], v[130:133], v[162:165], v[58:61]
	v_mfma_f32_16x16x32_bf16 v[58:61], v[138:141], v[166:169], v[58:61]
	s_waitcnt lgkmcnt(3)
	v_mfma_f32_16x16x32_bf16 v[46:49], v[106:109], v[170:173], v[46:49]
	v_mfma_f32_16x16x32_bf16 v[46:49], v[118:121], v[174:177], v[46:49]
	s_waitcnt lgkmcnt(1)
	v_mfma_f32_16x16x32_bf16 v[42:45], v[130:133], v[170:173], v[42:45]
	v_mfma_f32_16x16x32_bf16 v[42:45], v[138:141], v[174:177], v[42:45]
	v_mfma_f32_16x16x32_bf16 v[30:33], v[106:109], v[178:181], v[30:33]
	v_mfma_f32_16x16x32_bf16 v[30:33], v[118:121], v[182:185], v[30:33]
	v_mfma_f32_16x16x32_bf16 v[26:29], v[130:133], v[178:181], v[26:29]
	v_mfma_f32_16x16x32_bf16 v[26:29], v[138:141], v[182:185], v[26:29]
	v_mfma_f32_16x16x32_bf16 v[14:17], v[106:109], v[190:193], v[14:17]
	v_mfma_f32_16x16x32_bf16 v[14:17], v[118:121], v[194:197], v[14:17]
	v_mfma_f32_16x16x32_bf16 v[10:13], v[130:133], v[190:193], v[10:13]
	v_mfma_f32_16x16x32_bf16 v[10:13], v[138:141], v[194:197], v[10:13]
	v_mfma_f32_16x16x32_bf16 v[54:57], v[146:149], v[162:165], v[54:57]
	v_mfma_f32_16x16x32_bf16 v[54:57], v[150:153], v[166:169], v[54:57]
	v_mfma_f32_16x16x32_bf16 v[50:53], v[154:157], v[162:165], v[50:53]
	v_mfma_f32_16x16x32_bf16 v[50:53], v[158:161], v[166:169], v[50:53]
	v_mfma_f32_16x16x32_bf16 v[38:41], v[146:149], v[170:173], v[38:41]
	v_mfma_f32_16x16x32_bf16 v[38:41], v[150:153], v[174:177], v[38:41]
	s_waitcnt lgkmcnt(0)
	v_mfma_f32_16x16x32_bf16 v[34:37], v[154:157], v[170:173], v[34:37]
	v_mfma_f32_16x16x32_bf16 v[34:37], v[158:161], v[174:177], v[34:37]
	v_mfma_f32_16x16x32_bf16 v[22:25], v[146:149], v[178:181], v[22:25]
	v_mfma_f32_16x16x32_bf16 v[22:25], v[150:153], v[182:185], v[22:25]
	v_mfma_f32_16x16x32_bf16 v[18:21], v[154:157], v[178:181], v[18:21]
	v_mfma_f32_16x16x32_bf16 v[18:21], v[158:161], v[182:185], v[18:21]
	v_mfma_f32_16x16x32_bf16 v[6:9], v[146:149], v[190:193], v[6:9]
	v_mfma_f32_16x16x32_bf16 v[6:9], v[150:153], v[194:197], v[6:9]
	v_mfma_f32_16x16x32_bf16 v[2:5], v[154:157], v[190:193], v[2:5]
	v_mfma_f32_16x16x32_bf16 v[2:5], v[158:161], v[194:197], v[2:5]
	s_setprio 0
	s_barrier
	ds_read_b128 v[106:109], v227
	ds_read_b128 v[118:121], v227 offset:1024
	ds_read_b128 v[130:133], v227 offset:2048
	ds_read_b128 v[138:141], v227 offset:3072
	ds_read_b128 v[146:149], v228
	ds_read_b128 v[150:153], v228 offset:1024
	ds_read_b128 v[154:157], v228 offset:2048
	ds_read_b128 v[158:161], v228 offset:3072
	s_mov_b32 m0, s43
	s_add_i32 s78, s75, 0x100000
	ds_read_b128 v[162:165], v226 offset:32768
	ds_read_b128 v[166:169], v226 offset:33792
	ds_read_b128 v[170:173], v226 offset:34816
	ds_read_b128 v[174:177], v226 offset:35840
	ds_read_b128 v[178:181], v226 offset:36864
	ds_read_b128 v[182:185], v226 offset:37888
	ds_read_b128 v[190:193], v226 offset:38912
	ds_read_b128 v[194:197], v226 offset:39936
	buffer_load_dwordx4 v222, s[12:15], s78 offen lds
	s_add_i32 s78, s75, 0x180000
	s_mov_b32 m0, s44
	s_nop 0
	buffer_load_dwordx4 v222, s[12:15], s78 offen lds
	s_waitcnt vmcnt(8)
	s_waitcnt lgkmcnt(0)
	s_setprio 1
	s_waitcnt lgkmcnt(7)
	v_mfma_f32_16x16x32_bf16 v[142:145], v[106:109], v[162:165], v[142:145]
	s_barrier
	v_mfma_f32_16x16x32_bf16 v[142:145], v[118:121], v[166:169], v[142:145]
	s_waitcnt lgkmcnt(5)
	v_mfma_f32_16x16x32_bf16 v[134:137], v[130:133], v[162:165], v[134:137]
	v_mfma_f32_16x16x32_bf16 v[134:137], v[138:141], v[166:169], v[134:137]
	s_waitcnt lgkmcnt(3)
	v_mfma_f32_16x16x32_bf16 v[114:117], v[106:109], v[170:173], v[114:117]
	v_mfma_f32_16x16x32_bf16 v[114:117], v[118:121], v[174:177], v[114:117]
	s_waitcnt lgkmcnt(1)
	v_mfma_f32_16x16x32_bf16 v[110:113], v[130:133], v[170:173], v[110:113]
	v_mfma_f32_16x16x32_bf16 v[110:113], v[138:141], v[174:177], v[110:113]
	v_mfma_f32_16x16x32_bf16 v[94:97], v[106:109], v[178:181], v[94:97]
	v_mfma_f32_16x16x32_bf16 v[94:97], v[118:121], v[182:185], v[94:97]
	v_mfma_f32_16x16x32_bf16 v[90:93], v[130:133], v[178:181], v[90:93]
	v_mfma_f32_16x16x32_bf16 v[90:93], v[138:141], v[182:185], v[90:93]
	v_mfma_f32_16x16x32_bf16 v[78:81], v[106:109], v[190:193], v[78:81]
	v_mfma_f32_16x16x32_bf16 v[78:81], v[118:121], v[194:197], v[78:81]
	v_mfma_f32_16x16x32_bf16 v[74:77], v[130:133], v[190:193], v[74:77]
	v_mfma_f32_16x16x32_bf16 v[74:77], v[138:141], v[194:197], v[74:77]
	v_mfma_f32_16x16x32_bf16 v[126:129], v[146:149], v[162:165], v[126:129]
	v_mfma_f32_16x16x32_bf16 v[126:129], v[150:153], v[166:169], v[126:129]
	v_mfma_f32_16x16x32_bf16 v[122:125], v[154:157], v[162:165], v[122:125]
	v_mfma_f32_16x16x32_bf16 v[122:125], v[158:161], v[166:169], v[122:125]
	v_mfma_f32_16x16x32_bf16 v[102:105], v[146:149], v[170:173], v[102:105]
	v_mfma_f32_16x16x32_bf16 v[102:105], v[150:153], v[174:177], v[102:105]
	s_waitcnt lgkmcnt(0)
	v_mfma_f32_16x16x32_bf16 v[98:101], v[154:157], v[170:173], v[98:101]
	v_mfma_f32_16x16x32_bf16 v[98:101], v[158:161], v[174:177], v[98:101]
	v_mfma_f32_16x16x32_bf16 v[86:89], v[146:149], v[178:181], v[86:89]
	v_mfma_f32_16x16x32_bf16 v[86:89], v[150:153], v[182:185], v[86:89]
	v_mfma_f32_16x16x32_bf16 v[82:85], v[154:157], v[178:181], v[82:85]
	v_mfma_f32_16x16x32_bf16 v[82:85], v[158:161], v[182:185], v[82:85]
	v_mfma_f32_16x16x32_bf16 v[70:73], v[146:149], v[190:193], v[70:73]
	v_mfma_f32_16x16x32_bf16 v[70:73], v[150:153], v[194:197], v[70:73]
	v_mfma_f32_16x16x32_bf16 v[66:69], v[154:157], v[190:193], v[66:69]
	v_mfma_f32_16x16x32_bf16 v[66:69], v[158:161], v[194:197], v[66:69]
	s_setprio 0
	s_barrier
	s_mov_b32 m0, s48
	s_or_b32 s78, s77, 0x80
	ds_read_b128 v[162:165], v226 offset:49152
	ds_read_b128 v[166:169], v226 offset:50176
	ds_read_b128 v[170:173], v226 offset:51200
	ds_read_b128 v[174:177], v226 offset:52224
	ds_read_b128 v[178:181], v226 offset:53248
	ds_read_b128 v[182:185], v226 offset:54272
	ds_read_b128 v[190:193], v226 offset:55296
	ds_read_b128 v[194:197], v226 offset:56320
	buffer_load_dwordx4 v223, s[16:19], s78 offen lds
	s_add_i32 s78, s77, 0x80080
	s_mov_b32 m0, s49
	s_add_i32 s75, s75, 0x80080
	buffer_load_dwordx4 v223, s[16:19], s78 offen lds
	s_add_i32 s78, s77, 0x100080
	s_mov_b32 m0, s52
	s_add_i32 s77, s77, 0x180080
	buffer_load_dwordx4 v223, s[16:19], s78 offen lds
	s_mov_b32 m0, s53
	s_nop 0
	buffer_load_dwordx4 v223, s[16:19], s77 offen lds
	s_mov_b32 m0, s50
	s_nop 0
	buffer_load_dwordx4 v222, s[12:15], s76 offen lds
	s_mov_b32 m0, s51
	s_nop 0
	buffer_load_dwordx4 v222, s[12:15], s75 offen lds
	s_waitcnt vmcnt(8)
	s_waitcnt lgkmcnt(0)
	s_setprio 1
	s_waitcnt lgkmcnt(7)
	v_mfma_f32_16x16x32_bf16 v[62:65], v[106:109], v[162:165], v[62:65]
	s_barrier
	v_mfma_f32_16x16x32_bf16 v[62:65], v[118:121], v[166:169], v[62:65]
	s_waitcnt lgkmcnt(5)
	v_mfma_f32_16x16x32_bf16 v[58:61], v[130:133], v[162:165], v[58:61]
	v_mfma_f32_16x16x32_bf16 v[58:61], v[138:141], v[166:169], v[58:61]
	s_waitcnt lgkmcnt(3)
	v_mfma_f32_16x16x32_bf16 v[46:49], v[106:109], v[170:173], v[46:49]
	v_mfma_f32_16x16x32_bf16 v[46:49], v[118:121], v[174:177], v[46:49]
	s_waitcnt lgkmcnt(1)
	v_mfma_f32_16x16x32_bf16 v[42:45], v[130:133], v[170:173], v[42:45]
	v_mfma_f32_16x16x32_bf16 v[42:45], v[138:141], v[174:177], v[42:45]
	v_mfma_f32_16x16x32_bf16 v[30:33], v[106:109], v[178:181], v[30:33]
	v_mfma_f32_16x16x32_bf16 v[30:33], v[118:121], v[182:185], v[30:33]
	v_mfma_f32_16x16x32_bf16 v[26:29], v[130:133], v[178:181], v[26:29]
	v_mfma_f32_16x16x32_bf16 v[26:29], v[138:141], v[182:185], v[26:29]
	v_mfma_f32_16x16x32_bf16 v[14:17], v[106:109], v[190:193], v[14:17]
	v_mfma_f32_16x16x32_bf16 v[14:17], v[118:121], v[194:197], v[14:17]
	v_mfma_f32_16x16x32_bf16 v[10:13], v[130:133], v[190:193], v[10:13]
	v_mfma_f32_16x16x32_bf16 v[10:13], v[138:141], v[194:197], v[10:13]
	v_mfma_f32_16x16x32_bf16 v[54:57], v[146:149], v[162:165], v[54:57]
	v_mfma_f32_16x16x32_bf16 v[54:57], v[150:153], v[166:169], v[54:57]
	v_mfma_f32_16x16x32_bf16 v[50:53], v[154:157], v[162:165], v[50:53]
	v_mfma_f32_16x16x32_bf16 v[50:53], v[158:161], v[166:169], v[50:53]
	v_mfma_f32_16x16x32_bf16 v[38:41], v[146:149], v[170:173], v[38:41]
	v_mfma_f32_16x16x32_bf16 v[38:41], v[150:153], v[174:177], v[38:41]
	s_waitcnt lgkmcnt(0)
	v_mfma_f32_16x16x32_bf16 v[34:37], v[154:157], v[170:173], v[34:37]
	v_mfma_f32_16x16x32_bf16 v[34:37], v[158:161], v[174:177], v[34:37]
	v_mfma_f32_16x16x32_bf16 v[22:25], v[146:149], v[178:181], v[22:25]
	v_mfma_f32_16x16x32_bf16 v[22:25], v[150:153], v[182:185], v[22:25]
	v_mfma_f32_16x16x32_bf16 v[18:21], v[154:157], v[178:181], v[18:21]
	v_mfma_f32_16x16x32_bf16 v[18:21], v[158:161], v[182:185], v[18:21]
	v_mfma_f32_16x16x32_bf16 v[6:9], v[146:149], v[190:193], v[6:9]
	v_mfma_f32_16x16x32_bf16 v[6:9], v[150:153], v[194:197], v[6:9]
	v_mfma_f32_16x16x32_bf16 v[2:5], v[154:157], v[190:193], v[2:5]
	v_mfma_f32_16x16x32_bf16 v[2:5], v[158:161], v[194:197], v[2:5]
	s_setprio 0
	s_barrier
	s_add_i32 s74, s74, 2
	s_addk_i32 s72, 0x100
	s_addk_i32 s73, 0x100
	s_cmp_ge_i32 s74, s3
	s_cbranch_scc0 .LBB0_1290
	s_and_b64 vcc, exec, s[38:39]
	s_cbranch_vccz .LBB0_1293

.LBB0_1382:
	ds_read_b128 v[144:147], v138
	ds_read_b128 v[148:151], v138 offset:1024
	ds_read_b128 v[152:155], v138 offset:2048
	ds_read_b128 v[156:159], v138 offset:3072
	ds_read_b128 v[160:163], v139
	ds_read_b128 v[164:167], v139 offset:1024
	ds_read_b128 v[168:171], v139 offset:2048
	ds_read_b128 v[172:175], v139 offset:3072
	s_add_i32 s14, s74, 0xffe80080
	s_cmp_eq_u32 s61, s76
	s_cselect_b32 s77, s72, s14
	s_cselect_b32 s79, s73, s75
	s_or_b32 s78, s77, 0x80
	s_add_i32 s14, s74, 0xfff80000
	s_mov_b32 m0, s62
	ds_read_b128 v[176:179], v140
	ds_read_b128 v[180:183], v140 offset:1024
	ds_read_b128 v[184:187], v140 offset:2048
	ds_read_b128 v[188:191], v140 offset:3072
	ds_read_b128 v[192:195], v140 offset:4096
	ds_read_b128 v[196:199], v140 offset:5120
	ds_read_b128 v[200:203], v140 offset:6144
	ds_read_b128 v[204:207], v140 offset:7168
	buffer_load_dwordx4 v136, s[16:19], s14 offen lds
	s_mov_b32 m0, s63
	s_nop 0
	buffer_load_dwordx4 v136, s[16:19], s74 offen lds
	s_waitcnt vmcnt(8)
	s_waitcnt lgkmcnt(0)
	s_setprio 1
	s_waitcnt lgkmcnt(7)
	v_mfma_f32_16x16x32_bf16 v[118:121], v[144:147], v[176:179], v[118:121]
	s_barrier
	v_mfma_f32_16x16x32_bf16 v[118:121], v[148:151], v[180:183], v[118:121]
	s_waitcnt lgkmcnt(5)
	v_mfma_f32_16x16x32_bf16 v[114:117], v[152:155], v[176:179], v[114:117]
	v_mfma_f32_16x16x32_bf16 v[114:117], v[156:159], v[180:183], v[114:117]
	s_waitcnt lgkmcnt(3)
	v_mfma_f32_16x16x32_bf16 v[110:113], v[144:147], v[184:187], v[110:113]
	v_mfma_f32_16x16x32_bf16 v[110:113], v[148:151], v[188:191], v[110:113]
	s_waitcnt lgkmcnt(1)
	v_mfma_f32_16x16x32_bf16 v[102:105], v[152:155], v[184:187], v[102:105]
	v_mfma_f32_16x16x32_bf16 v[102:105], v[156:159], v[188:191], v[102:105]
	v_mfma_f32_16x16x32_bf16 v[94:97], v[144:147], v[192:195], v[94:97]
	v_mfma_f32_16x16x32_bf16 v[94:97], v[148:151], v[196:199], v[94:97]
	v_mfma_f32_16x16x32_bf16 v[86:89], v[152:155], v[192:195], v[86:89]
	v_mfma_f32_16x16x32_bf16 v[86:89], v[156:159], v[196:199], v[86:89]
	v_mfma_f32_16x16x32_bf16 v[78:81], v[144:147], v[200:203], v[78:81]
	v_mfma_f32_16x16x32_bf16 v[78:81], v[148:151], v[204:207], v[78:81]
	v_mfma_f32_16x16x32_bf16 v[66:69], v[152:155], v[200:203], v[66:69]
	v_mfma_f32_16x16x32_bf16 v[66:69], v[156:159], v[204:207], v[66:69]
	v_mfma_f32_16x16x32_bf16 v[126:129], v[160:163], v[176:179], v[126:129]
	v_mfma_f32_16x16x32_bf16 v[126:129], v[164:167], v[180:183], v[126:129]
	v_mfma_f32_16x16x32_bf16 v[122:125], v[168:171], v[176:179], v[122:125]
	v_mfma_f32_16x16x32_bf16 v[122:125], v[172:175], v[180:183], v[122:125]
	v_mfma_f32_16x16x32_bf16 v[106:109], v[160:163], v[184:187], v[106:109]
	v_mfma_f32_16x16x32_bf16 v[106:109], v[164:167], v[188:191], v[106:109]
	s_waitcnt lgkmcnt(0)
	v_mfma_f32_16x16x32_bf16 v[98:101], v[168:171], v[184:187], v[98:101]
	v_mfma_f32_16x16x32_bf16 v[98:101], v[172:175], v[188:191], v[98:101]
	v_mfma_f32_16x16x32_bf16 v[90:93], v[160:163], v[192:195], v[90:93]
	v_mfma_f32_16x16x32_bf16 v[90:93], v[164:167], v[196:199], v[90:93]
	v_mfma_f32_16x16x32_bf16 v[82:85], v[168:171], v[192:195], v[82:85]
	v_mfma_f32_16x16x32_bf16 v[82:85], v[172:175], v[196:199], v[82:85]
	v_mfma_f32_16x16x32_bf16 v[74:77], v[160:163], v[200:203], v[74:77]
	v_mfma_f32_16x16x32_bf16 v[74:77], v[164:167], v[204:207], v[74:77]
	v_mfma_f32_16x16x32_bf16 v[70:73], v[168:171], v[200:203], v[70:73]
	v_mfma_f32_16x16x32_bf16 v[70:73], v[172:175], v[204:207], v[70:73]
	s_setprio 0
	s_barrier
	s_mov_b32 m0, s45
	s_mov_b32 s14, s18
	s_mov_b32 s15, s19
	ds_read_b128 v[176:179], v140 offset:16384
	ds_read_b128 v[180:183], v140 offset:17408
	ds_read_b128 v[184:187], v140 offset:18432
	ds_read_b128 v[188:191], v140 offset:19456
	ds_read_b128 v[192:195], v140 offset:20480
	ds_read_b128 v[196:199], v140 offset:21504
	ds_read_b128 v[200:203], v140 offset:22528
	ds_read_b128 v[204:207], v140 offset:23552
	buffer_load_dwordx4 v137, s[12:15], s79 offen lds
	s_add_i32 s80, s79, 0x80000
	s_mov_b32 m0, s46
	s_nop 0
	buffer_load_dwordx4 v137, s[12:15], s80 offen lds
	s_add_i32 s80, s79, 0x100000
	s_mov_b32 m0, s47
	s_nop 0
	buffer_load_dwordx4 v137, s[12:15], s80 offen lds
	s_add_i32 s80, s79, 0x180000
	s_mov_b32 m0, s48
	s_nop 0
	buffer_load_dwordx4 v137, s[12:15], s80 offen lds
	s_mov_b32 m0, s44
	s_add_i32 s80, s77, 0x80000
	buffer_load_dwordx4 v136, s[16:19], s77 offen lds
	s_mov_b32 m0, s49
	s_nop 0
	buffer_load_dwordx4 v136, s[16:19], s80 offen lds
	s_waitcnt vmcnt(8)
	s_waitcnt lgkmcnt(0)
	s_setprio 1
	s_waitcnt lgkmcnt(7)
	v_mfma_f32_16x16x32_bf16 v[62:65], v[144:147], v[176:179], v[62:65]
	s_barrier
	v_mfma_f32_16x16x32_bf16 v[62:65], v[148:151], v[180:183], v[62:65]
	s_waitcnt lgkmcnt(5)
	v_mfma_f32_16x16x32_bf16 v[54:57], v[152:155], v[176:179], v[54:57]
	v_mfma_f32_16x16x32_bf16 v[54:57], v[156:159], v[180:183], v[54:57]
	s_waitcnt lgkmcnt(3)
	v_mfma_f32_16x16x32_bf16 v[46:49], v[144:147], v[184:187], v[46:49]
	v_mfma_f32_16x16x32_bf16 v[46:49], v[148:151], v[188:191], v[46:49]
	s_waitcnt lgkmcnt(1)
	v_mfma_f32_16x16x32_bf16 v[38:41], v[152:155], v[184:187], v[38:41]
	v_mfma_f32_16x16x32_bf16 v[38:41], v[156:159], v[188:191], v[38:41]
	v_mfma_f32_16x16x32_bf16 v[30:33], v[144:147], v[192:195], v[30:33]
	v_mfma_f32_16x16x32_bf16 v[30:33], v[148:151], v[196:199], v[30:33]
	v_mfma_f32_16x16x32_bf16 v[22:25], v[152:155], v[192:195], v[22:25]
	v_mfma_f32_16x16x32_bf16 v[22:25], v[156:159], v[196:199], v[22:25]
	v_mfma_f32_16x16x32_bf16 v[14:17], v[144:147], v[200:203], v[14:17]
	v_mfma_f32_16x16x32_bf16 v[14:17], v[148:151], v[204:207], v[14:17]
	v_mfma_f32_16x16x32_bf16 v[6:9], v[152:155], v[200:203], v[6:9]
	v_mfma_f32_16x16x32_bf16 v[6:9], v[156:159], v[204:207], v[6:9]
	v_mfma_f32_16x16x32_bf16 v[58:61], v[160:163], v[176:179], v[58:61]
	v_mfma_f32_16x16x32_bf16 v[58:61], v[164:167], v[180:183], v[58:61]
	v_mfma_f32_16x16x32_bf16 v[50:53], v[168:171], v[176:179], v[50:53]
	v_mfma_f32_16x16x32_bf16 v[50:53], v[172:175], v[180:183], v[50:53]
	v_mfma_f32_16x16x32_bf16 v[42:45], v[160:163], v[184:187], v[42:45]
	v_mfma_f32_16x16x32_bf16 v[42:45], v[164:167], v[188:191], v[42:45]
	s_waitcnt lgkmcnt(0)
	v_mfma_f32_16x16x32_bf16 v[34:37], v[168:171], v[184:187], v[34:37]
	v_mfma_f32_16x16x32_bf16 v[34:37], v[172:175], v[188:191], v[34:37]
	v_mfma_f32_16x16x32_bf16 v[26:29], v[160:163], v[192:195], v[26:29]
	v_mfma_f32_16x16x32_bf16 v[26:29], v[164:167], v[196:199], v[26:29]
	v_mfma_f32_16x16x32_bf16 v[18:21], v[168:171], v[192:195], v[18:21]
	v_mfma_f32_16x16x32_bf16 v[18:21], v[172:175], v[196:199], v[18:21]
	v_mfma_f32_16x16x32_bf16 v[10:13], v[160:163], v[200:203], v[10:13]
	v_mfma_f32_16x16x32_bf16 v[10:13], v[164:167], v[204:207], v[10:13]
	v_mfma_f32_16x16x32_bf16 v[2:5], v[168:171], v[200:203], v[2:5]
	v_mfma_f32_16x16x32_bf16 v[2:5], v[172:175], v[204:207], v[2:5]
	s_setprio 0
	s_barrier
	ds_read_b128 v[144:147], v141
	ds_read_b128 v[148:151], v141 offset:1024
	ds_read_b128 v[152:155], v141 offset:2048
	ds_read_b128 v[156:159], v141 offset:3072
	ds_read_b128 v[160:163], v142
	ds_read_b128 v[164:167], v142 offset:1024
	ds_read_b128 v[168:171], v142 offset:2048
	ds_read_b128 v[172:175], v142 offset:3072
	s_mov_b32 m0, s50
	s_add_i32 s80, s77, 0x100000
	ds_read_b128 v[176:179], v140 offset:32768
	ds_read_b128 v[180:183], v140 offset:33792
	ds_read_b128 v[184:187], v140 offset:34816
	ds_read_b128 v[188:191], v140 offset:35840
	ds_read_b128 v[192:195], v140 offset:36864
	ds_read_b128 v[196:199], v140 offset:37888
	ds_read_b128 v[200:203], v140 offset:38912
	ds_read_b128 v[204:207], v140 offset:39936
	buffer_load_dwordx4 v136, s[16:19], s80 offen lds
	s_add_i32 s80, s77, 0x180000
	s_mov_b32 m0, s51
	s_nop 0
	buffer_load_dwordx4 v136, s[16:19], s80 offen lds
	s_waitcnt vmcnt(8)
	s_waitcnt lgkmcnt(0)
	s_setprio 1
	s_waitcnt lgkmcnt(7)
	v_mfma_f32_16x16x32_bf16 v[118:121], v[144:147], v[176:179], v[118:121]
	s_barrier
	v_mfma_f32_16x16x32_bf16 v[118:121], v[148:151], v[180:183], v[118:121]
	s_waitcnt lgkmcnt(5)
	v_mfma_f32_16x16x32_bf16 v[114:117], v[152:155], v[176:179], v[114:117]
	v_mfma_f32_16x16x32_bf16 v[114:117], v[156:159], v[180:183], v[114:117]
	s_waitcnt lgkmcnt(3)
	v_mfma_f32_16x16x32_bf16 v[110:113], v[144:147], v[184:187], v[110:113]
	v_mfma_f32_16x16x32_bf16 v[110:113], v[148:151], v[188:191], v[110:113]
	s_waitcnt lgkmcnt(1)
	v_mfma_f32_16x16x32_bf16 v[102:105], v[152:155], v[184:187], v[102:105]
	v_mfma_f32_16x16x32_bf16 v[102:105], v[156:159], v[188:191], v[102:105]
	v_mfma_f32_16x16x32_bf16 v[94:97], v[144:147], v[192:195], v[94:97]
	v_mfma_f32_16x16x32_bf16 v[94:97], v[148:151], v[196:199], v[94:97]
	v_mfma_f32_16x16x32_bf16 v[86:89], v[152:155], v[192:195], v[86:89]
	v_mfma_f32_16x16x32_bf16 v[86:89], v[156:159], v[196:199], v[86:89]
	v_mfma_f32_16x16x32_bf16 v[78:81], v[144:147], v[200:203], v[78:81]
	v_mfma_f32_16x16x32_bf16 v[78:81], v[148:151], v[204:207], v[78:81]
	v_mfma_f32_16x16x32_bf16 v[66:69], v[152:155], v[200:203], v[66:69]
	v_mfma_f32_16x16x32_bf16 v[66:69], v[156:159], v[204:207], v[66:69]
	v_mfma_f32_16x16x32_bf16 v[126:129], v[160:163], v[176:179], v[126:129]
	v_mfma_f32_16x16x32_bf16 v[126:129], v[164:167], v[180:183], v[126:129]
	v_mfma_f32_16x16x32_bf16 v[122:125], v[168:171], v[176:179], v[122:125]
	v_mfma_f32_16x16x32_bf16 v[122:125], v[172:175], v[180:183], v[122:125]
	v_mfma_f32_16x16x32_bf16 v[106:109], v[160:163], v[184:187], v[106:109]
	v_mfma_f32_16x16x32_bf16 v[106:109], v[164:167], v[188:191], v[106:109]
	s_waitcnt lgkmcnt(0)
	v_mfma_f32_16x16x32_bf16 v[98:101], v[168:171], v[184:187], v[98:101]
	v_mfma_f32_16x16x32_bf16 v[98:101], v[172:175], v[188:191], v[98:101]
	v_mfma_f32_16x16x32_bf16 v[90:93], v[160:163], v[192:195], v[90:93]
	v_mfma_f32_16x16x32_bf16 v[90:93], v[164:167], v[196:199], v[90:93]
	v_mfma_f32_16x16x32_bf16 v[82:85], v[168:171], v[192:195], v[82:85]
	v_mfma_f32_16x16x32_bf16 v[82:85], v[172:175], v[196:199], v[82:85]
	v_mfma_f32_16x16x32_bf16 v[74:77], v[160:163], v[200:203], v[74:77]
	v_mfma_f32_16x16x32_bf16 v[74:77], v[164:167], v[204:207], v[74:77]
	v_mfma_f32_16x16x32_bf16 v[70:73], v[168:171], v[200:203], v[70:73]
	v_mfma_f32_16x16x32_bf16 v[70:73], v[172:175], v[204:207], v[70:73]
	s_setprio 0
	s_barrier
	s_mov_b32 m0, s53
	s_or_b32 s80, s79, 0x80
	ds_read_b128 v[176:179], v140 offset:49152
	ds_read_b128 v[180:183], v140 offset:50176
	ds_read_b128 v[184:187], v140 offset:51200
	ds_read_b128 v[188:191], v140 offset:52224
	ds_read_b128 v[192:195], v140 offset:53248
	ds_read_b128 v[196:199], v140 offset:54272
	ds_read_b128 v[200:203], v140 offset:55296
	ds_read_b128 v[204:207], v140 offset:56320
	buffer_load_dwordx4 v137, s[12:15], s80 offen lds
	s_add_i32 s80, s79, 0x80080
	s_mov_b32 m0, s54
	s_add_i32 s77, s77, 0x80080
	buffer_load_dwordx4 v137, s[12:15], s80 offen lds
	s_add_i32 s80, s79, 0x100080
	s_mov_b32 m0, s57
	s_add_i32 s79, s79, 0x180080
	buffer_load_dwordx4 v137, s[12:15], s80 offen lds
	s_mov_b32 m0, s58
	s_nop 0
	buffer_load_dwordx4 v137, s[12:15], s79 offen lds
	s_mov_b32 m0, s55
	s_nop 0
	buffer_load_dwordx4 v136, s[16:19], s78 offen lds
	s_mov_b32 m0, s56
	s_nop 0
	buffer_load_dwordx4 v136, s[16:19], s77 offen lds
	s_waitcnt vmcnt(8)
	s_waitcnt lgkmcnt(0)
	s_setprio 1
	s_waitcnt lgkmcnt(7)
	v_mfma_f32_16x16x32_bf16 v[62:65], v[144:147], v[176:179], v[62:65]
	s_barrier
	v_mfma_f32_16x16x32_bf16 v[62:65], v[148:151], v[180:183], v[62:65]
	s_waitcnt lgkmcnt(5)
	v_mfma_f32_16x16x32_bf16 v[54:57], v[152:155], v[176:179], v[54:57]
	v_mfma_f32_16x16x32_bf16 v[54:57], v[156:159], v[180:183], v[54:57]
	s_waitcnt lgkmcnt(3)
	v_mfma_f32_16x16x32_bf16 v[46:49], v[144:147], v[184:187], v[46:49]
	v_mfma_f32_16x16x32_bf16 v[46:49], v[148:151], v[188:191], v[46:49]
	s_waitcnt lgkmcnt(1)
	v_mfma_f32_16x16x32_bf16 v[38:41], v[152:155], v[184:187], v[38:41]
	v_mfma_f32_16x16x32_bf16 v[38:41], v[156:159], v[188:191], v[38:41]
	v_mfma_f32_16x16x32_bf16 v[30:33], v[144:147], v[192:195], v[30:33]
	v_mfma_f32_16x16x32_bf16 v[30:33], v[148:151], v[196:199], v[30:33]
	v_mfma_f32_16x16x32_bf16 v[22:25], v[152:155], v[192:195], v[22:25]
	v_mfma_f32_16x16x32_bf16 v[22:25], v[156:159], v[196:199], v[22:25]
	v_mfma_f32_16x16x32_bf16 v[14:17], v[144:147], v[200:203], v[14:17]
	v_mfma_f32_16x16x32_bf16 v[14:17], v[148:151], v[204:207], v[14:17]
	v_mfma_f32_16x16x32_bf16 v[6:9], v[152:155], v[200:203], v[6:9]
	v_mfma_f32_16x16x32_bf16 v[6:9], v[156:159], v[204:207], v[6:9]
	v_mfma_f32_16x16x32_bf16 v[58:61], v[160:163], v[176:179], v[58:61]
	v_mfma_f32_16x16x32_bf16 v[58:61], v[164:167], v[180:183], v[58:61]
	v_mfma_f32_16x16x32_bf16 v[50:53], v[168:171], v[176:179], v[50:53]
	v_mfma_f32_16x16x32_bf16 v[50:53], v[172:175], v[180:183], v[50:53]
	v_mfma_f32_16x16x32_bf16 v[42:45], v[160:163], v[184:187], v[42:45]
	v_mfma_f32_16x16x32_bf16 v[42:45], v[164:167], v[188:191], v[42:45]
	s_waitcnt lgkmcnt(0)
	v_mfma_f32_16x16x32_bf16 v[34:37], v[168:171], v[184:187], v[34:37]
	v_mfma_f32_16x16x32_bf16 v[34:37], v[172:175], v[188:191], v[34:37]
	v_mfma_f32_16x16x32_bf16 v[26:29], v[160:163], v[192:195], v[26:29]
	v_mfma_f32_16x16x32_bf16 v[26:29], v[164:167], v[196:199], v[26:29]
	v_mfma_f32_16x16x32_bf16 v[18:21], v[168:171], v[192:195], v[18:21]
	v_mfma_f32_16x16x32_bf16 v[18:21], v[172:175], v[196:199], v[18:21]
	v_mfma_f32_16x16x32_bf16 v[10:13], v[160:163], v[200:203], v[10:13]
	v_mfma_f32_16x16x32_bf16 v[10:13], v[164:167], v[204:207], v[10:13]
	v_mfma_f32_16x16x32_bf16 v[2:5], v[168:171], v[200:203], v[2:5]
	v_mfma_f32_16x16x32_bf16 v[2:5], v[172:175], v[204:207], v[2:5]
	s_setprio 0
	s_barrier
	s_add_i32 s76, s76, 2
	s_addk_i32 s74, 0x100
	s_addk_i32 s75, 0x100
	s_cmp_ge_i32 s76, s27
	s_cbranch_scc0 .LBB0_1382
	s_and_b64 vcc, exec, s[42:43]
	s_cbranch_vccz .LBB0_1385

.LBB0_1402:
	ds_read_b128 v[146:149], v138
	ds_read_b128 v[150:153], v138 offset:1024
	ds_read_b128 v[154:157], v138 offset:2048
	ds_read_b128 v[158:161], v138 offset:3072
	ds_read_b128 v[162:165], v139
	ds_read_b128 v[166:169], v139 offset:1024
	ds_read_b128 v[170:173], v139 offset:2048
	ds_read_b128 v[174:177], v139 offset:3072
	s_add_i32 s22, s75, 0xffe80080
	s_cmp_eq_u32 s62, s77
	s_cselect_b32 s78, s73, s22
	s_cselect_b32 s80, s74, s76
	s_or_b32 s79, s78, 0x80
	s_add_i32 s22, s75, 0xfff80000
	s_mov_b32 m0, s63
	ds_read_b128 v[178:181], v140
	ds_read_b128 v[182:185], v140 offset:1024
	ds_read_b128 v[186:189], v140 offset:2048
	ds_read_b128 v[190:193], v140 offset:3072
	ds_read_b128 v[194:197], v140 offset:4096
	ds_read_b128 v[198:201], v140 offset:5120
	ds_read_b128 v[202:205], v140 offset:6144
	ds_read_b128 v[206:209], v140 offset:7168
	buffer_load_dwordx4 v136, s[16:19], s22 offen lds
	s_mov_b32 m0, s64
	s_nop 0
	buffer_load_dwordx4 v136, s[16:19], s75 offen lds
	s_waitcnt vmcnt(8)
	s_waitcnt lgkmcnt(0)
	s_setprio 1
	s_waitcnt lgkmcnt(7)
	v_mfma_f32_16x16x32_bf16 v[118:121], v[146:149], v[178:181], v[118:121]
	s_barrier
	v_mfma_f32_16x16x32_bf16 v[118:121], v[150:153], v[182:185], v[118:121]
	s_waitcnt lgkmcnt(5)
	v_mfma_f32_16x16x32_bf16 v[114:117], v[154:157], v[178:181], v[114:117]
	v_mfma_f32_16x16x32_bf16 v[114:117], v[158:161], v[182:185], v[114:117]
	s_waitcnt lgkmcnt(3)
	v_mfma_f32_16x16x32_bf16 v[110:113], v[146:149], v[186:189], v[110:113]
	v_mfma_f32_16x16x32_bf16 v[110:113], v[150:153], v[190:193], v[110:113]
	s_waitcnt lgkmcnt(1)
	v_mfma_f32_16x16x32_bf16 v[102:105], v[154:157], v[186:189], v[102:105]
	v_mfma_f32_16x16x32_bf16 v[102:105], v[158:161], v[190:193], v[102:105]
	v_mfma_f32_16x16x32_bf16 v[94:97], v[146:149], v[194:197], v[94:97]
	v_mfma_f32_16x16x32_bf16 v[94:97], v[150:153], v[198:201], v[94:97]
	v_mfma_f32_16x16x32_bf16 v[86:89], v[154:157], v[194:197], v[86:89]
	v_mfma_f32_16x16x32_bf16 v[86:89], v[158:161], v[198:201], v[86:89]
	v_mfma_f32_16x16x32_bf16 v[78:81], v[146:149], v[202:205], v[78:81]
	v_mfma_f32_16x16x32_bf16 v[78:81], v[150:153], v[206:209], v[78:81]
	v_mfma_f32_16x16x32_bf16 v[66:69], v[154:157], v[202:205], v[66:69]
	v_mfma_f32_16x16x32_bf16 v[66:69], v[158:161], v[206:209], v[66:69]
	v_mfma_f32_16x16x32_bf16 v[126:129], v[162:165], v[178:181], v[126:129]
	v_mfma_f32_16x16x32_bf16 v[126:129], v[166:169], v[182:185], v[126:129]
	v_mfma_f32_16x16x32_bf16 v[122:125], v[170:173], v[178:181], v[122:125]
	v_mfma_f32_16x16x32_bf16 v[122:125], v[174:177], v[182:185], v[122:125]
	v_mfma_f32_16x16x32_bf16 v[106:109], v[162:165], v[186:189], v[106:109]
	v_mfma_f32_16x16x32_bf16 v[106:109], v[166:169], v[190:193], v[106:109]
	s_waitcnt lgkmcnt(0)
	v_mfma_f32_16x16x32_bf16 v[98:101], v[170:173], v[186:189], v[98:101]
	v_mfma_f32_16x16x32_bf16 v[98:101], v[174:177], v[190:193], v[98:101]
	v_mfma_f32_16x16x32_bf16 v[90:93], v[162:165], v[194:197], v[90:93]
	v_mfma_f32_16x16x32_bf16 v[90:93], v[166:169], v[198:201], v[90:93]
	v_mfma_f32_16x16x32_bf16 v[82:85], v[170:173], v[194:197], v[82:85]
	v_mfma_f32_16x16x32_bf16 v[82:85], v[174:177], v[198:201], v[82:85]
	v_mfma_f32_16x16x32_bf16 v[74:77], v[162:165], v[202:205], v[74:77]
	v_mfma_f32_16x16x32_bf16 v[74:77], v[166:169], v[206:209], v[74:77]
	v_mfma_f32_16x16x32_bf16 v[70:73], v[170:173], v[202:205], v[70:73]
	v_mfma_f32_16x16x32_bf16 v[70:73], v[174:177], v[206:209], v[70:73]
	s_setprio 0
	s_barrier
	s_mov_b32 m0, s31
	s_mov_b32 s22, s18
	s_mov_b32 s23, s19
	ds_read_b128 v[178:181], v140 offset:16384
	ds_read_b128 v[182:185], v140 offset:17408
	ds_read_b128 v[186:189], v140 offset:18432
	ds_read_b128 v[190:193], v140 offset:19456
	ds_read_b128 v[194:197], v140 offset:20480
	ds_read_b128 v[198:201], v140 offset:21504
	ds_read_b128 v[202:205], v140 offset:22528
	ds_read_b128 v[206:209], v140 offset:23552
	buffer_load_dwordx4 v137, s[20:23], s80 offen lds
	s_add_i32 s81, s80, 0x80000
	s_mov_b32 m0, s48
	s_nop 0
	buffer_load_dwordx4 v137, s[20:23], s81 offen lds
	s_add_i32 s81, s80, 0x100000
	s_mov_b32 m0, s49
	s_nop 0
	buffer_load_dwordx4 v137, s[20:23], s81 offen lds
	s_add_i32 s81, s80, 0x180000
	s_mov_b32 m0, s50
	s_nop 0
	buffer_load_dwordx4 v137, s[20:23], s81 offen lds
	s_mov_b32 m0, s30
	s_add_i32 s81, s78, 0x80000
	buffer_load_dwordx4 v136, s[16:19], s78 offen lds
	s_mov_b32 m0, s51
	s_nop 0
	buffer_load_dwordx4 v136, s[16:19], s81 offen lds
	s_waitcnt vmcnt(8)
	s_waitcnt lgkmcnt(0)
	s_setprio 1
	s_waitcnt lgkmcnt(7)
	v_mfma_f32_16x16x32_bf16 v[62:65], v[146:149], v[178:181], v[62:65]
	s_barrier
	v_mfma_f32_16x16x32_bf16 v[62:65], v[150:153], v[182:185], v[62:65]
	s_waitcnt lgkmcnt(5)
	v_mfma_f32_16x16x32_bf16 v[54:57], v[154:157], v[178:181], v[54:57]
	v_mfma_f32_16x16x32_bf16 v[54:57], v[158:161], v[182:185], v[54:57]
	s_waitcnt lgkmcnt(3)
	v_mfma_f32_16x16x32_bf16 v[46:49], v[146:149], v[186:189], v[46:49]
	v_mfma_f32_16x16x32_bf16 v[46:49], v[150:153], v[190:193], v[46:49]
	s_waitcnt lgkmcnt(1)
	v_mfma_f32_16x16x32_bf16 v[38:41], v[154:157], v[186:189], v[38:41]
	v_mfma_f32_16x16x32_bf16 v[38:41], v[158:161], v[190:193], v[38:41]
	v_mfma_f32_16x16x32_bf16 v[30:33], v[146:149], v[194:197], v[30:33]
	v_mfma_f32_16x16x32_bf16 v[30:33], v[150:153], v[198:201], v[30:33]
	v_mfma_f32_16x16x32_bf16 v[22:25], v[154:157], v[194:197], v[22:25]
	v_mfma_f32_16x16x32_bf16 v[22:25], v[158:161], v[198:201], v[22:25]
	v_mfma_f32_16x16x32_bf16 v[14:17], v[146:149], v[202:205], v[14:17]
	v_mfma_f32_16x16x32_bf16 v[14:17], v[150:153], v[206:209], v[14:17]
	v_mfma_f32_16x16x32_bf16 v[6:9], v[154:157], v[202:205], v[6:9]
	v_mfma_f32_16x16x32_bf16 v[6:9], v[158:161], v[206:209], v[6:9]
	v_mfma_f32_16x16x32_bf16 v[58:61], v[162:165], v[178:181], v[58:61]
	v_mfma_f32_16x16x32_bf16 v[58:61], v[166:169], v[182:185], v[58:61]
	v_mfma_f32_16x16x32_bf16 v[50:53], v[170:173], v[178:181], v[50:53]
	v_mfma_f32_16x16x32_bf16 v[50:53], v[174:177], v[182:185], v[50:53]
	v_mfma_f32_16x16x32_bf16 v[42:45], v[162:165], v[186:189], v[42:45]
	v_mfma_f32_16x16x32_bf16 v[42:45], v[166:169], v[190:193], v[42:45]
	s_waitcnt lgkmcnt(0)
	v_mfma_f32_16x16x32_bf16 v[34:37], v[170:173], v[186:189], v[34:37]
	v_mfma_f32_16x16x32_bf16 v[34:37], v[174:177], v[190:193], v[34:37]
	v_mfma_f32_16x16x32_bf16 v[26:29], v[162:165], v[194:197], v[26:29]
	v_mfma_f32_16x16x32_bf16 v[26:29], v[166:169], v[198:201], v[26:29]
	v_mfma_f32_16x16x32_bf16 v[18:21], v[170:173], v[194:197], v[18:21]
	v_mfma_f32_16x16x32_bf16 v[18:21], v[174:177], v[198:201], v[18:21]
	v_mfma_f32_16x16x32_bf16 v[10:13], v[162:165], v[202:205], v[10:13]
	v_mfma_f32_16x16x32_bf16 v[10:13], v[166:169], v[206:209], v[10:13]
	v_mfma_f32_16x16x32_bf16 v[2:5], v[170:173], v[202:205], v[2:5]
	v_mfma_f32_16x16x32_bf16 v[2:5], v[174:177], v[206:209], v[2:5]
	s_setprio 0
	s_barrier
	ds_read_b128 v[146:149], v141
	ds_read_b128 v[150:153], v141 offset:1024
	ds_read_b128 v[154:157], v141 offset:2048
	ds_read_b128 v[158:161], v141 offset:3072
	ds_read_b128 v[162:165], v142
	ds_read_b128 v[166:169], v142 offset:1024
	ds_read_b128 v[170:173], v142 offset:2048
	ds_read_b128 v[174:177], v142 offset:3072
	s_mov_b32 m0, s52
	s_add_i32 s81, s78, 0x100000
	ds_read_b128 v[178:181], v140 offset:32768
	ds_read_b128 v[182:185], v140 offset:33792
	ds_read_b128 v[186:189], v140 offset:34816
	ds_read_b128 v[190:193], v140 offset:35840
	ds_read_b128 v[194:197], v140 offset:36864
	ds_read_b128 v[198:201], v140 offset:37888
	ds_read_b128 v[202:205], v140 offset:38912
	ds_read_b128 v[206:209], v140 offset:39936
	buffer_load_dwordx4 v136, s[16:19], s81 offen lds
	s_add_i32 s81, s78, 0x180000
	s_mov_b32 m0, s53
	s_nop 0
	buffer_load_dwordx4 v136, s[16:19], s81 offen lds
	s_waitcnt vmcnt(8)
	s_waitcnt lgkmcnt(0)
	s_setprio 1
	s_waitcnt lgkmcnt(7)
	v_mfma_f32_16x16x32_bf16 v[118:121], v[146:149], v[178:181], v[118:121]
	s_barrier
	v_mfma_f32_16x16x32_bf16 v[118:121], v[150:153], v[182:185], v[118:121]
	s_waitcnt lgkmcnt(5)
	v_mfma_f32_16x16x32_bf16 v[114:117], v[154:157], v[178:181], v[114:117]
	v_mfma_f32_16x16x32_bf16 v[114:117], v[158:161], v[182:185], v[114:117]
	s_waitcnt lgkmcnt(3)
	v_mfma_f32_16x16x32_bf16 v[110:113], v[146:149], v[186:189], v[110:113]
	v_mfma_f32_16x16x32_bf16 v[110:113], v[150:153], v[190:193], v[110:113]
	s_waitcnt lgkmcnt(1)
	v_mfma_f32_16x16x32_bf16 v[102:105], v[154:157], v[186:189], v[102:105]
	v_mfma_f32_16x16x32_bf16 v[102:105], v[158:161], v[190:193], v[102:105]
	v_mfma_f32_16x16x32_bf16 v[94:97], v[146:149], v[194:197], v[94:97]
	v_mfma_f32_16x16x32_bf16 v[94:97], v[150:153], v[198:201], v[94:97]
	v_mfma_f32_16x16x32_bf16 v[86:89], v[154:157], v[194:197], v[86:89]
	v_mfma_f32_16x16x32_bf16 v[86:89], v[158:161], v[198:201], v[86:89]
	v_mfma_f32_16x16x32_bf16 v[78:81], v[146:149], v[202:205], v[78:81]
	v_mfma_f32_16x16x32_bf16 v[78:81], v[150:153], v[206:209], v[78:81]
	v_mfma_f32_16x16x32_bf16 v[66:69], v[154:157], v[202:205], v[66:69]
	v_mfma_f32_16x16x32_bf16 v[66:69], v[158:161], v[206:209], v[66:69]
	v_mfma_f32_16x16x32_bf16 v[126:129], v[162:165], v[178:181], v[126:129]
	v_mfma_f32_16x16x32_bf16 v[126:129], v[166:169], v[182:185], v[126:129]
	v_mfma_f32_16x16x32_bf16 v[122:125], v[170:173], v[178:181], v[122:125]
	v_mfma_f32_16x16x32_bf16 v[122:125], v[174:177], v[182:185], v[122:125]
	v_mfma_f32_16x16x32_bf16 v[106:109], v[162:165], v[186:189], v[106:109]
	v_mfma_f32_16x16x32_bf16 v[106:109], v[166:169], v[190:193], v[106:109]
	s_waitcnt lgkmcnt(0)
	v_mfma_f32_16x16x32_bf16 v[98:101], v[170:173], v[186:189], v[98:101]
	v_mfma_f32_16x16x32_bf16 v[98:101], v[174:177], v[190:193], v[98:101]
	v_mfma_f32_16x16x32_bf16 v[90:93], v[162:165], v[194:197], v[90:93]
	v_mfma_f32_16x16x32_bf16 v[90:93], v[166:169], v[198:201], v[90:93]
	v_mfma_f32_16x16x32_bf16 v[82:85], v[170:173], v[194:197], v[82:85]
	v_mfma_f32_16x16x32_bf16 v[82:85], v[174:177], v[198:201], v[82:85]
	v_mfma_f32_16x16x32_bf16 v[74:77], v[162:165], v[202:205], v[74:77]
	v_mfma_f32_16x16x32_bf16 v[74:77], v[166:169], v[206:209], v[74:77]
	v_mfma_f32_16x16x32_bf16 v[70:73], v[170:173], v[202:205], v[70:73]
	v_mfma_f32_16x16x32_bf16 v[70:73], v[174:177], v[206:209], v[70:73]
	s_setprio 0
	s_barrier
	s_mov_b32 m0, s54
	s_or_b32 s81, s80, 0x80
	ds_read_b128 v[178:181], v140 offset:49152
	ds_read_b128 v[182:185], v140 offset:50176
	ds_read_b128 v[186:189], v140 offset:51200
	ds_read_b128 v[190:193], v140 offset:52224
	ds_read_b128 v[194:197], v140 offset:53248
	ds_read_b128 v[198:201], v140 offset:54272
	ds_read_b128 v[202:205], v140 offset:55296
	ds_read_b128 v[206:209], v140 offset:56320
	buffer_load_dwordx4 v137, s[20:23], s81 offen lds
	s_add_i32 s81, s80, 0x80080
	s_mov_b32 m0, s55
	s_add_i32 s78, s78, 0x80080
	buffer_load_dwordx4 v137, s[20:23], s81 offen lds
	s_add_i32 s81, s80, 0x100080
	s_mov_b32 m0, s58
	s_add_i32 s80, s80, 0x180080
	buffer_load_dwordx4 v137, s[20:23], s81 offen lds
	s_mov_b32 m0, s59
	s_nop 0
	buffer_load_dwordx4 v137, s[20:23], s80 offen lds
	s_mov_b32 m0, s56
	s_nop 0
	buffer_load_dwordx4 v136, s[16:19], s79 offen lds
	s_mov_b32 m0, s57
	s_nop 0
	buffer_load_dwordx4 v136, s[16:19], s78 offen lds
	s_waitcnt vmcnt(8)
	s_waitcnt lgkmcnt(0)
	s_setprio 1
	s_waitcnt lgkmcnt(7)
	v_mfma_f32_16x16x32_bf16 v[62:65], v[146:149], v[178:181], v[62:65]
	s_barrier
	v_mfma_f32_16x16x32_bf16 v[62:65], v[150:153], v[182:185], v[62:65]
	s_waitcnt lgkmcnt(5)
	v_mfma_f32_16x16x32_bf16 v[54:57], v[154:157], v[178:181], v[54:57]
	v_mfma_f32_16x16x32_bf16 v[54:57], v[158:161], v[182:185], v[54:57]
	s_waitcnt lgkmcnt(3)
	v_mfma_f32_16x16x32_bf16 v[46:49], v[146:149], v[186:189], v[46:49]
	v_mfma_f32_16x16x32_bf16 v[46:49], v[150:153], v[190:193], v[46:49]
	s_waitcnt lgkmcnt(1)
	v_mfma_f32_16x16x32_bf16 v[38:41], v[154:157], v[186:189], v[38:41]
	v_mfma_f32_16x16x32_bf16 v[38:41], v[158:161], v[190:193], v[38:41]
	v_mfma_f32_16x16x32_bf16 v[30:33], v[146:149], v[194:197], v[30:33]
	v_mfma_f32_16x16x32_bf16 v[30:33], v[150:153], v[198:201], v[30:33]
	v_mfma_f32_16x16x32_bf16 v[22:25], v[154:157], v[194:197], v[22:25]
	v_mfma_f32_16x16x32_bf16 v[22:25], v[158:161], v[198:201], v[22:25]
	v_mfma_f32_16x16x32_bf16 v[14:17], v[146:149], v[202:205], v[14:17]
	v_mfma_f32_16x16x32_bf16 v[14:17], v[150:153], v[206:209], v[14:17]
	v_mfma_f32_16x16x32_bf16 v[6:9], v[154:157], v[202:205], v[6:9]
	v_mfma_f32_16x16x32_bf16 v[6:9], v[158:161], v[206:209], v[6:9]
	v_mfma_f32_16x16x32_bf16 v[58:61], v[162:165], v[178:181], v[58:61]
	v_mfma_f32_16x16x32_bf16 v[58:61], v[166:169], v[182:185], v[58:61]
	v_mfma_f32_16x16x32_bf16 v[50:53], v[170:173], v[178:181], v[50:53]
	v_mfma_f32_16x16x32_bf16 v[50:53], v[174:177], v[182:185], v[50:53]
	v_mfma_f32_16x16x32_bf16 v[42:45], v[162:165], v[186:189], v[42:45]
	v_mfma_f32_16x16x32_bf16 v[42:45], v[166:169], v[190:193], v[42:45]
	s_waitcnt lgkmcnt(0)
	v_mfma_f32_16x16x32_bf16 v[34:37], v[170:173], v[186:189], v[34:37]
	v_mfma_f32_16x16x32_bf16 v[34:37], v[174:177], v[190:193], v[34:37]
	v_mfma_f32_16x16x32_bf16 v[26:29], v[162:165], v[194:197], v[26:29]
	v_mfma_f32_16x16x32_bf16 v[26:29], v[166:169], v[198:201], v[26:29]
	v_mfma_f32_16x16x32_bf16 v[18:21], v[170:173], v[194:197], v[18:21]
	v_mfma_f32_16x16x32_bf16 v[18:21], v[174:177], v[198:201], v[18:21]
	v_mfma_f32_16x16x32_bf16 v[10:13], v[162:165], v[202:205], v[10:13]
	v_mfma_f32_16x16x32_bf16 v[10:13], v[166:169], v[206:209], v[10:13]
	v_mfma_f32_16x16x32_bf16 v[2:5], v[170:173], v[202:205], v[2:5]
	v_mfma_f32_16x16x32_bf16 v[2:5], v[174:177], v[206:209], v[2:5]
	s_setprio 0
	s_barrier
	s_add_i32 s77, s77, 2
	s_addk_i32 s75, 0x100
	s_addk_i32 s76, 0x100
	s_cmp_ge_i32 s77, s13
	s_cbranch_scc0 .LBB0_1402
	s_and_b64 vcc, exec, s[46:47]
	s_cbranch_vccz .LBB0_1405

.LBB0_1519:
	ds_read_b128 v[134:137], v208
	ds_read_b128 v[138:141], v208 offset:1024
	ds_read_b128 v[142:145], v208 offset:2048
	ds_read_b128 v[146:149], v208 offset:3072
	ds_read_b128 v[150:153], v209
	ds_read_b128 v[154:157], v209 offset:1024
	ds_read_b128 v[158:161], v209 offset:2048
	ds_read_b128 v[162:165], v209 offset:3072
	s_add_i32 s18, s80, 0xffbf8080
	s_cmp_eq_u32 s65, s82
	s_cselect_b32 s83, s6, s18
	s_cselect_b32 s85, s7, s81
	s_or_b32 s84, s83, 0x80
	s_add_i32 s18, s80, 0xffea8000
	s_mov_b32 m0, s66
	ds_read_b128 v[166:169], v210
	ds_read_b128 v[170:173], v210 offset:1024
	ds_read_b128 v[174:177], v210 offset:2048
	ds_read_b128 v[178:181], v210 offset:3072
	ds_read_b128 v[182:185], v210 offset:4096
	ds_read_b128 v[186:189], v210 offset:5120
	ds_read_b128 v[190:193], v210 offset:6144
	ds_read_b128 v[194:197], v210 offset:7168
	buffer_load_dwordx4 v206, s[12:15], s18 offen lds
	s_mov_b32 m0, s69
	s_nop 0
	buffer_load_dwordx4 v206, s[12:15], s80 offen lds
	s_waitcnt vmcnt(8)
	s_waitcnt lgkmcnt(0)
	s_setprio 1
	s_waitcnt lgkmcnt(7)
	v_mfma_f32_16x16x32_bf16 v[126:129], v[134:137], v[166:169], v[126:129]
	s_barrier
	v_mfma_f32_16x16x32_bf16 v[126:129], v[138:141], v[170:173], v[126:129]
	s_waitcnt lgkmcnt(5)
	v_mfma_f32_16x16x32_bf16 v[122:125], v[142:145], v[166:169], v[122:125]
	v_mfma_f32_16x16x32_bf16 v[122:125], v[146:149], v[170:173], v[122:125]
	s_waitcnt lgkmcnt(3)
	v_mfma_f32_16x16x32_bf16 v[118:121], v[134:137], v[174:177], v[118:121]
	v_mfma_f32_16x16x32_bf16 v[118:121], v[138:141], v[178:181], v[118:121]
	s_waitcnt lgkmcnt(1)
	v_mfma_f32_16x16x32_bf16 v[114:117], v[142:145], v[174:177], v[114:117]
	v_mfma_f32_16x16x32_bf16 v[114:117], v[146:149], v[178:181], v[114:117]
	v_mfma_f32_16x16x32_bf16 v[106:109], v[134:137], v[182:185], v[106:109]
	v_mfma_f32_16x16x32_bf16 v[106:109], v[138:141], v[186:189], v[106:109]
	v_mfma_f32_16x16x32_bf16 v[98:101], v[142:145], v[182:185], v[98:101]
	v_mfma_f32_16x16x32_bf16 v[98:101], v[146:149], v[186:189], v[98:101]
	v_mfma_f32_16x16x32_bf16 v[90:93], v[134:137], v[190:193], v[90:93]
	v_mfma_f32_16x16x32_bf16 v[90:93], v[138:141], v[194:197], v[90:93]
	v_mfma_f32_16x16x32_bf16 v[82:85], v[142:145], v[190:193], v[82:85]
	v_mfma_f32_16x16x32_bf16 v[82:85], v[146:149], v[194:197], v[82:85]
	v_mfma_f32_16x16x32_bf16 v[110:113], v[150:153], v[166:169], v[110:113]
	v_mfma_f32_16x16x32_bf16 v[110:113], v[154:157], v[170:173], v[110:113]
	v_mfma_f32_16x16x32_bf16 v[102:105], v[158:161], v[166:169], v[102:105]
	v_mfma_f32_16x16x32_bf16 v[102:105], v[162:165], v[170:173], v[102:105]
	v_mfma_f32_16x16x32_bf16 v[94:97], v[150:153], v[174:177], v[94:97]
	v_mfma_f32_16x16x32_bf16 v[94:97], v[154:157], v[178:181], v[94:97]
	s_waitcnt lgkmcnt(0)
	v_mfma_f32_16x16x32_bf16 v[86:89], v[158:161], v[174:177], v[86:89]
	v_mfma_f32_16x16x32_bf16 v[86:89], v[162:165], v[178:181], v[86:89]
	v_mfma_f32_16x16x32_bf16 v[78:81], v[150:153], v[182:185], v[78:81]
	v_mfma_f32_16x16x32_bf16 v[78:81], v[154:157], v[186:189], v[78:81]
	v_mfma_f32_16x16x32_bf16 v[74:77], v[158:161], v[182:185], v[74:77]
	v_mfma_f32_16x16x32_bf16 v[74:77], v[162:165], v[186:189], v[74:77]
	v_mfma_f32_16x16x32_bf16 v[70:73], v[150:153], v[190:193], v[70:73]
	v_mfma_f32_16x16x32_bf16 v[70:73], v[154:157], v[194:197], v[70:73]
	v_mfma_f32_16x16x32_bf16 v[66:69], v[158:161], v[190:193], v[66:69]
	v_mfma_f32_16x16x32_bf16 v[66:69], v[162:165], v[194:197], v[66:69]
	s_setprio 0
	s_barrier
	s_mov_b32 m0, s27
	s_mov_b32 s18, s14
	s_mov_b32 s19, s15
	ds_read_b128 v[166:169], v210 offset:16384
	ds_read_b128 v[170:173], v210 offset:17408
	ds_read_b128 v[174:177], v210 offset:18432
	ds_read_b128 v[178:181], v210 offset:19456
	ds_read_b128 v[182:185], v210 offset:20480
	ds_read_b128 v[186:189], v210 offset:21504
	ds_read_b128 v[190:193], v210 offset:22528
	ds_read_b128 v[194:197], v210 offset:23552
	buffer_load_dwordx4 v207, s[16:19], s85 offen lds
	s_add_i32 s86, s85, 0x158000
	s_mov_b32 m0, s30
	s_nop 0
	buffer_load_dwordx4 v207, s[16:19], s86 offen lds
	s_add_i32 s86, s85, 0x2b0000
	s_mov_b32 m0, s31
	s_nop 0
	buffer_load_dwordx4 v207, s[16:19], s86 offen lds
	s_add_i32 s86, s85, 0x408000
	s_mov_b32 m0, s50
	s_nop 0
	buffer_load_dwordx4 v207, s[16:19], s86 offen lds
	s_mov_b32 m0, s25
	s_add_i32 s86, s83, 0x158000
	buffer_load_dwordx4 v206, s[12:15], s83 offen lds
	s_mov_b32 m0, s51
	s_nop 0
	buffer_load_dwordx4 v206, s[12:15], s86 offen lds
	s_waitcnt vmcnt(8)
	s_waitcnt lgkmcnt(0)
	s_setprio 1
	s_waitcnt lgkmcnt(7)
	v_mfma_f32_16x16x32_bf16 v[62:65], v[134:137], v[166:169], v[62:65]
	s_barrier
	v_mfma_f32_16x16x32_bf16 v[62:65], v[138:141], v[170:173], v[62:65]
	s_waitcnt lgkmcnt(5)
	v_mfma_f32_16x16x32_bf16 v[58:61], v[142:145], v[166:169], v[58:61]
	v_mfma_f32_16x16x32_bf16 v[58:61], v[146:149], v[170:173], v[58:61]
	s_waitcnt lgkmcnt(3)
	v_mfma_f32_16x16x32_bf16 v[54:57], v[134:137], v[174:177], v[54:57]
	v_mfma_f32_16x16x32_bf16 v[54:57], v[138:141], v[178:181], v[54:57]
	s_waitcnt lgkmcnt(1)
	v_mfma_f32_16x16x32_bf16 v[50:53], v[142:145], v[174:177], v[50:53]
	v_mfma_f32_16x16x32_bf16 v[50:53], v[146:149], v[178:181], v[50:53]
	v_mfma_f32_16x16x32_bf16 v[42:45], v[134:137], v[182:185], v[42:45]
	v_mfma_f32_16x16x32_bf16 v[42:45], v[138:141], v[186:189], v[42:45]
	v_mfma_f32_16x16x32_bf16 v[34:37], v[142:145], v[182:185], v[34:37]
	v_mfma_f32_16x16x32_bf16 v[34:37], v[146:149], v[186:189], v[34:37]
	v_mfma_f32_16x16x32_bf16 v[26:29], v[134:137], v[190:193], v[26:29]
	v_mfma_f32_16x16x32_bf16 v[26:29], v[138:141], v[194:197], v[26:29]
	v_mfma_f32_16x16x32_bf16 v[18:21], v[142:145], v[190:193], v[18:21]
	v_mfma_f32_16x16x32_bf16 v[18:21], v[146:149], v[194:197], v[18:21]
	v_mfma_f32_16x16x32_bf16 v[46:49], v[150:153], v[166:169], v[46:49]
	v_mfma_f32_16x16x32_bf16 v[46:49], v[154:157], v[170:173], v[46:49]
	v_mfma_f32_16x16x32_bf16 v[38:41], v[158:161], v[166:169], v[38:41]
	v_mfma_f32_16x16x32_bf16 v[38:41], v[162:165], v[170:173], v[38:41]
	v_mfma_f32_16x16x32_bf16 v[30:33], v[150:153], v[174:177], v[30:33]
	v_mfma_f32_16x16x32_bf16 v[30:33], v[154:157], v[178:181], v[30:33]
	s_waitcnt lgkmcnt(0)
	v_mfma_f32_16x16x32_bf16 v[22:25], v[158:161], v[174:177], v[22:25]
	v_mfma_f32_16x16x32_bf16 v[22:25], v[162:165], v[178:181], v[22:25]
	v_mfma_f32_16x16x32_bf16 v[14:17], v[150:153], v[182:185], v[14:17]
	v_mfma_f32_16x16x32_bf16 v[14:17], v[154:157], v[186:189], v[14:17]
	v_mfma_f32_16x16x32_bf16 v[10:13], v[158:161], v[182:185], v[10:13]
	v_mfma_f32_16x16x32_bf16 v[10:13], v[162:165], v[186:189], v[10:13]
	v_mfma_f32_16x16x32_bf16 v[6:9], v[150:153], v[190:193], v[6:9]
	v_mfma_f32_16x16x32_bf16 v[6:9], v[154:157], v[194:197], v[6:9]
	v_mfma_f32_16x16x32_bf16 v[2:5], v[158:161], v[190:193], v[2:5]
	v_mfma_f32_16x16x32_bf16 v[2:5], v[162:165], v[194:197], v[2:5]
	s_setprio 0
	s_barrier
	ds_read_b128 v[134:137], v211
	ds_read_b128 v[138:141], v211 offset:1024
	ds_read_b128 v[142:145], v211 offset:2048
	ds_read_b128 v[146:149], v211 offset:3072
	ds_read_b128 v[150:153], v212
	ds_read_b128 v[154:157], v212 offset:1024
	ds_read_b128 v[158:161], v212 offset:2048
	ds_read_b128 v[162:165], v212 offset:3072
	s_mov_b32 m0, s52
	s_add_i32 s86, s83, 0x2b0000
	ds_read_b128 v[166:169], v210 offset:32768
	ds_read_b128 v[170:173], v210 offset:33792
	ds_read_b128 v[174:177], v210 offset:34816
	ds_read_b128 v[178:181], v210 offset:35840
	ds_read_b128 v[182:185], v210 offset:36864
	ds_read_b128 v[186:189], v210 offset:37888
	ds_read_b128 v[190:193], v210 offset:38912
	ds_read_b128 v[194:197], v210 offset:39936
	buffer_load_dwordx4 v206, s[12:15], s86 offen lds
	s_add_i32 s86, s83, 0x408000
	s_mov_b32 m0, s53
	s_nop 0
	buffer_load_dwordx4 v206, s[12:15], s86 offen lds
	s_waitcnt vmcnt(8)
	s_waitcnt lgkmcnt(0)
	s_setprio 1
	s_waitcnt lgkmcnt(7)
	v_mfma_f32_16x16x32_bf16 v[126:129], v[134:137], v[166:169], v[126:129]
	s_barrier
	v_mfma_f32_16x16x32_bf16 v[126:129], v[138:141], v[170:173], v[126:129]
	s_waitcnt lgkmcnt(5)
	v_mfma_f32_16x16x32_bf16 v[122:125], v[142:145], v[166:169], v[122:125]
	v_mfma_f32_16x16x32_bf16 v[122:125], v[146:149], v[170:173], v[122:125]
	s_waitcnt lgkmcnt(3)
	v_mfma_f32_16x16x32_bf16 v[118:121], v[134:137], v[174:177], v[118:121]
	v_mfma_f32_16x16x32_bf16 v[118:121], v[138:141], v[178:181], v[118:121]
	s_waitcnt lgkmcnt(1)
	v_mfma_f32_16x16x32_bf16 v[114:117], v[142:145], v[174:177], v[114:117]
	v_mfma_f32_16x16x32_bf16 v[114:117], v[146:149], v[178:181], v[114:117]
	v_mfma_f32_16x16x32_bf16 v[106:109], v[134:137], v[182:185], v[106:109]
	v_mfma_f32_16x16x32_bf16 v[106:109], v[138:141], v[186:189], v[106:109]
	v_mfma_f32_16x16x32_bf16 v[98:101], v[142:145], v[182:185], v[98:101]
	v_mfma_f32_16x16x32_bf16 v[98:101], v[146:149], v[186:189], v[98:101]
	v_mfma_f32_16x16x32_bf16 v[90:93], v[134:137], v[190:193], v[90:93]
	v_mfma_f32_16x16x32_bf16 v[90:93], v[138:141], v[194:197], v[90:93]
	v_mfma_f32_16x16x32_bf16 v[82:85], v[142:145], v[190:193], v[82:85]
	v_mfma_f32_16x16x32_bf16 v[82:85], v[146:149], v[194:197], v[82:85]
	v_mfma_f32_16x16x32_bf16 v[110:113], v[150:153], v[166:169], v[110:113]
	v_mfma_f32_16x16x32_bf16 v[110:113], v[154:157], v[170:173], v[110:113]
	v_mfma_f32_16x16x32_bf16 v[102:105], v[158:161], v[166:169], v[102:105]
	v_mfma_f32_16x16x32_bf16 v[102:105], v[162:165], v[170:173], v[102:105]
	v_mfma_f32_16x16x32_bf16 v[94:97], v[150:153], v[174:177], v[94:97]
	v_mfma_f32_16x16x32_bf16 v[94:97], v[154:157], v[178:181], v[94:97]
	s_waitcnt lgkmcnt(0)
	v_mfma_f32_16x16x32_bf16 v[86:89], v[158:161], v[174:177], v[86:89]
	v_mfma_f32_16x16x32_bf16 v[86:89], v[162:165], v[178:181], v[86:89]
	v_mfma_f32_16x16x32_bf16 v[78:81], v[150:153], v[182:185], v[78:81]
	v_mfma_f32_16x16x32_bf16 v[78:81], v[154:157], v[186:189], v[78:81]
	v_mfma_f32_16x16x32_bf16 v[74:77], v[158:161], v[182:185], v[74:77]
	v_mfma_f32_16x16x32_bf16 v[74:77], v[162:165], v[186:189], v[74:77]
	v_mfma_f32_16x16x32_bf16 v[70:73], v[150:153], v[190:193], v[70:73]
	v_mfma_f32_16x16x32_bf16 v[70:73], v[154:157], v[194:197], v[70:73]
	v_mfma_f32_16x16x32_bf16 v[66:69], v[158:161], v[190:193], v[66:69]
	v_mfma_f32_16x16x32_bf16 v[66:69], v[162:165], v[194:197], v[66:69]
	s_setprio 0
	s_barrier
	s_mov_b32 m0, s57
	s_or_b32 s86, s85, 0x80
	ds_read_b128 v[166:169], v210 offset:49152
	ds_read_b128 v[170:173], v210 offset:50176
	ds_read_b128 v[174:177], v210 offset:51200
	ds_read_b128 v[178:181], v210 offset:52224
	ds_read_b128 v[182:185], v210 offset:53248
	ds_read_b128 v[186:189], v210 offset:54272
	ds_read_b128 v[190:193], v210 offset:55296
	ds_read_b128 v[194:197], v210 offset:56320
	buffer_load_dwordx4 v207, s[16:19], s86 offen lds
	s_add_i32 s86, s85, 0x158080
	s_mov_b32 m0, s58
	s_add_i32 s83, s83, 0x158080
	buffer_load_dwordx4 v207, s[16:19], s86 offen lds
	s_add_i32 s86, s85, 0x2b0080
	s_mov_b32 m0, s61
	s_add_i32 s85, s85, 0x408080
	buffer_load_dwordx4 v207, s[16:19], s86 offen lds
	s_mov_b32 m0, s62
	s_nop 0
	buffer_load_dwordx4 v207, s[16:19], s85 offen lds
	s_mov_b32 m0, s59
	s_nop 0
	buffer_load_dwordx4 v206, s[12:15], s84 offen lds
	s_mov_b32 m0, s60
	s_nop 0
	buffer_load_dwordx4 v206, s[12:15], s83 offen lds
	s_waitcnt vmcnt(8)
	s_waitcnt lgkmcnt(0)
	s_setprio 1
	s_waitcnt lgkmcnt(7)
	v_mfma_f32_16x16x32_bf16 v[62:65], v[134:137], v[166:169], v[62:65]
	s_barrier
	v_mfma_f32_16x16x32_bf16 v[62:65], v[138:141], v[170:173], v[62:65]
	s_waitcnt lgkmcnt(5)
	v_mfma_f32_16x16x32_bf16 v[58:61], v[142:145], v[166:169], v[58:61]
	v_mfma_f32_16x16x32_bf16 v[58:61], v[146:149], v[170:173], v[58:61]
	s_waitcnt lgkmcnt(3)
	v_mfma_f32_16x16x32_bf16 v[54:57], v[134:137], v[174:177], v[54:57]
	v_mfma_f32_16x16x32_bf16 v[54:57], v[138:141], v[178:181], v[54:57]
	s_waitcnt lgkmcnt(1)
	v_mfma_f32_16x16x32_bf16 v[50:53], v[142:145], v[174:177], v[50:53]
	v_mfma_f32_16x16x32_bf16 v[50:53], v[146:149], v[178:181], v[50:53]
	v_mfma_f32_16x16x32_bf16 v[42:45], v[134:137], v[182:185], v[42:45]
	v_mfma_f32_16x16x32_bf16 v[42:45], v[138:141], v[186:189], v[42:45]
	v_mfma_f32_16x16x32_bf16 v[34:37], v[142:145], v[182:185], v[34:37]
	v_mfma_f32_16x16x32_bf16 v[34:37], v[146:149], v[186:189], v[34:37]
	v_mfma_f32_16x16x32_bf16 v[26:29], v[134:137], v[190:193], v[26:29]
	v_mfma_f32_16x16x32_bf16 v[26:29], v[138:141], v[194:197], v[26:29]
	v_mfma_f32_16x16x32_bf16 v[18:21], v[142:145], v[190:193], v[18:21]
	v_mfma_f32_16x16x32_bf16 v[18:21], v[146:149], v[194:197], v[18:21]
	v_mfma_f32_16x16x32_bf16 v[46:49], v[150:153], v[166:169], v[46:49]
	v_mfma_f32_16x16x32_bf16 v[46:49], v[154:157], v[170:173], v[46:49]
	v_mfma_f32_16x16x32_bf16 v[38:41], v[158:161], v[166:169], v[38:41]
	v_mfma_f32_16x16x32_bf16 v[38:41], v[162:165], v[170:173], v[38:41]
	v_mfma_f32_16x16x32_bf16 v[30:33], v[150:153], v[174:177], v[30:33]
	v_mfma_f32_16x16x32_bf16 v[30:33], v[154:157], v[178:181], v[30:33]
	s_waitcnt lgkmcnt(0)
	v_mfma_f32_16x16x32_bf16 v[22:25], v[158:161], v[174:177], v[22:25]
	v_mfma_f32_16x16x32_bf16 v[22:25], v[162:165], v[178:181], v[22:25]
	v_mfma_f32_16x16x32_bf16 v[14:17], v[150:153], v[182:185], v[14:17]
	v_mfma_f32_16x16x32_bf16 v[14:17], v[154:157], v[186:189], v[14:17]
	v_mfma_f32_16x16x32_bf16 v[10:13], v[158:161], v[182:185], v[10:13]
	v_mfma_f32_16x16x32_bf16 v[10:13], v[162:165], v[186:189], v[10:13]
	v_mfma_f32_16x16x32_bf16 v[6:9], v[150:153], v[190:193], v[6:9]
	v_mfma_f32_16x16x32_bf16 v[6:9], v[154:157], v[194:197], v[6:9]
	v_mfma_f32_16x16x32_bf16 v[2:5], v[158:161], v[190:193], v[2:5]
	v_mfma_f32_16x16x32_bf16 v[2:5], v[162:165], v[194:197], v[2:5]
	s_setprio 0
	s_barrier
	s_add_i32 s82, s82, 2
	s_addk_i32 s80, 0x100
	s_addk_i32 s81, 0x100
	s_cmp_ge_i32 s82, s3
	s_cbranch_scc0 .LBB0_1519
	v_pk_mul_f32 v[182:183], v[128:129], 0.5 op_sel_hi:[1,0]
	v_pk_mul_f32 v[184:185], v[126:127], 0.5 op_sel_hi:[1,0]
	v_pk_mul_f32 v[186:187], v[124:125], 0.5 op_sel_hi:[1,0]
	v_pk_mul_f32 v[188:189], v[122:123], 0.5 op_sel_hi:[1,0]
	v_pk_mul_f32 v[196:197], v[112:113], 0.5 op_sel_hi:[1,0]
	v_pk_mul_f32 v[194:195], v[110:111], 0.5 op_sel_hi:[1,0]
	v_pk_mul_f32 v[192:193], v[104:105], 0.5 op_sel_hi:[1,0]
	v_pk_mul_f32 v[190:191], v[102:103], 0.5 op_sel_hi:[1,0]
	v_pk_mul_f32 v[180:181], v[120:121], 0.5 op_sel_hi:[1,0]
	v_pk_mul_f32 v[178:179], v[118:119], 0.5 op_sel_hi:[1,0]
	v_pk_mul_f32 v[176:177], v[116:117], 0.5 op_sel_hi:[1,0]
	v_pk_mul_f32 v[174:175], v[114:115], 0.5 op_sel_hi:[1,0]
	v_pk_mul_f32 v[170:171], v[96:97], 0.5 op_sel_hi:[1,0]
	v_pk_mul_f32 v[168:169], v[94:95], 0.5 op_sel_hi:[1,0]
	v_pk_mul_f32 v[166:167], v[88:89], 0.5 op_sel_hi:[1,0]
	v_pk_mul_f32 v[164:165], v[86:87], 0.5 op_sel_hi:[1,0]
	v_pk_mul_f32 v[162:163], v[108:109], 0.5 op_sel_hi:[1,0]
	v_pk_mul_f32 v[160:161], v[106:107], 0.5 op_sel_hi:[1,0]
	v_pk_mul_f32 v[158:159], v[100:101], 0.5 op_sel_hi:[1,0]
	v_pk_mul_f32 v[156:157], v[98:99], 0.5 op_sel_hi:[1,0]
	v_pk_mul_f32 v[154:155], v[80:81], 0.5 op_sel_hi:[1,0]
	v_pk_mul_f32 v[152:153], v[78:79], 0.5 op_sel_hi:[1,0]
	v_pk_mul_f32 v[150:151], v[76:77], 0.5 op_sel_hi:[1,0]
	v_pk_mul_f32 v[148:149], v[74:75], 0.5 op_sel_hi:[1,0]
	v_pk_mul_f32 v[144:145], v[92:93], 0.5 op_sel_hi:[1,0]
	v_pk_mul_f32 v[142:143], v[90:91], 0.5 op_sel_hi:[1,0]
	v_pk_mul_f32 v[140:141], v[84:85], 0.5 op_sel_hi:[1,0]
	v_pk_mul_f32 v[138:139], v[82:83], 0.5 op_sel_hi:[1,0]
	v_pk_mul_f32 v[136:137], v[72:73], 0.5 op_sel_hi:[1,0]
	v_pk_mul_f32 v[134:135], v[70:71], 0.5 op_sel_hi:[1,0]
	v_pk_mul_f32 v[128:129], v[68:69], 0.5 op_sel_hi:[1,0]
	v_pk_mul_f32 v[126:127], v[66:67], 0.5 op_sel_hi:[1,0]
	v_pk_mul_f32 v[122:123], v[64:65], 0.5 op_sel_hi:[1,0]
	v_pk_mul_f32 v[120:121], v[62:63], 0.5 op_sel_hi:[1,0]
	v_pk_mul_f32 v[118:119], v[60:61], 0.5 op_sel_hi:[1,0]
	v_pk_mul_f32 v[116:117], v[58:59], 0.5 op_sel_hi:[1,0]
	v_pk_mul_f32 v[112:113], v[48:49], 0.5 op_sel_hi:[1,0]
	v_pk_mul_f32 v[110:111], v[46:47], 0.5 op_sel_hi:[1,0]
	v_pk_mul_f32 v[108:109], v[40:41], 0.5 op_sel_hi:[1,0]
	v_pk_mul_f32 v[106:107], v[38:39], 0.5 op_sel_hi:[1,0]
	v_pk_mul_f32 v[104:105], v[56:57], 0.5 op_sel_hi:[1,0]
	v_pk_mul_f32 v[102:103], v[54:55], 0.5 op_sel_hi:[1,0]
	v_pk_mul_f32 v[100:101], v[52:53], 0.5 op_sel_hi:[1,0]
	v_pk_mul_f32 v[98:99], v[50:51], 0.5 op_sel_hi:[1,0]
	v_pk_mul_f32 v[96:97], v[32:33], 0.5 op_sel_hi:[1,0]
	v_pk_mul_f32 v[94:95], v[30:31], 0.5 op_sel_hi:[1,0]
	v_pk_mul_f32 v[92:93], v[24:25], 0.5 op_sel_hi:[1,0]
	v_pk_mul_f32 v[90:91], v[22:23], 0.5 op_sel_hi:[1,0]
	v_pk_mul_f32 v[88:89], v[44:45], 0.5 op_sel_hi:[1,0]
	v_pk_mul_f32 v[86:87], v[42:43], 0.5 op_sel_hi:[1,0]
	v_pk_mul_f32 v[84:85], v[36:37], 0.5 op_sel_hi:[1,0]
	v_pk_mul_f32 v[82:83], v[34:35], 0.5 op_sel_hi:[1,0]
	v_pk_mul_f32 v[80:81], v[16:17], 0.5 op_sel_hi:[1,0]
	v_pk_mul_f32 v[78:79], v[14:15], 0.5 op_sel_hi:[1,0]
	v_pk_mul_f32 v[76:77], v[12:13], 0.5 op_sel_hi:[1,0]
	v_pk_mul_f32 v[74:75], v[10:11], 0.5 op_sel_hi:[1,0]
	v_pk_mul_f32 v[72:73], v[28:29], 0.5 op_sel_hi:[1,0]
	v_pk_mul_f32 v[70:71], v[26:27], 0.5 op_sel_hi:[1,0]
	v_pk_mul_f32 v[68:69], v[20:21], 0.5 op_sel_hi:[1,0]
	v_pk_mul_f32 v[66:67], v[18:19], 0.5 op_sel_hi:[1,0]
	v_pk_mul_f32 v[64:65], v[8:9], 0.5 op_sel_hi:[1,0]
	v_pk_mul_f32 v[62:63], v[6:7], 0.5 op_sel_hi:[1,0]
	v_pk_mul_f32 v[60:61], v[4:5], 0.5 op_sel_hi:[1,0]
	v_pk_mul_f32 v[58:59], v[2:3], 0.5 op_sel_hi:[1,0]
	s_and_b64 vcc, exec, s[40:41]
	s_cbranch_vccz .LBB0_1522
